# GEMM K-loops: removed the redundant back-to-back s_setprio 0 / s_setprio 1 pair in the middle of each MFMA super-phase
# baseline (speedup 1.0000x reference)
; #define PG8_STAGE(bufoff, gbase, voff) do { _Pragma("unroll") for (int _i = 0; _i < 2; ++_i) \
;         __builtin_amdgcn_global_load_lds((const unsigned*)((const char*)(gbase) + (voff)[_i]), (PG8_LAS unsigned*)(lds + (bufoff) + ldsw + _i * 8192), 16, 0, 0); } while (0)
; #define PG8_LDA(dst, b, h) do { _Pragma("unroll") for (int m = 0; m < 4; ++m) _Pragma("unroll") for (int k = 0; k < 2; ++k) dst[m][k] = *(const PG8_LAS bf16x8*)(lds + PG8_SA(b, h) + aoff + m * 2048 + k * 1024); } while (0)
; #define PG8_LDB(dst, b, h) do { _Pragma("unroll") for (int n = 0; n < 2; ++n) _Pragma("unroll") for (int k = 0; k < 2; ++k) dst[n][k] = *(const PG8_LAS bf16x8*)(lds + PG8_SB(b, h) + boff + n * 2048 + k * 1024); } while (0)
; #define PG8_MMA(ai, bj, At, Bt) do { __builtin_amdgcn_s_setprio(1); _Pragma("unroll") for (int m = 0; m < 4; ++m) _Pragma("unroll") for (int n = 0; n < 2; ++n) _Pragma("unroll") for (int k = 0; k < 2; ++k) \
;         acc[ai][bj][m][n] = __builtin_amdgcn_mfma_f32_16x16x32_bf16(Bt[n][k], At[m][k], acc[ai][bj][m][n], 0, 0, 0); __builtin_amdgcn_s_setprio(0); } while (0)
; #define PG8_WAIT_V(n) asm volatile("s_waitcnt vmcnt(" #n ")" ::: "memory")
; #define PG8_WAIT_L(n) asm volatile("s_waitcnt lgkmcnt(" #n ")" ::: "memory")
; #define PG8_BAR __builtin_amdgcn_s_barrier()
; #define PG8_SCHED __builtin_amdgcn_sched_barrier(0)
; template <class Epi, class Sched, bool ALIGN_EPI = false, bool SP2 = false>
; __device__ __forceinline__ void gemm_phase(PG8_LAS unsigned char* lds, const Gemm g, const Sched& S, const Epi& E, int tid_in) {
;     ...
;             PG8_LDB(B0, 0, 0); PG8_LDB(B1, 0, 1); PG8_SCHED; PG8_LDA(At, 0, 0); PG8_STAGE(PG8_SA(1, 1), a1 + hstep, voffA);
;             PG8_WAIT_V(8); PG8_WAIT_L(0); PG8_BAR; PG8_MMA(0, 0, At, B0); PG8_MMA(0, 1, At, B1); PG8_BAR; PG8_SCHED;
;             PG8_LDA(At, 0, 1); PG8_STAGE(PG8_SB(0, 0), b2, voffB); PG8_STAGE(PG8_SB(0, 1), b2 + hstep, voffB); PG8_STAGE(PG8_SA(0, 0), a2, voffA);
.LBB0_135:
	s_add_u32 s62, s64, 0xfff80080
	s_addc_u32 s63, s65, -1
	s_add_i32 s76, 0, 0x10000
	s_cmp_eq_u32 s75, 28
	s_cselect_b32 s95, s17, s63
	s_cselect_b32 s94, s43, s62
	v_add_u32_e32 v96, s76, v205
	s_cselect_b32 s93, s41, s74
	s_cselect_b32 s92, s72, s73
	s_add_i32 s77, 0, 0x14000
	ds_read_b128 v[130:133], v96
	ds_read_b128 v[134:137], v96 offset:1024
	ds_read_b128 v[138:141], v96 offset:2048
	ds_read_b128 v[142:145], v96 offset:3072
	v_add_u32_e32 v96, s77, v205
	ds_read_b128 v[146:149], v96
	ds_read_b128 v[150:153], v96 offset:1024
	ds_read_b128 v[154:157], v96 offset:2048
	ds_read_b128 v[158:161], v96 offset:3072
	v_lshl_add_u64 v[196:197], s[64:65], 0, v[180:181]
	s_add_i32 m0, s37, 0xc000
	ds_read_b128 v[162:165], v216
	ds_read_b128 v[184:187], v216 offset:1024
	ds_read_b128 v[188:191], v216 offset:2048
	ds_read_b128 v[192:195], v216 offset:3072
	ds_read_b128 v[218:221], v216 offset:4096
	ds_read_b128 v[222:225], v216 offset:5120
	ds_read_b128 v[226:229], v216 offset:6144
	ds_read_b128 v[230:233], v216 offset:7168
	global_load_lds_dwordx4 v[196:197], off
	v_lshl_add_u64 v[196:197], s[64:65], 0, v[182:183]
	s_add_i32 m0, s37, 0xe000
	s_nop 0
	global_load_lds_dwordx4 v[196:197], off
	s_waitcnt vmcnt(8)
	s_waitcnt lgkmcnt(0)
	s_barrier
	s_setprio 1
	s_waitcnt lgkmcnt(0)
	v_mfma_f32_16x16x32_bf16 v[126:129], v[130:133], v[162:165], v[126:129]
	v_mfma_f32_16x16x32_bf16 v[122:125], v[138:141], v[162:165], v[122:125]
	v_mfma_f32_16x16x32_bf16 v[118:121], v[130:133], v[188:191], v[118:121]
	v_mfma_f32_16x16x32_bf16 v[114:117], v[138:141], v[188:191], v[114:117]
	v_mfma_f32_16x16x32_bf16 v[102:105], v[130:133], v[218:221], v[102:105]
	v_mfma_f32_16x16x32_bf16 v[98:101], v[138:141], v[218:221], v[98:101]
	v_mfma_f32_16x16x32_bf16 v[84:87], v[130:133], v[226:229], v[84:87]
	v_mfma_f32_16x16x32_bf16 v[80:83], v[138:141], v[226:229], v[80:83]
	v_mfma_f32_16x16x32_bf16 v[126:129], v[134:137], v[184:187], v[126:129]
	v_mfma_f32_16x16x32_bf16 v[122:125], v[142:145], v[184:187], v[122:125]
	v_mfma_f32_16x16x32_bf16 v[118:121], v[134:137], v[192:195], v[118:121]
	v_mfma_f32_16x16x32_bf16 v[114:117], v[142:145], v[192:195], v[114:117]
	v_mfma_f32_16x16x32_bf16 v[102:105], v[134:137], v[222:225], v[102:105]
	v_mfma_f32_16x16x32_bf16 v[98:101], v[142:145], v[222:225], v[98:101]
	v_mfma_f32_16x16x32_bf16 v[84:87], v[134:137], v[230:233], v[84:87]
	v_mfma_f32_16x16x32_bf16 v[80:83], v[142:145], v[230:233], v[80:83]
	v_mfma_f32_16x16x32_bf16 v[110:113], v[146:149], v[162:165], v[110:113]
	v_mfma_f32_16x16x32_bf16 v[106:109], v[154:157], v[162:165], v[106:109]
	v_mfma_f32_16x16x32_bf16 v[92:95], v[146:149], v[188:191], v[92:95]
	v_mfma_f32_16x16x32_bf16 v[88:91], v[154:157], v[188:191], v[88:91]
	v_mfma_f32_16x16x32_bf16 v[76:79], v[146:149], v[218:221], v[76:79]
	v_mfma_f32_16x16x32_bf16 v[72:75], v[154:157], v[218:221], v[72:75]
	v_mfma_f32_16x16x32_bf16 v[68:71], v[146:149], v[226:229], v[68:71]
	v_mfma_f32_16x16x32_bf16 v[64:67], v[154:157], v[226:229], v[64:67]
	v_mfma_f32_16x16x32_bf16 v[110:113], v[150:153], v[184:187], v[110:113]
	v_mfma_f32_16x16x32_bf16 v[106:109], v[158:161], v[184:187], v[106:109]
	v_mfma_f32_16x16x32_bf16 v[92:95], v[150:153], v[192:195], v[92:95]
	v_mfma_f32_16x16x32_bf16 v[88:91], v[158:161], v[192:195], v[88:91]
	v_mfma_f32_16x16x32_bf16 v[76:79], v[150:153], v[222:225], v[76:79]
	v_mfma_f32_16x16x32_bf16 v[72:75], v[158:161], v[222:225], v[72:75]
	v_mfma_f32_16x16x32_bf16 v[68:71], v[150:153], v[230:233], v[68:71]
	v_mfma_f32_16x16x32_bf16 v[64:67], v[158:161], v[230:233], v[64:67]
	s_setprio 0
	s_barrier
	s_add_i32 s62, s76, s70
	v_lshl_add_u64 v[196:197], s[92:93], 0, v[174:175]
	s_mov_b32 m0, s62
	ds_read_b128 v[162:165], v216 offset:16384
	ds_read_b128 v[184:187], v216 offset:17408
	ds_read_b128 v[188:191], v216 offset:18432
	ds_read_b128 v[192:195], v216 offset:19456
	ds_read_b128 v[218:221], v216 offset:20480
	ds_read_b128 v[222:225], v216 offset:21504
	ds_read_b128 v[226:229], v216 offset:22528
	ds_read_b128 v[230:233], v216 offset:23552
	global_load_lds_dwordx4 v[196:197], off
	s_add_i32 m0, s62, 0x2000
	s_add_u32 s62, s92, 0x80000
	v_lshl_add_u64 v[198:199], s[92:93], 0, v[178:179]
	s_addc_u32 s63, s93, 0
	s_add_i32 s76, s77, s70
	global_load_lds_dwordx4 v[198:199], off
	v_lshl_add_u64 v[200:201], s[62:63], 0, v[174:175]
	s_mov_b32 m0, s76
	v_lshl_add_u64 v[234:235], s[94:95], 0, v[176:177]
	global_load_lds_dwordx4 v[200:201], off
	v_lshl_add_u64 v[200:201], s[62:63], 0, v[178:179]
	s_add_i32 m0, s76, 0x2000
	s_nop 0
	global_load_lds_dwordx4 v[200:201], off
	v_lshl_add_u64 v[200:201], s[94:95], 0, v[172:173]
	s_mov_b32 m0, s37
	s_nop 0
	global_load_lds_dwordx4 v[200:201], off
	s_mov_b32 m0, s71
	s_nop 0
	global_load_lds_dwordx4 v[234:235], off
	s_waitcnt vmcnt(8)
	s_waitcnt lgkmcnt(0)
	s_barrier
; #define PG8_STAGE(bufoff, gbase, voff) do { _Pragma("unroll") for (int _i = 0; _i < 2; ++_i) \
;         __builtin_amdgcn_global_load_lds((const unsigned*)((const char*)(gbase) + (voff)[_i]), (PG8_LAS unsigned*)(lds + (bufoff) + ldsw + _i * 8192), 16, 0, 0); } while (0)
; #define PG8_LDA(dst, b, h) do { _Pragma("unroll") for (int m = 0; m < 4; ++m) _Pragma("unroll") for (int k = 0; k < 2; ++k) dst[m][k] = *(const PG8_LAS bf16x8*)(lds + PG8_SA(b, h) + aoff + m * 2048 + k * 1024); } while (0)
; #define PG8_LDB(dst, b, h) do { _Pragma("unroll") for (int n = 0; n < 2; ++n) _Pragma("unroll") for (int k = 0; k < 2; ++k) dst[n][k] = *(const PG8_LAS bf16x8*)(lds + PG8_SB(b, h) + boff + n * 2048 + k * 1024); } while (0)
; #define PG8_MMA(ai, bj, At, Bt) do { __builtin_amdgcn_s_setprio(1); _Pragma("unroll") for (int m = 0; m < 4; ++m) _Pragma("unroll") for (int n = 0; n < 2; ++n) _Pragma("unroll") for (int k = 0; k < 2; ++k) \
;         acc[ai][bj][m][n] = __builtin_amdgcn_mfma_f32_16x16x32_bf16(Bt[n][k], At[m][k], acc[ai][bj][m][n], 0, 0, 0); __builtin_amdgcn_s_setprio(0); } while (0)
; #define PG8_WAIT_V(n) asm volatile("s_waitcnt vmcnt(" #n ")" ::: "memory")
; #define PG8_WAIT_L(n) asm volatile("s_waitcnt lgkmcnt(" #n ")" ::: "memory")
; #define PG8_BAR __builtin_amdgcn_s_barrier()
; #define PG8_SCHED __builtin_amdgcn_sched_barrier(0)
; template <class Epi, class Sched, bool ALIGN_EPI = false, bool SP2 = false>
; __device__ __forceinline__ void gemm_phase(PG8_LAS unsigned char* lds, const Gemm g, const Sched& S, const Epi& E, int tid_in) {
;     ...
;             PG8_WAIT_V(8); PG8_WAIT_L(0); PG8_BAR; PG8_MMA(1, 0, At, B0); PG8_MMA(1, 1, At, B1); PG8_BAR; PG8_SCHED;
;             PG8_LDB(B0, 1, 0); PG8_LDB(B1, 1, 1); PG8_SCHED; PG8_LDA(At, 1, 0); PG8_STAGE(PG8_SA(0, 1), a2 + hstep, voffA);
;             PG8_WAIT_V(8); PG8_WAIT_L(0); PG8_BAR; PG8_MMA(0, 0, At, B0); PG8_MMA(0, 1, At, B1); PG8_BAR; PG8_SCHED;
	s_setprio 1
	s_waitcnt lgkmcnt(0)
	v_mfma_f32_16x16x32_bf16 v[60:63], v[130:133], v[162:165], v[60:63]
	v_mfma_f32_16x16x32_bf16 v[56:59], v[138:141], v[162:165], v[56:59]
	v_mfma_f32_16x16x32_bf16 v[52:55], v[130:133], v[188:191], v[52:55]
	v_mfma_f32_16x16x32_bf16 v[48:51], v[138:141], v[188:191], v[48:51]
	v_mfma_f32_16x16x32_bf16 v[36:39], v[130:133], v[218:221], v[36:39]
	v_mfma_f32_16x16x32_bf16 v[32:35], v[138:141], v[218:221], v[32:35]
	v_mfma_f32_16x16x32_bf16 v[20:23], v[130:133], v[226:229], v[20:23]
	v_mfma_f32_16x16x32_bf16 v[16:19], v[138:141], v[226:229], v[16:19]
	v_mfma_f32_16x16x32_bf16 v[60:63], v[134:137], v[184:187], v[60:63]
	v_mfma_f32_16x16x32_bf16 v[56:59], v[142:145], v[184:187], v[56:59]
	v_mfma_f32_16x16x32_bf16 v[52:55], v[134:137], v[192:195], v[52:55]
	v_mfma_f32_16x16x32_bf16 v[48:51], v[142:145], v[192:195], v[48:51]
	v_mfma_f32_16x16x32_bf16 v[36:39], v[134:137], v[222:225], v[36:39]
	v_mfma_f32_16x16x32_bf16 v[32:35], v[142:145], v[222:225], v[32:35]
	v_mfma_f32_16x16x32_bf16 v[20:23], v[134:137], v[230:233], v[20:23]
	v_mfma_f32_16x16x32_bf16 v[16:19], v[142:145], v[230:233], v[16:19]
	v_mfma_f32_16x16x32_bf16 v[44:47], v[146:149], v[162:165], v[44:47]
	v_mfma_f32_16x16x32_bf16 v[40:43], v[154:157], v[162:165], v[40:43]
	v_mfma_f32_16x16x32_bf16 v[28:31], v[146:149], v[188:191], v[28:31]
	v_mfma_f32_16x16x32_bf16 v[24:27], v[154:157], v[188:191], v[24:27]
	v_mfma_f32_16x16x32_bf16 v[12:15], v[146:149], v[218:221], v[12:15]
	v_mfma_f32_16x16x32_bf16 v[8:11], v[154:157], v[218:221], v[8:11]
	v_mfma_f32_16x16x32_bf16 v[4:7], v[146:149], v[226:229], v[4:7]
	v_mfma_f32_16x16x32_bf16 v[0:3], v[154:157], v[226:229], v[0:3]
	v_mfma_f32_16x16x32_bf16 v[44:47], v[150:153], v[184:187], v[44:47]
	v_mfma_f32_16x16x32_bf16 v[40:43], v[158:161], v[184:187], v[40:43]
	v_mfma_f32_16x16x32_bf16 v[28:31], v[150:153], v[192:195], v[28:31]
	v_mfma_f32_16x16x32_bf16 v[24:27], v[158:161], v[192:195], v[24:27]
	v_mfma_f32_16x16x32_bf16 v[12:15], v[150:153], v[222:225], v[12:15]
	v_mfma_f32_16x16x32_bf16 v[8:11], v[158:161], v[222:225], v[8:11]
	v_mfma_f32_16x16x32_bf16 v[4:7], v[150:153], v[230:233], v[4:7]
	v_mfma_f32_16x16x32_bf16 v[0:3], v[158:161], v[230:233], v[0:3]
	s_setprio 0
	s_barrier
	s_add_i32 s76, 0, 0x18000
	v_add_u32_e32 v96, s76, v205
	s_add_i32 s77, 0, 0x1c000
	ds_read_b128 v[130:133], v96
	ds_read_b128 v[134:137], v96 offset:1024
	ds_read_b128 v[138:141], v96 offset:2048
	ds_read_b128 v[142:145], v96 offset:3072
	v_add_u32_e32 v96, s77, v205
	ds_read_b128 v[146:149], v96
	ds_read_b128 v[150:153], v96 offset:1024
	ds_read_b128 v[154:157], v96 offset:2048
	ds_read_b128 v[158:161], v96 offset:3072
	s_add_u32 s62, s94, 0x80000
	s_addc_u32 s63, s95, 0
	s_mov_b32 m0, s91
	v_lshl_add_u64 v[236:237], s[62:63], 0, v[172:173]
	ds_read_b128 v[162:165], v216 offset:32768
	ds_read_b128 v[184:187], v216 offset:33792
	ds_read_b128 v[188:191], v216 offset:34816
	ds_read_b128 v[192:195], v216 offset:35840
	ds_read_b128 v[218:221], v216 offset:36864
	ds_read_b128 v[222:225], v216 offset:37888
	ds_read_b128 v[226:229], v216 offset:38912
	ds_read_b128 v[230:233], v216 offset:39936
	global_load_lds_dwordx4 v[236:237], off
	v_lshl_add_u64 v[236:237], s[62:63], 0, v[176:177]
	s_mov_b32 m0, s96
	s_nop 0
	global_load_lds_dwordx4 v[236:237], off
	s_waitcnt vmcnt(8)
	s_waitcnt lgkmcnt(0)
	s_barrier
	s_setprio 1
	s_waitcnt lgkmcnt(0)
	v_mfma_f32_16x16x32_bf16 v[126:129], v[130:133], v[162:165], v[126:129]
	v_mfma_f32_16x16x32_bf16 v[122:125], v[138:141], v[162:165], v[122:125]
	v_mfma_f32_16x16x32_bf16 v[118:121], v[130:133], v[188:191], v[118:121]
	v_mfma_f32_16x16x32_bf16 v[114:117], v[138:141], v[188:191], v[114:117]
	v_mfma_f32_16x16x32_bf16 v[102:105], v[130:133], v[218:221], v[102:105]
	v_mfma_f32_16x16x32_bf16 v[98:101], v[138:141], v[218:221], v[98:101]
	v_mfma_f32_16x16x32_bf16 v[84:87], v[130:133], v[226:229], v[84:87]
	v_mfma_f32_16x16x32_bf16 v[80:83], v[138:141], v[226:229], v[80:83]
	v_mfma_f32_16x16x32_bf16 v[126:129], v[134:137], v[184:187], v[126:129]
	v_mfma_f32_16x16x32_bf16 v[122:125], v[142:145], v[184:187], v[122:125]
	v_mfma_f32_16x16x32_bf16 v[118:121], v[134:137], v[192:195], v[118:121]
	v_mfma_f32_16x16x32_bf16 v[114:117], v[142:145], v[192:195], v[114:117]
	v_mfma_f32_16x16x32_bf16 v[102:105], v[134:137], v[222:225], v[102:105]
	v_mfma_f32_16x16x32_bf16 v[98:101], v[142:145], v[222:225], v[98:101]
	v_mfma_f32_16x16x32_bf16 v[84:87], v[134:137], v[230:233], v[84:87]
	v_mfma_f32_16x16x32_bf16 v[80:83], v[142:145], v[230:233], v[80:83]
	v_mfma_f32_16x16x32_bf16 v[110:113], v[146:149], v[162:165], v[110:113]
	v_mfma_f32_16x16x32_bf16 v[106:109], v[154:157], v[162:165], v[106:109]
	v_mfma_f32_16x16x32_bf16 v[92:95], v[146:149], v[188:191], v[92:95]
	v_mfma_f32_16x16x32_bf16 v[88:91], v[154:157], v[188:191], v[88:91]
	v_mfma_f32_16x16x32_bf16 v[76:79], v[146:149], v[218:221], v[76:79]
	v_mfma_f32_16x16x32_bf16 v[72:75], v[154:157], v[218:221], v[72:75]
	v_mfma_f32_16x16x32_bf16 v[68:71], v[146:149], v[226:229], v[68:71]
	v_mfma_f32_16x16x32_bf16 v[64:67], v[154:157], v[226:229], v[64:67]
	v_mfma_f32_16x16x32_bf16 v[110:113], v[150:153], v[184:187], v[110:113]
	v_mfma_f32_16x16x32_bf16 v[106:109], v[158:161], v[184:187], v[106:109]
	v_mfma_f32_16x16x32_bf16 v[92:95], v[150:153], v[192:195], v[92:95]
	v_mfma_f32_16x16x32_bf16 v[88:91], v[158:161], v[192:195], v[88:91]
	v_mfma_f32_16x16x32_bf16 v[76:79], v[150:153], v[222:225], v[76:79]
	v_mfma_f32_16x16x32_bf16 v[72:75], v[158:161], v[222:225], v[72:75]
	v_mfma_f32_16x16x32_bf16 v[68:71], v[150:153], v[230:233], v[68:71]
	v_mfma_f32_16x16x32_bf16 v[64:67], v[158:161], v[230:233], v[64:67]
	s_setprio 0
	s_barrier
; #define PG8_STAGE(bufoff, gbase, voff) do { _Pragma("unroll") for (int _i = 0; _i < 2; ++_i) \
;         __builtin_amdgcn_global_load_lds((const unsigned*)((const char*)(gbase) + (voff)[_i]), (PG8_LAS unsigned*)(lds + (bufoff) + ldsw + _i * 8192), 16, 0, 0); } while (0)
; #define PG8_LDA(dst, b, h) do { _Pragma("unroll") for (int m = 0; m < 4; ++m) _Pragma("unroll") for (int k = 0; k < 2; ++k) dst[m][k] = *(const PG8_LAS bf16x8*)(lds + PG8_SA(b, h) + aoff + m * 2048 + k * 1024); } while (0)
; #define PG8_MMA(ai, bj, At, Bt) do { __builtin_amdgcn_s_setprio(1); _Pragma("unroll") for (int m = 0; m < 4; ++m) _Pragma("unroll") for (int n = 0; n < 2; ++n) _Pragma("unroll") for (int k = 0; k < 2; ++k) \
;         acc[ai][bj][m][n] = __builtin_amdgcn_mfma_f32_16x16x32_bf16(Bt[n][k], At[m][k], acc[ai][bj][m][n], 0, 0, 0); __builtin_amdgcn_s_setprio(0); } while (0)
; #define PG8_WAIT_V(n) asm volatile("s_waitcnt vmcnt(" #n ")" ::: "memory")
; #define PG8_WAIT_L(n) asm volatile("s_waitcnt lgkmcnt(" #n ")" ::: "memory")
; #define PG8_BAR __builtin_amdgcn_s_barrier()
; #define PG8_SCHED __builtin_amdgcn_sched_barrier(0)
; template <class Epi, class Sched, bool ALIGN_EPI = false, bool SP2 = false>
; __device__ __forceinline__ void gemm_phase(PG8_LAS unsigned char* lds, const Gemm g, const Sched& S, const Epi& E, int tid_in) {
;     ...
;             PG8_WAIT_V(8); PG8_WAIT_L(0); PG8_BAR; PG8_MMA(0, 0, At, B0); PG8_MMA(0, 1, At, B1); PG8_BAR; PG8_SCHED;
;             PG8_LDA(At, 1, 1); PG8_STAGE(PG8_SB(1, 0), b3, voffB); PG8_STAGE(PG8_SB(1, 1), b3 + hstep, voffB); PG8_STAGE(PG8_SA(1, 0), a3, voffA);
;             PG8_WAIT_V(8); PG8_WAIT_L(0); PG8_BAR; PG8_MMA(1, 0, At, B0); PG8_MMA(1, 1, At, B1); PG8_BAR; PG8_SCHED;
	s_add_i32 s62, s76, s70
	v_lshl_add_u64 v[196:197], v[196:197], 0, s[88:89]
	s_mov_b32 m0, s62
	ds_read_b128 v[162:165], v216 offset:49152
	ds_read_b128 v[184:187], v216 offset:50176
	ds_read_b128 v[188:191], v216 offset:51200
	ds_read_b128 v[192:195], v216 offset:52224
	ds_read_b128 v[218:221], v216 offset:53248
	ds_read_b128 v[222:225], v216 offset:54272
	ds_read_b128 v[226:229], v216 offset:55296
	ds_read_b128 v[230:233], v216 offset:56320
	global_load_lds_dwordx4 v[196:197], off
	s_add_i32 m0, s62, 0x2000
	s_add_u32 s62, s92, 0x80080
	v_lshl_add_u64 v[196:197], v[198:199], 0, s[88:89]
	s_addc_u32 s63, s93, 0
	s_add_i32 s76, s77, s70
	global_load_lds_dwordx4 v[196:197], off
	v_lshl_add_u64 v[196:197], s[62:63], 0, v[174:175]
	s_mov_b32 m0, s76
	s_nop 0
	global_load_lds_dwordx4 v[196:197], off
	v_lshl_add_u64 v[196:197], s[62:63], 0, v[178:179]
	s_add_i32 m0, s76, 0x2000
	s_nop 0
	global_load_lds_dwordx4 v[196:197], off
	v_lshl_add_u64 v[196:197], v[200:201], 0, s[88:89]
	s_mov_b32 m0, s97
	s_nop 0
	global_load_lds_dwordx4 v[196:197], off
	v_lshl_add_u64 v[196:197], v[234:235], 0, s[88:89]
	s_mov_b32 m0, s2
	s_nop 0
	global_load_lds_dwordx4 v[196:197], off
	s_waitcnt vmcnt(8)
	s_waitcnt lgkmcnt(0)
	s_barrier
	s_setprio 1
	s_waitcnt lgkmcnt(0)
	v_mfma_f32_16x16x32_bf16 v[60:63], v[130:133], v[162:165], v[60:63]
	v_mfma_f32_16x16x32_bf16 v[56:59], v[138:141], v[162:165], v[56:59]
	v_mfma_f32_16x16x32_bf16 v[52:55], v[130:133], v[188:191], v[52:55]
	v_mfma_f32_16x16x32_bf16 v[48:51], v[138:141], v[188:191], v[48:51]
	v_mfma_f32_16x16x32_bf16 v[36:39], v[130:133], v[218:221], v[36:39]
	v_mfma_f32_16x16x32_bf16 v[32:35], v[138:141], v[218:221], v[32:35]
	v_mfma_f32_16x16x32_bf16 v[20:23], v[130:133], v[226:229], v[20:23]
	v_mfma_f32_16x16x32_bf16 v[16:19], v[138:141], v[226:229], v[16:19]
	v_mfma_f32_16x16x32_bf16 v[60:63], v[134:137], v[184:187], v[60:63]
	v_mfma_f32_16x16x32_bf16 v[56:59], v[142:145], v[184:187], v[56:59]
	v_mfma_f32_16x16x32_bf16 v[52:55], v[134:137], v[192:195], v[52:55]
	v_mfma_f32_16x16x32_bf16 v[48:51], v[142:145], v[192:195], v[48:51]
	v_mfma_f32_16x16x32_bf16 v[36:39], v[134:137], v[222:225], v[36:39]
	v_mfma_f32_16x16x32_bf16 v[32:35], v[142:145], v[222:225], v[32:35]
	v_mfma_f32_16x16x32_bf16 v[20:23], v[134:137], v[230:233], v[20:23]
	v_mfma_f32_16x16x32_bf16 v[16:19], v[142:145], v[230:233], v[16:19]
	v_mfma_f32_16x16x32_bf16 v[44:47], v[146:149], v[162:165], v[44:47]
	v_mfma_f32_16x16x32_bf16 v[40:43], v[154:157], v[162:165], v[40:43]
	v_mfma_f32_16x16x32_bf16 v[28:31], v[146:149], v[188:191], v[28:31]
	v_mfma_f32_16x16x32_bf16 v[24:27], v[154:157], v[188:191], v[24:27]
	v_mfma_f32_16x16x32_bf16 v[12:15], v[146:149], v[218:221], v[12:15]
	v_mfma_f32_16x16x32_bf16 v[8:11], v[154:157], v[218:221], v[8:11]
	v_mfma_f32_16x16x32_bf16 v[4:7], v[146:149], v[226:229], v[4:7]
	v_mfma_f32_16x16x32_bf16 v[0:3], v[154:157], v[226:229], v[0:3]
	v_mfma_f32_16x16x32_bf16 v[44:47], v[150:153], v[184:187], v[44:47]
	v_mfma_f32_16x16x32_bf16 v[40:43], v[158:161], v[184:187], v[40:43]
	v_mfma_f32_16x16x32_bf16 v[28:31], v[150:153], v[192:195], v[28:31]
	v_mfma_f32_16x16x32_bf16 v[24:27], v[158:161], v[192:195], v[24:27]
	v_mfma_f32_16x16x32_bf16 v[12:15], v[150:153], v[222:225], v[12:15]
	v_mfma_f32_16x16x32_bf16 v[8:11], v[158:161], v[222:225], v[8:11]
	v_mfma_f32_16x16x32_bf16 v[4:7], v[150:153], v[230:233], v[4:7]
	v_mfma_f32_16x16x32_bf16 v[0:3], v[158:161], v[230:233], v[0:3]
	s_setprio 0
	s_barrier
	s_add_i32 s75, s75, 2
	s_add_u32 s64, s64, 0x100
	s_addc_u32 s65, s65, 0
	s_add_u32 s73, s73, 0x100
	s_addc_u32 s74, s74, 0
	s_cmp_gt_u32 s75, 29
	s_cbranch_scc0 .LBB0_135
	s_and_b64 vcc, exec, s[38:39]
	s_cbranch_vccz .LBB0_138
	s_barrier

; #define PG8_STAGE(bufoff, gbase, voff) do { _Pragma("unroll") for (int _i = 0; _i < 2; ++_i) \
;         __builtin_amdgcn_global_load_lds((const unsigned*)((const char*)(gbase) + (voff)[_i]), (PG8_LAS unsigned*)(lds + (bufoff) + ldsw + _i * 8192), 16, 0, 0); } while (0)
; #define PG8_LDA(dst, b, h) do { _Pragma("unroll") for (int m = 0; m < 4; ++m) _Pragma("unroll") for (int k = 0; k < 2; ++k) dst[m][k] = *(const PG8_LAS bf16x8*)(lds + PG8_SA(b, h) + aoff + m * 2048 + k * 1024); } while (0)
; #define PG8_LDB(dst, b, h) do { _Pragma("unroll") for (int n = 0; n < 2; ++n) _Pragma("unroll") for (int k = 0; k < 2; ++k) dst[n][k] = *(const PG8_LAS bf16x8*)(lds + PG8_SB(b, h) + boff + n * 2048 + k * 1024); } while (0)
; #define PG8_MMA(ai, bj, At, Bt) do { __builtin_amdgcn_s_setprio(1); _Pragma("unroll") for (int m = 0; m < 4; ++m) _Pragma("unroll") for (int n = 0; n < 2; ++n) _Pragma("unroll") for (int k = 0; k < 2; ++k) \
;         acc[ai][bj][m][n] = __builtin_amdgcn_mfma_f32_16x16x32_bf16(Bt[n][k], At[m][k], acc[ai][bj][m][n], 0, 0, 0); __builtin_amdgcn_s_setprio(0); } while (0)
; #define PG8_WAIT_V(n) asm volatile("s_waitcnt vmcnt(" #n ")" ::: "memory")
; #define PG8_WAIT_L(n) asm volatile("s_waitcnt lgkmcnt(" #n ")" ::: "memory")
; #define PG8_BAR __builtin_amdgcn_s_barrier()
; #define PG8_SCHED __builtin_amdgcn_sched_barrier(0)
; template <class Epi, class Sched, bool ALIGN_EPI = false, bool SP2 = false>
; __device__ __forceinline__ void gemm_phase(PG8_LAS unsigned char* lds, const Gemm g, const Sched& S, const Epi& E, int tid_in) {
;     ...
;             PG8_LDB(B0, 0, 0); PG8_LDB(B1, 0, 1); PG8_SCHED; PG8_LDA(At, 0, 0); PG8_STAGE(PG8_SA(1, 1), a1 + hstep, voffA);
;             PG8_WAIT_V(8); PG8_WAIT_L(0); PG8_BAR; PG8_MMA(0, 0, At, B0); PG8_MMA(0, 1, At, B1); PG8_BAR; PG8_SCHED;
;             PG8_LDA(At, 0, 1); PG8_STAGE(PG8_SB(0, 0), b2, voffB); PG8_STAGE(PG8_SB(0, 1), b2 + hstep, voffB); PG8_STAGE(PG8_SA(0, 0), a2, voffA);
.LBB0_403:
	s_add_u32 s46, s44, 0xfff80080
	s_addc_u32 s47, s45, -1
	s_add_i32 s62, 0, 0x10000
	s_cmp_eq_u32 s75, 28
	s_cselect_b32 s65, s35, s47
	s_cselect_b32 s64, s43, s46
	v_add_u32_e32 v96, s62, v205
	s_cselect_b32 s47, s37, s74
	s_cselect_b32 s46, s72, s73
	s_add_i32 s76, 0, 0x14000
	ds_read_b128 v[130:133], v96
	ds_read_b128 v[134:137], v96 offset:1024
	ds_read_b128 v[138:141], v96 offset:2048
	ds_read_b128 v[142:145], v96 offset:3072
	v_add_u32_e32 v96, s76, v205
	ds_read_b128 v[146:149], v96
	ds_read_b128 v[150:153], v96 offset:1024
	ds_read_b128 v[154:157], v96 offset:2048
	ds_read_b128 v[158:161], v96 offset:3072
	v_lshl_add_u64 v[200:201], s[44:45], 0, v[180:181]
	s_add_i32 m0, s29, 0xc000
	ds_read_b128 v[162:165], v216
	ds_read_b128 v[184:187], v216 offset:1024
	ds_read_b128 v[188:191], v216 offset:2048
	ds_read_b128 v[192:195], v216 offset:3072
	ds_read_b128 v[196:199], v216 offset:4096
	ds_read_b128 v[218:221], v216 offset:5120
	ds_read_b128 v[222:225], v216 offset:6144
	ds_read_b128 v[226:229], v216 offset:7168
	global_load_lds_dwordx4 v[200:201], off
	v_lshl_add_u64 v[200:201], s[44:45], 0, v[182:183]
	s_add_i32 m0, s29, 0xe000
	s_nop 0
	global_load_lds_dwordx4 v[200:201], off
	s_waitcnt vmcnt(8)
	s_waitcnt lgkmcnt(0)
	s_barrier
	s_setprio 1
	s_waitcnt lgkmcnt(0)
	v_mfma_f32_16x16x32_bf16 v[126:129], v[130:133], v[162:165], v[126:129]
	v_mfma_f32_16x16x32_bf16 v[122:125], v[138:141], v[162:165], v[122:125]
	v_mfma_f32_16x16x32_bf16 v[118:121], v[130:133], v[188:191], v[118:121]
	v_mfma_f32_16x16x32_bf16 v[114:117], v[138:141], v[188:191], v[114:117]
	v_mfma_f32_16x16x32_bf16 v[102:105], v[130:133], v[196:199], v[102:105]
	v_mfma_f32_16x16x32_bf16 v[98:101], v[138:141], v[196:199], v[98:101]
	v_mfma_f32_16x16x32_bf16 v[84:87], v[130:133], v[222:225], v[84:87]
	v_mfma_f32_16x16x32_bf16 v[80:83], v[138:141], v[222:225], v[80:83]
	v_mfma_f32_16x16x32_bf16 v[126:129], v[134:137], v[184:187], v[126:129]
	v_mfma_f32_16x16x32_bf16 v[122:125], v[142:145], v[184:187], v[122:125]
	v_mfma_f32_16x16x32_bf16 v[118:121], v[134:137], v[192:195], v[118:121]
	v_mfma_f32_16x16x32_bf16 v[114:117], v[142:145], v[192:195], v[114:117]
	v_mfma_f32_16x16x32_bf16 v[102:105], v[134:137], v[218:221], v[102:105]
	v_mfma_f32_16x16x32_bf16 v[98:101], v[142:145], v[218:221], v[98:101]
	v_mfma_f32_16x16x32_bf16 v[84:87], v[134:137], v[226:229], v[84:87]
	v_mfma_f32_16x16x32_bf16 v[80:83], v[142:145], v[226:229], v[80:83]
	v_mfma_f32_16x16x32_bf16 v[110:113], v[146:149], v[162:165], v[110:113]
	v_mfma_f32_16x16x32_bf16 v[106:109], v[154:157], v[162:165], v[106:109]
	v_mfma_f32_16x16x32_bf16 v[92:95], v[146:149], v[188:191], v[92:95]
	v_mfma_f32_16x16x32_bf16 v[88:91], v[154:157], v[188:191], v[88:91]
	v_mfma_f32_16x16x32_bf16 v[76:79], v[146:149], v[196:199], v[76:79]
	v_mfma_f32_16x16x32_bf16 v[72:75], v[154:157], v[196:199], v[72:75]
	v_mfma_f32_16x16x32_bf16 v[68:71], v[146:149], v[222:225], v[68:71]
	v_mfma_f32_16x16x32_bf16 v[64:67], v[154:157], v[222:225], v[64:67]
	v_mfma_f32_16x16x32_bf16 v[110:113], v[150:153], v[184:187], v[110:113]
	v_mfma_f32_16x16x32_bf16 v[106:109], v[158:161], v[184:187], v[106:109]
	v_mfma_f32_16x16x32_bf16 v[92:95], v[150:153], v[192:195], v[92:95]
	v_mfma_f32_16x16x32_bf16 v[88:91], v[158:161], v[192:195], v[88:91]
	v_mfma_f32_16x16x32_bf16 v[76:79], v[150:153], v[218:221], v[76:79]
	v_mfma_f32_16x16x32_bf16 v[72:75], v[158:161], v[218:221], v[72:75]
	v_mfma_f32_16x16x32_bf16 v[68:71], v[150:153], v[226:229], v[68:71]
	v_mfma_f32_16x16x32_bf16 v[64:67], v[158:161], v[226:229], v[64:67]
	s_setprio 0
	s_barrier
	s_add_i32 s62, s62, s96
	v_lshl_add_u64 v[200:201], s[46:47], 0, v[174:175]
	s_mov_b32 m0, s62
	ds_read_b128 v[162:165], v216 offset:16384
	ds_read_b128 v[184:187], v216 offset:17408
	ds_read_b128 v[188:191], v216 offset:18432
	ds_read_b128 v[192:195], v216 offset:19456
	ds_read_b128 v[196:199], v216 offset:20480
	ds_read_b128 v[218:221], v216 offset:21504
	ds_read_b128 v[222:225], v216 offset:22528
	ds_read_b128 v[226:229], v216 offset:23552
	global_load_lds_dwordx4 v[200:201], off
	s_add_i32 m0, s62, 0x2000
	s_add_u32 s62, s46, 0x80000
	v_lshl_add_u64 v[230:231], s[46:47], 0, v[178:179]
	s_addc_u32 s63, s47, 0
	s_add_i32 s76, s76, s96
	global_load_lds_dwordx4 v[230:231], off
	v_lshl_add_u64 v[232:233], s[62:63], 0, v[174:175]
	s_mov_b32 m0, s76
	v_lshl_add_u64 v[234:235], s[64:65], 0, v[176:177]
	global_load_lds_dwordx4 v[232:233], off
	v_lshl_add_u64 v[232:233], s[62:63], 0, v[178:179]
	s_add_i32 m0, s76, 0x2000
	s_nop 0
	global_load_lds_dwordx4 v[232:233], off
	v_lshl_add_u64 v[232:233], s[64:65], 0, v[172:173]
	s_mov_b32 m0, s29
	s_nop 0
	global_load_lds_dwordx4 v[232:233], off
	s_mov_b32 m0, s97
	s_nop 0
	global_load_lds_dwordx4 v[234:235], off
	s_waitcnt vmcnt(8)
	s_waitcnt lgkmcnt(0)
	s_barrier
; #define PG8_STAGE(bufoff, gbase, voff) do { _Pragma("unroll") for (int _i = 0; _i < 2; ++_i) \
;         __builtin_amdgcn_global_load_lds((const unsigned*)((const char*)(gbase) + (voff)[_i]), (PG8_LAS unsigned*)(lds + (bufoff) + ldsw + _i * 8192), 16, 0, 0); } while (0)
; #define PG8_LDA(dst, b, h) do { _Pragma("unroll") for (int m = 0; m < 4; ++m) _Pragma("unroll") for (int k = 0; k < 2; ++k) dst[m][k] = *(const PG8_LAS bf16x8*)(lds + PG8_SA(b, h) + aoff + m * 2048 + k * 1024); } while (0)
; #define PG8_LDB(dst, b, h) do { _Pragma("unroll") for (int n = 0; n < 2; ++n) _Pragma("unroll") for (int k = 0; k < 2; ++k) dst[n][k] = *(const PG8_LAS bf16x8*)(lds + PG8_SB(b, h) + boff + n * 2048 + k * 1024); } while (0)
; #define PG8_MMA(ai, bj, At, Bt) do { __builtin_amdgcn_s_setprio(1); _Pragma("unroll") for (int m = 0; m < 4; ++m) _Pragma("unroll") for (int n = 0; n < 2; ++n) _Pragma("unroll") for (int k = 0; k < 2; ++k) \
;         acc[ai][bj][m][n] = __builtin_amdgcn_mfma_f32_16x16x32_bf16(Bt[n][k], At[m][k], acc[ai][bj][m][n], 0, 0, 0); __builtin_amdgcn_s_setprio(0); } while (0)
; #define PG8_WAIT_V(n) asm volatile("s_waitcnt vmcnt(" #n ")" ::: "memory")
; #define PG8_WAIT_L(n) asm volatile("s_waitcnt lgkmcnt(" #n ")" ::: "memory")
; #define PG8_BAR __builtin_amdgcn_s_barrier()
; #define PG8_SCHED __builtin_amdgcn_sched_barrier(0)
; template <class Epi, class Sched, bool ALIGN_EPI = false, bool SP2 = false>
; __device__ __forceinline__ void gemm_phase(PG8_LAS unsigned char* lds, const Gemm g, const Sched& S, const Epi& E, int tid_in) {
;     ...
;             PG8_WAIT_V(8); PG8_WAIT_L(0); PG8_BAR; PG8_MMA(1, 0, At, B0); PG8_MMA(1, 1, At, B1); PG8_BAR; PG8_SCHED;
;             PG8_LDB(B0, 1, 0); PG8_LDB(B1, 1, 1); PG8_SCHED; PG8_LDA(At, 1, 0); PG8_STAGE(PG8_SA(0, 1), a2 + hstep, voffA);
;             PG8_WAIT_V(8); PG8_WAIT_L(0); PG8_BAR; PG8_MMA(0, 0, At, B0); PG8_MMA(0, 1, At, B1); PG8_BAR; PG8_SCHED;
	s_setprio 1
	s_waitcnt lgkmcnt(0)
	v_mfma_f32_16x16x32_bf16 v[60:63], v[130:133], v[162:165], v[60:63]
	v_mfma_f32_16x16x32_bf16 v[56:59], v[138:141], v[162:165], v[56:59]
	v_mfma_f32_16x16x32_bf16 v[52:55], v[130:133], v[188:191], v[52:55]
	v_mfma_f32_16x16x32_bf16 v[48:51], v[138:141], v[188:191], v[48:51]
	v_mfma_f32_16x16x32_bf16 v[36:39], v[130:133], v[196:199], v[36:39]
	v_mfma_f32_16x16x32_bf16 v[32:35], v[138:141], v[196:199], v[32:35]
	v_mfma_f32_16x16x32_bf16 v[20:23], v[130:133], v[222:225], v[20:23]
	v_mfma_f32_16x16x32_bf16 v[16:19], v[138:141], v[222:225], v[16:19]
	v_mfma_f32_16x16x32_bf16 v[60:63], v[134:137], v[184:187], v[60:63]
	v_mfma_f32_16x16x32_bf16 v[56:59], v[142:145], v[184:187], v[56:59]
	v_mfma_f32_16x16x32_bf16 v[52:55], v[134:137], v[192:195], v[52:55]
	v_mfma_f32_16x16x32_bf16 v[48:51], v[142:145], v[192:195], v[48:51]
	v_mfma_f32_16x16x32_bf16 v[36:39], v[134:137], v[218:221], v[36:39]
	v_mfma_f32_16x16x32_bf16 v[32:35], v[142:145], v[218:221], v[32:35]
	v_mfma_f32_16x16x32_bf16 v[20:23], v[134:137], v[226:229], v[20:23]
	v_mfma_f32_16x16x32_bf16 v[16:19], v[142:145], v[226:229], v[16:19]
	v_mfma_f32_16x16x32_bf16 v[44:47], v[146:149], v[162:165], v[44:47]
	v_mfma_f32_16x16x32_bf16 v[40:43], v[154:157], v[162:165], v[40:43]
	v_mfma_f32_16x16x32_bf16 v[28:31], v[146:149], v[188:191], v[28:31]
	v_mfma_f32_16x16x32_bf16 v[24:27], v[154:157], v[188:191], v[24:27]
	v_mfma_f32_16x16x32_bf16 v[12:15], v[146:149], v[196:199], v[12:15]
	v_mfma_f32_16x16x32_bf16 v[8:11], v[154:157], v[196:199], v[8:11]
	v_mfma_f32_16x16x32_bf16 v[4:7], v[146:149], v[222:225], v[4:7]
	v_mfma_f32_16x16x32_bf16 v[0:3], v[154:157], v[222:225], v[0:3]
	v_mfma_f32_16x16x32_bf16 v[44:47], v[150:153], v[184:187], v[44:47]
	v_mfma_f32_16x16x32_bf16 v[40:43], v[158:161], v[184:187], v[40:43]
	v_mfma_f32_16x16x32_bf16 v[28:31], v[150:153], v[192:195], v[28:31]
	v_mfma_f32_16x16x32_bf16 v[24:27], v[158:161], v[192:195], v[24:27]
	v_mfma_f32_16x16x32_bf16 v[12:15], v[150:153], v[218:221], v[12:15]
	v_mfma_f32_16x16x32_bf16 v[8:11], v[158:161], v[218:221], v[8:11]
	v_mfma_f32_16x16x32_bf16 v[4:7], v[150:153], v[226:229], v[4:7]
	v_mfma_f32_16x16x32_bf16 v[0:3], v[158:161], v[226:229], v[0:3]
	s_setprio 0
	s_barrier
	s_add_i32 s76, 0, 0x18000
	v_add_u32_e32 v96, s76, v205
	s_add_i32 s77, 0, 0x1c000
	ds_read_b128 v[130:133], v96
	ds_read_b128 v[134:137], v96 offset:1024
	ds_read_b128 v[138:141], v96 offset:2048
	ds_read_b128 v[142:145], v96 offset:3072
	v_add_u32_e32 v96, s77, v205
	ds_read_b128 v[146:149], v96
	ds_read_b128 v[150:153], v96 offset:1024
	ds_read_b128 v[154:157], v96 offset:2048
	ds_read_b128 v[158:161], v96 offset:3072
	s_add_u32 s62, s64, 0x80000
	s_addc_u32 s63, s65, 0
	s_mov_b32 m0, s20
	v_lshl_add_u64 v[236:237], s[62:63], 0, v[172:173]
	ds_read_b128 v[162:165], v216 offset:32768
	ds_read_b128 v[184:187], v216 offset:33792
	ds_read_b128 v[188:191], v216 offset:34816
	ds_read_b128 v[192:195], v216 offset:35840
	ds_read_b128 v[196:199], v216 offset:36864
	ds_read_b128 v[218:221], v216 offset:37888
	ds_read_b128 v[222:225], v216 offset:38912
	ds_read_b128 v[226:229], v216 offset:39936
	global_load_lds_dwordx4 v[236:237], off
	v_lshl_add_u64 v[236:237], s[62:63], 0, v[176:177]
	s_mov_b32 m0, s21
	s_nop 0
	global_load_lds_dwordx4 v[236:237], off
	s_waitcnt vmcnt(8)
	s_waitcnt lgkmcnt(0)
	s_barrier
	s_setprio 1
	s_waitcnt lgkmcnt(0)
	v_mfma_f32_16x16x32_bf16 v[126:129], v[130:133], v[162:165], v[126:129]
	v_mfma_f32_16x16x32_bf16 v[122:125], v[138:141], v[162:165], v[122:125]
	v_mfma_f32_16x16x32_bf16 v[118:121], v[130:133], v[188:191], v[118:121]
	v_mfma_f32_16x16x32_bf16 v[114:117], v[138:141], v[188:191], v[114:117]
	v_mfma_f32_16x16x32_bf16 v[102:105], v[130:133], v[196:199], v[102:105]
	v_mfma_f32_16x16x32_bf16 v[98:101], v[138:141], v[196:199], v[98:101]
	v_mfma_f32_16x16x32_bf16 v[84:87], v[130:133], v[222:225], v[84:87]
	v_mfma_f32_16x16x32_bf16 v[80:83], v[138:141], v[222:225], v[80:83]
	v_mfma_f32_16x16x32_bf16 v[126:129], v[134:137], v[184:187], v[126:129]
	v_mfma_f32_16x16x32_bf16 v[122:125], v[142:145], v[184:187], v[122:125]
	v_mfma_f32_16x16x32_bf16 v[118:121], v[134:137], v[192:195], v[118:121]
	v_mfma_f32_16x16x32_bf16 v[114:117], v[142:145], v[192:195], v[114:117]
	v_mfma_f32_16x16x32_bf16 v[102:105], v[134:137], v[218:221], v[102:105]
	v_mfma_f32_16x16x32_bf16 v[98:101], v[142:145], v[218:221], v[98:101]
	v_mfma_f32_16x16x32_bf16 v[84:87], v[134:137], v[226:229], v[84:87]
	v_mfma_f32_16x16x32_bf16 v[80:83], v[142:145], v[226:229], v[80:83]
	v_mfma_f32_16x16x32_bf16 v[110:113], v[146:149], v[162:165], v[110:113]
	v_mfma_f32_16x16x32_bf16 v[106:109], v[154:157], v[162:165], v[106:109]
	v_mfma_f32_16x16x32_bf16 v[92:95], v[146:149], v[188:191], v[92:95]
	v_mfma_f32_16x16x32_bf16 v[88:91], v[154:157], v[188:191], v[88:91]
	v_mfma_f32_16x16x32_bf16 v[76:79], v[146:149], v[196:199], v[76:79]
	v_mfma_f32_16x16x32_bf16 v[72:75], v[154:157], v[196:199], v[72:75]
	v_mfma_f32_16x16x32_bf16 v[68:71], v[146:149], v[222:225], v[68:71]
	v_mfma_f32_16x16x32_bf16 v[64:67], v[154:157], v[222:225], v[64:67]
	v_mfma_f32_16x16x32_bf16 v[110:113], v[150:153], v[184:187], v[110:113]
	v_mfma_f32_16x16x32_bf16 v[106:109], v[158:161], v[184:187], v[106:109]
	v_mfma_f32_16x16x32_bf16 v[92:95], v[150:153], v[192:195], v[92:95]
	v_mfma_f32_16x16x32_bf16 v[88:91], v[158:161], v[192:195], v[88:91]
	v_mfma_f32_16x16x32_bf16 v[76:79], v[150:153], v[218:221], v[76:79]
	v_mfma_f32_16x16x32_bf16 v[72:75], v[158:161], v[218:221], v[72:75]
	v_mfma_f32_16x16x32_bf16 v[68:71], v[150:153], v[226:229], v[68:71]
	v_mfma_f32_16x16x32_bf16 v[64:67], v[158:161], v[226:229], v[64:67]
	s_setprio 0
	s_barrier
; #define PG8_STAGE(bufoff, gbase, voff) do { _Pragma("unroll") for (int _i = 0; _i < 2; ++_i) \
;         __builtin_amdgcn_global_load_lds((const unsigned*)((const char*)(gbase) + (voff)[_i]), (PG8_LAS unsigned*)(lds + (bufoff) + ldsw + _i * 8192), 16, 0, 0); } while (0)
; #define PG8_LDA(dst, b, h) do { _Pragma("unroll") for (int m = 0; m < 4; ++m) _Pragma("unroll") for (int k = 0; k < 2; ++k) dst[m][k] = *(const PG8_LAS bf16x8*)(lds + PG8_SA(b, h) + aoff + m * 2048 + k * 1024); } while (0)
; #define PG8_MMA(ai, bj, At, Bt) do { __builtin_amdgcn_s_setprio(1); _Pragma("unroll") for (int m = 0; m < 4; ++m) _Pragma("unroll") for (int n = 0; n < 2; ++n) _Pragma("unroll") for (int k = 0; k < 2; ++k) \
;         acc[ai][bj][m][n] = __builtin_amdgcn_mfma_f32_16x16x32_bf16(Bt[n][k], At[m][k], acc[ai][bj][m][n], 0, 0, 0); __builtin_amdgcn_s_setprio(0); } while (0)
; #define PG8_WAIT_V(n) asm volatile("s_waitcnt vmcnt(" #n ")" ::: "memory")
; #define PG8_WAIT_L(n) asm volatile("s_waitcnt lgkmcnt(" #n ")" ::: "memory")
; #define PG8_BAR __builtin_amdgcn_s_barrier()
; #define PG8_SCHED __builtin_amdgcn_sched_barrier(0)
; template <class Epi, class Sched, bool ALIGN_EPI = false, bool SP2 = false>
; __device__ __forceinline__ void gemm_phase(PG8_LAS unsigned char* lds, const Gemm g, const Sched& S, const Epi& E, int tid_in) {
;     ...
;             PG8_LDA(At, 1, 1); PG8_STAGE(PG8_SB(1, 0), b3, voffB); PG8_STAGE(PG8_SB(1, 1), b3 + hstep, voffB); PG8_STAGE(PG8_SA(1, 0), a3, voffA);
;             PG8_WAIT_V(8); PG8_WAIT_L(0); PG8_BAR; PG8_MMA(1, 0, At, B0); PG8_MMA(1, 1, At, B1); PG8_BAR; PG8_SCHED;
;     __device__ __forceinline__ void operator()(const acc_t& acc, const pg8::Unit& u, int wr, int wc, int fr, int fq) const {
;         const int pn = u.pn, row0 = u.pm * 256 + wr * 64 + fr, cw = wc * 32 + 8 * fq;
;         if (pn < 4) store_tile_bf16<0>(acc, RQ, 1024, row0, pn * 256 + cw);
	s_add_i32 s62, s76, s96
	v_lshl_add_u64 v[200:201], v[200:201], 0, s[88:89]
	s_mov_b32 m0, s62
	ds_read_b128 v[162:165], v216 offset:49152
	ds_read_b128 v[184:187], v216 offset:50176
	ds_read_b128 v[188:191], v216 offset:51200
	ds_read_b128 v[192:195], v216 offset:52224
	ds_read_b128 v[196:199], v216 offset:53248
	ds_read_b128 v[218:221], v216 offset:54272
	ds_read_b128 v[222:225], v216 offset:55296
	ds_read_b128 v[226:229], v216 offset:56320
	global_load_lds_dwordx4 v[200:201], off
	s_add_i32 m0, s62, 0x2000
	s_add_u32 s46, s46, 0x80080
	v_lshl_add_u64 v[200:201], v[230:231], 0, s[88:89]
	s_addc_u32 s47, s47, 0
	s_add_i32 s62, s77, s96
	global_load_lds_dwordx4 v[200:201], off
	v_lshl_add_u64 v[200:201], s[46:47], 0, v[174:175]
	s_mov_b32 m0, s62
	s_nop 0
	global_load_lds_dwordx4 v[200:201], off
	v_lshl_add_u64 v[200:201], s[46:47], 0, v[178:179]
	s_add_i32 m0, s62, 0x2000
	s_nop 0
	global_load_lds_dwordx4 v[200:201], off
	v_lshl_add_u64 v[200:201], v[232:233], 0, s[88:89]
	s_mov_b32 m0, s22
	s_nop 0
	global_load_lds_dwordx4 v[200:201], off
	v_lshl_add_u64 v[200:201], v[234:235], 0, s[88:89]
	s_mov_b32 m0, s23
	s_nop 0
	global_load_lds_dwordx4 v[200:201], off
	s_waitcnt vmcnt(8)
	s_waitcnt lgkmcnt(0)
	s_barrier
	s_setprio 1
	s_waitcnt lgkmcnt(0)
	v_mfma_f32_16x16x32_bf16 v[60:63], v[130:133], v[162:165], v[60:63]
	v_mfma_f32_16x16x32_bf16 v[56:59], v[138:141], v[162:165], v[56:59]
	v_mfma_f32_16x16x32_bf16 v[52:55], v[130:133], v[188:191], v[52:55]
	v_mfma_f32_16x16x32_bf16 v[48:51], v[138:141], v[188:191], v[48:51]
	v_mfma_f32_16x16x32_bf16 v[36:39], v[130:133], v[196:199], v[36:39]
	v_mfma_f32_16x16x32_bf16 v[32:35], v[138:141], v[196:199], v[32:35]
	v_mfma_f32_16x16x32_bf16 v[20:23], v[130:133], v[222:225], v[20:23]
	v_mfma_f32_16x16x32_bf16 v[16:19], v[138:141], v[222:225], v[16:19]
	v_mfma_f32_16x16x32_bf16 v[60:63], v[134:137], v[184:187], v[60:63]
	v_mfma_f32_16x16x32_bf16 v[56:59], v[142:145], v[184:187], v[56:59]
	v_mfma_f32_16x16x32_bf16 v[52:55], v[134:137], v[192:195], v[52:55]
	v_mfma_f32_16x16x32_bf16 v[48:51], v[142:145], v[192:195], v[48:51]
	v_mfma_f32_16x16x32_bf16 v[36:39], v[134:137], v[218:221], v[36:39]
	v_mfma_f32_16x16x32_bf16 v[32:35], v[142:145], v[218:221], v[32:35]
	v_mfma_f32_16x16x32_bf16 v[20:23], v[134:137], v[226:229], v[20:23]
	v_mfma_f32_16x16x32_bf16 v[16:19], v[142:145], v[226:229], v[16:19]
	v_mfma_f32_16x16x32_bf16 v[44:47], v[146:149], v[162:165], v[44:47]
	v_mfma_f32_16x16x32_bf16 v[40:43], v[154:157], v[162:165], v[40:43]
	v_mfma_f32_16x16x32_bf16 v[28:31], v[146:149], v[188:191], v[28:31]
	v_mfma_f32_16x16x32_bf16 v[24:27], v[154:157], v[188:191], v[24:27]
	v_mfma_f32_16x16x32_bf16 v[12:15], v[146:149], v[196:199], v[12:15]
	v_mfma_f32_16x16x32_bf16 v[8:11], v[154:157], v[196:199], v[8:11]
	v_mfma_f32_16x16x32_bf16 v[4:7], v[146:149], v[222:225], v[4:7]
	v_mfma_f32_16x16x32_bf16 v[0:3], v[154:157], v[222:225], v[0:3]
	v_mfma_f32_16x16x32_bf16 v[44:47], v[150:153], v[184:187], v[44:47]
	v_mfma_f32_16x16x32_bf16 v[40:43], v[158:161], v[184:187], v[40:43]
	v_mfma_f32_16x16x32_bf16 v[28:31], v[150:153], v[192:195], v[28:31]
	v_mfma_f32_16x16x32_bf16 v[24:27], v[158:161], v[192:195], v[24:27]
	v_mfma_f32_16x16x32_bf16 v[12:15], v[150:153], v[218:221], v[12:15]
	v_mfma_f32_16x16x32_bf16 v[8:11], v[158:161], v[218:221], v[8:11]
	v_mfma_f32_16x16x32_bf16 v[4:7], v[150:153], v[226:229], v[4:7]
	v_mfma_f32_16x16x32_bf16 v[0:3], v[158:161], v[226:229], v[0:3]
	s_setprio 0
	s_barrier
	s_add_i32 s75, s75, 2
	s_add_u32 s44, s44, 0x100
	s_addc_u32 s45, s45, 0
	s_add_u32 s73, s73, 0x100
	s_addc_u32 s74, s74, 0
	s_cmp_gt_u32 s75, 29
	s_cbranch_scc0 .LBB0_403
	s_and_b64 vcc, exec, s[30:31]
	s_cbranch_vccnz .LBB0_408
	v_lshl_add_u32 v184, s42, 8, v204
	s_cmp_gt_i32 s28, 3
	s_mov_b64 s[42:43], -1
	s_cbranch_scc1 .LBB0_409

; #define PG8_STAGE(bufoff, gbase, voff) do { _Pragma("unroll") for (int _i = 0; _i < 2; ++_i) \
;         __builtin_amdgcn_global_load_lds((const unsigned*)((const char*)(gbase) + (voff)[_i]), (PG8_LAS unsigned*)(lds + (bufoff) + ldsw + _i * 8192), 16, 0, 0); } while (0)
; #define PG8_LDA(dst, b, h) do { _Pragma("unroll") for (int m = 0; m < 4; ++m) _Pragma("unroll") for (int k = 0; k < 2; ++k) dst[m][k] = *(const PG8_LAS bf16x8*)(lds + PG8_SA(b, h) + aoff + m * 2048 + k * 1024); } while (0)
; #define PG8_LDB(dst, b, h) do { _Pragma("unroll") for (int n = 0; n < 2; ++n) _Pragma("unroll") for (int k = 0; k < 2; ++k) dst[n][k] = *(const PG8_LAS bf16x8*)(lds + PG8_SB(b, h) + boff + n * 2048 + k * 1024); } while (0)
; #define PG8_MMA(ai, bj, At, Bt) do { __builtin_amdgcn_s_setprio(1); _Pragma("unroll") for (int m = 0; m < 4; ++m) _Pragma("unroll") for (int n = 0; n < 2; ++n) _Pragma("unroll") for (int k = 0; k < 2; ++k) \
;         acc[ai][bj][m][n] = __builtin_amdgcn_mfma_f32_16x16x32_bf16(Bt[n][k], At[m][k], acc[ai][bj][m][n], 0, 0, 0); __builtin_amdgcn_s_setprio(0); } while (0)
; #define PG8_WAIT_V(n) asm volatile("s_waitcnt vmcnt(" #n ")" ::: "memory")
; #define PG8_WAIT_L(n) asm volatile("s_waitcnt lgkmcnt(" #n ")" ::: "memory")
; template <class Epi, class Sched, bool ALIGN_EPI = false, bool SP2 = false>
; __device__ __forceinline__ void gemm_phase(PG8_LAS unsigned char* lds, const Gemm g, const Sched& S, const Epi& E, int tid_in) {
;     ...
;             const bool last = (t == nt - 2);
;             const char* a1 = cA + (size_t)(t + 1) * kstep;
;             const char* a2 = last ? nA : cA + (size_t)(t + 2) * kstep; const char* b2 = last ? nB : cB + (size_t)(t + 2) * kstep;
;             const char* a3 = a2 + kstep; const char* b3 = b2 + kstep;
;             if (last && has_next) S.a_ready(nxt);
;             if constexpr (SP2) {
;             PG8_LDB(B0, 0, 0); PG8_LDB(B1, 0, 1); PG8_SCHED; PG8_LDA(At, 0, 0); PG8_STAGE(PG8_SA(1, 1), a1 + hstep, voffA);
;             PG8_WAIT_V(8); PG8_WAIT_L(0); PG8_BAR; PG8_MMA(0, 0, At, B0); PG8_MMA(0, 1, At, B1); PG8_BAR; PG8_SCHED;
;             PG8_LDA(At, 0, 1); PG8_STAGE(PG8_SB(0, 0), b2, voffB); PG8_STAGE(PG8_SB(0, 1), b2 + hstep, voffB); PG8_STAGE(PG8_SA(0, 0), a2, voffA);
;             PG8_WAIT_V(8); PG8_WAIT_L(0); PG8_BAR; PG8_MMA(1, 0, At, B0); PG8_MMA(1, 1, At, B1); PG8_BAR; PG8_SCHED;
.LBB0_455:
	s_add_u32 s42, s40, 0xfff80080
	s_addc_u32 s43, s41, -1
	s_add_i32 s62, 0, 0x10000
	s_cmp_eq_u32 s77, 28
	s_cselect_b32 s45, s39, s43
	s_cselect_b32 s44, s73, s42
	v_add_u32_e32 v96, s62, v203
	s_cselect_b32 s43, s37, s76
	s_cselect_b32 s42, s74, s75
	s_add_i32 s78, 0, 0x14000
	ds_read_b128 v[130:133], v96
	ds_read_b128 v[134:137], v96 offset:1024
	ds_read_b128 v[138:141], v96 offset:2048
	ds_read_b128 v[142:145], v96 offset:3072
	v_add_u32_e32 v96, s78, v203
	ds_read_b128 v[146:149], v96
	ds_read_b128 v[150:153], v96 offset:1024
	ds_read_b128 v[154:157], v96 offset:2048
	ds_read_b128 v[158:161], v96 offset:3072
	v_lshl_add_u64 v[196:197], s[40:41], 0, v[180:181]
	s_add_i32 m0, s1, 0xc000
	ds_read_b128 v[162:165], v215
	ds_read_b128 v[184:187], v215 offset:1024
	ds_read_b128 v[188:191], v215 offset:2048
	ds_read_b128 v[192:195], v215 offset:3072
	ds_read_b128 v[216:219], v215 offset:4096
	ds_read_b128 v[220:223], v215 offset:5120
	ds_read_b128 v[224:227], v215 offset:6144
	ds_read_b128 v[228:231], v215 offset:7168
	global_load_lds_dwordx4 v[196:197], off
	v_lshl_add_u64 v[196:197], s[40:41], 0, v[182:183]
	s_add_i32 m0, s1, 0xe000
	s_nop 0
	global_load_lds_dwordx4 v[196:197], off
	s_waitcnt vmcnt(8)
	s_waitcnt lgkmcnt(0)
	s_barrier
	s_setprio 1
	s_waitcnt lgkmcnt(0)
	v_mfma_f32_16x16x32_bf16 v[126:129], v[130:133], v[162:165], v[126:129]
	v_mfma_f32_16x16x32_bf16 v[122:125], v[138:141], v[162:165], v[122:125]
	v_mfma_f32_16x16x32_bf16 v[118:121], v[130:133], v[188:191], v[118:121]
	v_mfma_f32_16x16x32_bf16 v[114:117], v[138:141], v[188:191], v[114:117]
	v_mfma_f32_16x16x32_bf16 v[102:105], v[130:133], v[216:219], v[102:105]
	v_mfma_f32_16x16x32_bf16 v[98:101], v[138:141], v[216:219], v[98:101]
	v_mfma_f32_16x16x32_bf16 v[84:87], v[130:133], v[224:227], v[84:87]
	v_mfma_f32_16x16x32_bf16 v[80:83], v[138:141], v[224:227], v[80:83]
	v_mfma_f32_16x16x32_bf16 v[126:129], v[134:137], v[184:187], v[126:129]
	v_mfma_f32_16x16x32_bf16 v[122:125], v[142:145], v[184:187], v[122:125]
	v_mfma_f32_16x16x32_bf16 v[118:121], v[134:137], v[192:195], v[118:121]
	v_mfma_f32_16x16x32_bf16 v[114:117], v[142:145], v[192:195], v[114:117]
	v_mfma_f32_16x16x32_bf16 v[102:105], v[134:137], v[220:223], v[102:105]
	v_mfma_f32_16x16x32_bf16 v[98:101], v[142:145], v[220:223], v[98:101]
	v_mfma_f32_16x16x32_bf16 v[84:87], v[134:137], v[228:231], v[84:87]
	v_mfma_f32_16x16x32_bf16 v[80:83], v[142:145], v[228:231], v[80:83]
	v_mfma_f32_16x16x32_bf16 v[110:113], v[146:149], v[162:165], v[110:113]
	v_mfma_f32_16x16x32_bf16 v[106:109], v[154:157], v[162:165], v[106:109]
	v_mfma_f32_16x16x32_bf16 v[92:95], v[146:149], v[188:191], v[92:95]
	v_mfma_f32_16x16x32_bf16 v[88:91], v[154:157], v[188:191], v[88:91]
	v_mfma_f32_16x16x32_bf16 v[76:79], v[146:149], v[216:219], v[76:79]
	v_mfma_f32_16x16x32_bf16 v[72:75], v[154:157], v[216:219], v[72:75]
	v_mfma_f32_16x16x32_bf16 v[68:71], v[146:149], v[224:227], v[68:71]
	v_mfma_f32_16x16x32_bf16 v[64:67], v[154:157], v[224:227], v[64:67]
	v_mfma_f32_16x16x32_bf16 v[110:113], v[150:153], v[184:187], v[110:113]
	v_mfma_f32_16x16x32_bf16 v[106:109], v[158:161], v[184:187], v[106:109]
	v_mfma_f32_16x16x32_bf16 v[92:95], v[150:153], v[192:195], v[92:95]
	v_mfma_f32_16x16x32_bf16 v[88:91], v[158:161], v[192:195], v[88:91]
	v_mfma_f32_16x16x32_bf16 v[76:79], v[150:153], v[220:223], v[76:79]
	v_mfma_f32_16x16x32_bf16 v[72:75], v[158:161], v[220:223], v[72:75]
	v_mfma_f32_16x16x32_bf16 v[68:71], v[150:153], v[228:231], v[68:71]
	v_mfma_f32_16x16x32_bf16 v[64:67], v[158:161], v[228:231], v[64:67]
	s_setprio 0
	s_barrier
	s_add_i32 s62, s62, s64
	v_lshl_add_u64 v[196:197], s[42:43], 0, v[176:177]
	s_mov_b32 m0, s62
	ds_read_b128 v[162:165], v215 offset:16384
	ds_read_b128 v[184:187], v215 offset:17408
	ds_read_b128 v[188:191], v215 offset:18432
	ds_read_b128 v[192:195], v215 offset:19456
	ds_read_b128 v[216:219], v215 offset:20480
	ds_read_b128 v[220:223], v215 offset:21504
	ds_read_b128 v[224:227], v215 offset:22528
	ds_read_b128 v[228:231], v215 offset:23552
	global_load_lds_dwordx4 v[196:197], off
	s_add_i32 m0, s62, 0x2000
	s_add_u32 s62, s42, 0x80000
	v_lshl_add_u64 v[198:199], s[42:43], 0, v[172:173]
	s_addc_u32 s63, s43, 0
	s_add_i32 s78, s78, s64
	global_load_lds_dwordx4 v[198:199], off
	v_lshl_add_u64 v[200:201], s[62:63], 0, v[176:177]
	s_mov_b32 m0, s78
	v_lshl_add_u64 v[232:233], s[44:45], 0, v[174:175]
	global_load_lds_dwordx4 v[200:201], off
	v_lshl_add_u64 v[200:201], s[62:63], 0, v[172:173]
	s_add_i32 m0, s78, 0x2000
	s_nop 0
	global_load_lds_dwordx4 v[200:201], off
	v_lshl_add_u64 v[200:201], s[44:45], 0, v[178:179]
	s_mov_b32 m0, s1
	s_nop 0
	global_load_lds_dwordx4 v[200:201], off
	s_mov_b32 m0, s3
	s_nop 0
	global_load_lds_dwordx4 v[232:233], off
	s_waitcnt vmcnt(8)
	s_waitcnt lgkmcnt(0)
	s_barrier
; #define PG8_STAGE(bufoff, gbase, voff) do { _Pragma("unroll") for (int _i = 0; _i < 2; ++_i) \
;         __builtin_amdgcn_global_load_lds((const unsigned*)((const char*)(gbase) + (voff)[_i]), (PG8_LAS unsigned*)(lds + (bufoff) + ldsw + _i * 8192), 16, 0, 0); } while (0)
; #define PG8_LDA(dst, b, h) do { _Pragma("unroll") for (int m = 0; m < 4; ++m) _Pragma("unroll") for (int k = 0; k < 2; ++k) dst[m][k] = *(const PG8_LAS bf16x8*)(lds + PG8_SA(b, h) + aoff + m * 2048 + k * 1024); } while (0)
; #define PG8_LDB(dst, b, h) do { _Pragma("unroll") for (int n = 0; n < 2; ++n) _Pragma("unroll") for (int k = 0; k < 2; ++k) dst[n][k] = *(const PG8_LAS bf16x8*)(lds + PG8_SB(b, h) + boff + n * 2048 + k * 1024); } while (0)
; #define PG8_MMA(ai, bj, At, Bt) do { __builtin_amdgcn_s_setprio(1); _Pragma("unroll") for (int m = 0; m < 4; ++m) _Pragma("unroll") for (int n = 0; n < 2; ++n) _Pragma("unroll") for (int k = 0; k < 2; ++k) \
;         acc[ai][bj][m][n] = __builtin_amdgcn_mfma_f32_16x16x32_bf16(Bt[n][k], At[m][k], acc[ai][bj][m][n], 0, 0, 0); __builtin_amdgcn_s_setprio(0); } while (0)
; #define PG8_WAIT_V(n) asm volatile("s_waitcnt vmcnt(" #n ")" ::: "memory")
; #define PG8_WAIT_L(n) asm volatile("s_waitcnt lgkmcnt(" #n ")" ::: "memory")
; #define PG8_BAR __builtin_amdgcn_s_barrier()
; #define PG8_SCHED __builtin_amdgcn_sched_barrier(0)
; template <class Epi, class Sched, bool ALIGN_EPI = false, bool SP2 = false>
; __device__ __forceinline__ void gemm_phase(PG8_LAS unsigned char* lds, const Gemm g, const Sched& S, const Epi& E, int tid_in) {
;     ...
;             PG8_WAIT_V(8); PG8_WAIT_L(0); PG8_BAR; PG8_MMA(1, 0, At, B0); PG8_MMA(1, 1, At, B1); PG8_BAR; PG8_SCHED;
;             PG8_LDB(B0, 1, 0); PG8_LDB(B1, 1, 1); PG8_SCHED; PG8_LDA(At, 1, 0); PG8_STAGE(PG8_SA(0, 1), a2 + hstep, voffA);
;             PG8_WAIT_V(8); PG8_WAIT_L(0); PG8_BAR; PG8_MMA(0, 0, At, B0); PG8_MMA(0, 1, At, B1); PG8_BAR; PG8_SCHED;
	s_setprio 1
	s_waitcnt lgkmcnt(0)
	v_mfma_f32_16x16x32_bf16 v[60:63], v[130:133], v[162:165], v[60:63]
	v_mfma_f32_16x16x32_bf16 v[56:59], v[138:141], v[162:165], v[56:59]
	v_mfma_f32_16x16x32_bf16 v[52:55], v[130:133], v[188:191], v[52:55]
	v_mfma_f32_16x16x32_bf16 v[48:51], v[138:141], v[188:191], v[48:51]
	v_mfma_f32_16x16x32_bf16 v[36:39], v[130:133], v[216:219], v[36:39]
	v_mfma_f32_16x16x32_bf16 v[32:35], v[138:141], v[216:219], v[32:35]
	v_mfma_f32_16x16x32_bf16 v[20:23], v[130:133], v[224:227], v[20:23]
	v_mfma_f32_16x16x32_bf16 v[16:19], v[138:141], v[224:227], v[16:19]
	v_mfma_f32_16x16x32_bf16 v[60:63], v[134:137], v[184:187], v[60:63]
	v_mfma_f32_16x16x32_bf16 v[56:59], v[142:145], v[184:187], v[56:59]
	v_mfma_f32_16x16x32_bf16 v[52:55], v[134:137], v[192:195], v[52:55]
	v_mfma_f32_16x16x32_bf16 v[48:51], v[142:145], v[192:195], v[48:51]
	v_mfma_f32_16x16x32_bf16 v[36:39], v[134:137], v[220:223], v[36:39]
	v_mfma_f32_16x16x32_bf16 v[32:35], v[142:145], v[220:223], v[32:35]
	v_mfma_f32_16x16x32_bf16 v[20:23], v[134:137], v[228:231], v[20:23]
	v_mfma_f32_16x16x32_bf16 v[16:19], v[142:145], v[228:231], v[16:19]
	v_mfma_f32_16x16x32_bf16 v[44:47], v[146:149], v[162:165], v[44:47]
	v_mfma_f32_16x16x32_bf16 v[40:43], v[154:157], v[162:165], v[40:43]
	v_mfma_f32_16x16x32_bf16 v[28:31], v[146:149], v[188:191], v[28:31]
	v_mfma_f32_16x16x32_bf16 v[24:27], v[154:157], v[188:191], v[24:27]
	v_mfma_f32_16x16x32_bf16 v[12:15], v[146:149], v[216:219], v[12:15]
	v_mfma_f32_16x16x32_bf16 v[8:11], v[154:157], v[216:219], v[8:11]
	v_mfma_f32_16x16x32_bf16 v[4:7], v[146:149], v[224:227], v[4:7]
	v_mfma_f32_16x16x32_bf16 v[0:3], v[154:157], v[224:227], v[0:3]
	v_mfma_f32_16x16x32_bf16 v[44:47], v[150:153], v[184:187], v[44:47]
	v_mfma_f32_16x16x32_bf16 v[40:43], v[158:161], v[184:187], v[40:43]
	v_mfma_f32_16x16x32_bf16 v[28:31], v[150:153], v[192:195], v[28:31]
	v_mfma_f32_16x16x32_bf16 v[24:27], v[158:161], v[192:195], v[24:27]
	v_mfma_f32_16x16x32_bf16 v[12:15], v[150:153], v[220:223], v[12:15]
	v_mfma_f32_16x16x32_bf16 v[8:11], v[158:161], v[220:223], v[8:11]
	v_mfma_f32_16x16x32_bf16 v[4:7], v[150:153], v[228:231], v[4:7]
	v_mfma_f32_16x16x32_bf16 v[0:3], v[158:161], v[228:231], v[0:3]
	s_setprio 0
	s_barrier
	s_add_i32 s62, 0, 0x18000
	v_add_u32_e32 v96, s62, v203
	s_add_i32 s63, 0, 0x1c000
	ds_read_b128 v[130:133], v96
	ds_read_b128 v[134:137], v96 offset:1024
	ds_read_b128 v[138:141], v96 offset:2048
	ds_read_b128 v[142:145], v96 offset:3072
	v_add_u32_e32 v96, s63, v203
	ds_read_b128 v[146:149], v96
	ds_read_b128 v[150:153], v96 offset:1024
	ds_read_b128 v[154:157], v96 offset:2048
	ds_read_b128 v[158:161], v96 offset:3072
	s_add_u32 s44, s44, 0x80000
	s_addc_u32 s45, s45, 0
	s_mov_b32 m0, s65
	v_lshl_add_u64 v[234:235], s[44:45], 0, v[178:179]
	ds_read_b128 v[162:165], v215 offset:32768
	ds_read_b128 v[184:187], v215 offset:33792
	ds_read_b128 v[188:191], v215 offset:34816
	ds_read_b128 v[192:195], v215 offset:35840
	ds_read_b128 v[216:219], v215 offset:36864
	ds_read_b128 v[220:223], v215 offset:37888
	ds_read_b128 v[224:227], v215 offset:38912
	ds_read_b128 v[228:231], v215 offset:39936
	global_load_lds_dwordx4 v[234:235], off
	v_lshl_add_u64 v[234:235], s[44:45], 0, v[174:175]
	s_mov_b32 m0, s66
	s_nop 0
	global_load_lds_dwordx4 v[234:235], off
	s_waitcnt vmcnt(8)
	s_waitcnt lgkmcnt(0)
	s_barrier
	s_setprio 1
	s_waitcnt lgkmcnt(0)
	v_mfma_f32_16x16x32_bf16 v[126:129], v[130:133], v[162:165], v[126:129]
	v_mfma_f32_16x16x32_bf16 v[122:125], v[138:141], v[162:165], v[122:125]
	v_mfma_f32_16x16x32_bf16 v[118:121], v[130:133], v[188:191], v[118:121]
	v_mfma_f32_16x16x32_bf16 v[114:117], v[138:141], v[188:191], v[114:117]
	v_mfma_f32_16x16x32_bf16 v[102:105], v[130:133], v[216:219], v[102:105]
	v_mfma_f32_16x16x32_bf16 v[98:101], v[138:141], v[216:219], v[98:101]
	v_mfma_f32_16x16x32_bf16 v[84:87], v[130:133], v[224:227], v[84:87]
	v_mfma_f32_16x16x32_bf16 v[80:83], v[138:141], v[224:227], v[80:83]
	v_mfma_f32_16x16x32_bf16 v[126:129], v[134:137], v[184:187], v[126:129]
	v_mfma_f32_16x16x32_bf16 v[122:125], v[142:145], v[184:187], v[122:125]
	v_mfma_f32_16x16x32_bf16 v[118:121], v[134:137], v[192:195], v[118:121]
	v_mfma_f32_16x16x32_bf16 v[114:117], v[142:145], v[192:195], v[114:117]
	v_mfma_f32_16x16x32_bf16 v[102:105], v[134:137], v[220:223], v[102:105]
	v_mfma_f32_16x16x32_bf16 v[98:101], v[142:145], v[220:223], v[98:101]
	v_mfma_f32_16x16x32_bf16 v[84:87], v[134:137], v[228:231], v[84:87]
	v_mfma_f32_16x16x32_bf16 v[80:83], v[142:145], v[228:231], v[80:83]
	v_mfma_f32_16x16x32_bf16 v[110:113], v[146:149], v[162:165], v[110:113]
	v_mfma_f32_16x16x32_bf16 v[106:109], v[154:157], v[162:165], v[106:109]
	v_mfma_f32_16x16x32_bf16 v[92:95], v[146:149], v[188:191], v[92:95]
	v_mfma_f32_16x16x32_bf16 v[88:91], v[154:157], v[188:191], v[88:91]
	v_mfma_f32_16x16x32_bf16 v[76:79], v[146:149], v[216:219], v[76:79]
	v_mfma_f32_16x16x32_bf16 v[72:75], v[154:157], v[216:219], v[72:75]
	v_mfma_f32_16x16x32_bf16 v[68:71], v[146:149], v[224:227], v[68:71]
	v_mfma_f32_16x16x32_bf16 v[64:67], v[154:157], v[224:227], v[64:67]
	v_mfma_f32_16x16x32_bf16 v[110:113], v[150:153], v[184:187], v[110:113]
	v_mfma_f32_16x16x32_bf16 v[106:109], v[158:161], v[184:187], v[106:109]
	v_mfma_f32_16x16x32_bf16 v[92:95], v[150:153], v[192:195], v[92:95]
	v_mfma_f32_16x16x32_bf16 v[88:91], v[158:161], v[192:195], v[88:91]
	v_mfma_f32_16x16x32_bf16 v[76:79], v[150:153], v[220:223], v[76:79]
	v_mfma_f32_16x16x32_bf16 v[72:75], v[158:161], v[220:223], v[72:75]
	v_mfma_f32_16x16x32_bf16 v[68:71], v[150:153], v[228:231], v[68:71]
	v_mfma_f32_16x16x32_bf16 v[64:67], v[158:161], v[228:231], v[64:67]
	s_setprio 0
	s_barrier
; #define PG8_STAGE(bufoff, gbase, voff) do { _Pragma("unroll") for (int _i = 0; _i < 2; ++_i) \
;         __builtin_amdgcn_global_load_lds((const unsigned*)((const char*)(gbase) + (voff)[_i]), (PG8_LAS unsigned*)(lds + (bufoff) + ldsw + _i * 8192), 16, 0, 0); } while (0)
; #define PG8_LDA(dst, b, h) do { _Pragma("unroll") for (int m = 0; m < 4; ++m) _Pragma("unroll") for (int k = 0; k < 2; ++k) dst[m][k] = *(const PG8_LAS bf16x8*)(lds + PG8_SA(b, h) + aoff + m * 2048 + k * 1024); } while (0)
; #define PG8_MMA(ai, bj, At, Bt) do { __builtin_amdgcn_s_setprio(1); _Pragma("unroll") for (int m = 0; m < 4; ++m) _Pragma("unroll") for (int n = 0; n < 2; ++n) _Pragma("unroll") for (int k = 0; k < 2; ++k) \
;         acc[ai][bj][m][n] = __builtin_amdgcn_mfma_f32_16x16x32_bf16(Bt[n][k], At[m][k], acc[ai][bj][m][n], 0, 0, 0); __builtin_amdgcn_s_setprio(0); } while (0)
; #define PG8_WAIT_V(n) asm volatile("s_waitcnt vmcnt(" #n ")" ::: "memory")
; #define PG8_WAIT_L(n) asm volatile("s_waitcnt lgkmcnt(" #n ")" ::: "memory")
; #define PG8_BAR __builtin_amdgcn_s_barrier()
; #define PG8_SCHED __builtin_amdgcn_sched_barrier(0)
; template <class Epi, class Sched, bool ALIGN_EPI = false, bool SP2 = false>
; __device__ __forceinline__ void gemm_phase(PG8_LAS unsigned char* lds, const Gemm g, const Sched& S, const Epi& E, int tid_in) {
;     ...
;             PG8_LDA(At, 1, 1); PG8_STAGE(PG8_SB(1, 0), b3, voffB); PG8_STAGE(PG8_SB(1, 1), b3 + hstep, voffB); PG8_STAGE(PG8_SA(1, 0), a3, voffA);
;             PG8_WAIT_V(8); PG8_WAIT_L(0); PG8_BAR; PG8_MMA(1, 0, At, B0); PG8_MMA(1, 1, At, B1); PG8_BAR; PG8_SCHED;
;     ...
;         if constexpr (ALIGN_EPI) { if (wr == 0) PG8_BAR; }
	s_add_i32 s44, s62, s64
	v_lshl_add_u64 v[196:197], v[196:197], 0, s[88:89]
	s_mov_b32 m0, s44
	ds_read_b128 v[162:165], v215 offset:49152
	ds_read_b128 v[184:187], v215 offset:50176
	ds_read_b128 v[188:191], v215 offset:51200
	ds_read_b128 v[192:195], v215 offset:52224
	ds_read_b128 v[216:219], v215 offset:53248
	ds_read_b128 v[220:223], v215 offset:54272
	ds_read_b128 v[224:227], v215 offset:55296
	ds_read_b128 v[228:231], v215 offset:56320
	global_load_lds_dwordx4 v[196:197], off
	s_add_i32 m0, s44, 0x2000
	s_add_u32 s42, s42, 0x80080
	v_lshl_add_u64 v[196:197], v[198:199], 0, s[88:89]
	s_addc_u32 s43, s43, 0
	s_add_i32 s44, s63, s64
	global_load_lds_dwordx4 v[196:197], off
	v_lshl_add_u64 v[196:197], s[42:43], 0, v[176:177]
	s_mov_b32 m0, s44
	s_nop 0
	global_load_lds_dwordx4 v[196:197], off
	v_lshl_add_u64 v[196:197], s[42:43], 0, v[172:173]
	s_add_i32 m0, s44, 0x2000
	s_nop 0
	global_load_lds_dwordx4 v[196:197], off
	v_lshl_add_u64 v[196:197], v[200:201], 0, s[88:89]
	s_mov_b32 m0, s67
	s_nop 0
	global_load_lds_dwordx4 v[196:197], off
	v_lshl_add_u64 v[196:197], v[232:233], 0, s[88:89]
	s_mov_b32 m0, s71
	s_nop 0
	global_load_lds_dwordx4 v[196:197], off
	s_waitcnt vmcnt(8)
	s_waitcnt lgkmcnt(0)
	s_barrier
	s_setprio 1
	s_waitcnt lgkmcnt(0)
	v_mfma_f32_16x16x32_bf16 v[60:63], v[130:133], v[162:165], v[60:63]
	v_mfma_f32_16x16x32_bf16 v[56:59], v[138:141], v[162:165], v[56:59]
	v_mfma_f32_16x16x32_bf16 v[52:55], v[130:133], v[188:191], v[52:55]
	v_mfma_f32_16x16x32_bf16 v[48:51], v[138:141], v[188:191], v[48:51]
	v_mfma_f32_16x16x32_bf16 v[36:39], v[130:133], v[216:219], v[36:39]
	v_mfma_f32_16x16x32_bf16 v[32:35], v[138:141], v[216:219], v[32:35]
	v_mfma_f32_16x16x32_bf16 v[20:23], v[130:133], v[224:227], v[20:23]
	v_mfma_f32_16x16x32_bf16 v[16:19], v[138:141], v[224:227], v[16:19]
	v_mfma_f32_16x16x32_bf16 v[60:63], v[134:137], v[184:187], v[60:63]
	v_mfma_f32_16x16x32_bf16 v[56:59], v[142:145], v[184:187], v[56:59]
	v_mfma_f32_16x16x32_bf16 v[52:55], v[134:137], v[192:195], v[52:55]
	v_mfma_f32_16x16x32_bf16 v[48:51], v[142:145], v[192:195], v[48:51]
	v_mfma_f32_16x16x32_bf16 v[36:39], v[134:137], v[220:223], v[36:39]
	v_mfma_f32_16x16x32_bf16 v[32:35], v[142:145], v[220:223], v[32:35]
	v_mfma_f32_16x16x32_bf16 v[20:23], v[134:137], v[228:231], v[20:23]
	v_mfma_f32_16x16x32_bf16 v[16:19], v[142:145], v[228:231], v[16:19]
	v_mfma_f32_16x16x32_bf16 v[44:47], v[146:149], v[162:165], v[44:47]
	v_mfma_f32_16x16x32_bf16 v[40:43], v[154:157], v[162:165], v[40:43]
	v_mfma_f32_16x16x32_bf16 v[28:31], v[146:149], v[188:191], v[28:31]
	v_mfma_f32_16x16x32_bf16 v[24:27], v[154:157], v[188:191], v[24:27]
	v_mfma_f32_16x16x32_bf16 v[12:15], v[146:149], v[216:219], v[12:15]
	v_mfma_f32_16x16x32_bf16 v[8:11], v[154:157], v[216:219], v[8:11]
	v_mfma_f32_16x16x32_bf16 v[4:7], v[146:149], v[224:227], v[4:7]
	v_mfma_f32_16x16x32_bf16 v[0:3], v[154:157], v[224:227], v[0:3]
	v_mfma_f32_16x16x32_bf16 v[44:47], v[150:153], v[184:187], v[44:47]
	v_mfma_f32_16x16x32_bf16 v[40:43], v[158:161], v[184:187], v[40:43]
	v_mfma_f32_16x16x32_bf16 v[28:31], v[150:153], v[192:195], v[28:31]
	v_mfma_f32_16x16x32_bf16 v[24:27], v[158:161], v[192:195], v[24:27]
	v_mfma_f32_16x16x32_bf16 v[12:15], v[150:153], v[220:223], v[12:15]
	v_mfma_f32_16x16x32_bf16 v[8:11], v[158:161], v[220:223], v[8:11]
	v_mfma_f32_16x16x32_bf16 v[4:7], v[150:153], v[228:231], v[4:7]
	v_mfma_f32_16x16x32_bf16 v[0:3], v[158:161], v[228:231], v[0:3]
	s_setprio 0
	s_barrier
	s_add_i32 s77, s77, 2
	s_add_u32 s40, s40, 0x100
	s_addc_u32 s41, s41, 0
	s_add_u32 s75, s75, 0x100
	s_addc_u32 s76, s76, 0
	s_cmp_gt_u32 s77, 29
	s_cbranch_scc0 .LBB0_455
	s_and_b64 vcc, exec, s[34:35]
	s_cbranch_vccz .LBB0_458
	s_barrier

; #define PG8_STAGE(bufoff, gbase, voff) do { _Pragma("unroll") for (int _i = 0; _i < 2; ++_i) \
;         __builtin_amdgcn_global_load_lds((const unsigned*)((const char*)(gbase) + (voff)[_i]), (PG8_LAS unsigned*)(lds + (bufoff) + ldsw + _i * 8192), 16, 0, 0); } while (0)
; #define PG8_LDA(dst, b, h) do { _Pragma("unroll") for (int m = 0; m < 4; ++m) _Pragma("unroll") for (int k = 0; k < 2; ++k) dst[m][k] = *(const PG8_LAS bf16x8*)(lds + PG8_SA(b, h) + aoff + m * 2048 + k * 1024); } while (0)
; #define PG8_LDB(dst, b, h) do { _Pragma("unroll") for (int n = 0; n < 2; ++n) _Pragma("unroll") for (int k = 0; k < 2; ++k) dst[n][k] = *(const PG8_LAS bf16x8*)(lds + PG8_SB(b, h) + boff + n * 2048 + k * 1024); } while (0)
; #define PG8_MMA(ai, bj, At, Bt) do { __builtin_amdgcn_s_setprio(1); _Pragma("unroll") for (int m = 0; m < 4; ++m) _Pragma("unroll") for (int n = 0; n < 2; ++n) _Pragma("unroll") for (int k = 0; k < 2; ++k) \
;         acc[ai][bj][m][n] = __builtin_amdgcn_mfma_f32_16x16x32_bf16(Bt[n][k], At[m][k], acc[ai][bj][m][n], 0, 0, 0); __builtin_amdgcn_s_setprio(0); } while (0)
; #define PG8_WAIT_V(n) asm volatile("s_waitcnt vmcnt(" #n ")" ::: "memory")
; #define PG8_WAIT_L(n) asm volatile("s_waitcnt lgkmcnt(" #n ")" ::: "memory")
; template <class Epi, class Sched, bool ALIGN_EPI = false, bool SP2 = false>
; __device__ __forceinline__ void gemm_phase(PG8_LAS unsigned char* lds, const Gemm g, const Sched& S, const Epi& E, int tid_in) {
;     ...
;             const bool last = (t == nt - 2);
;             const char* a1 = cA + (size_t)(t + 1) * kstep;
;             const char* a2 = last ? nA : cA + (size_t)(t + 2) * kstep; const char* b2 = last ? nB : cB + (size_t)(t + 2) * kstep;
;             const char* a3 = a2 + kstep; const char* b3 = b2 + kstep;
;             if (last && has_next) S.a_ready(nxt);
;             if constexpr (SP2) {
;             PG8_LDB(B0, 0, 0); PG8_LDB(B1, 0, 1); PG8_SCHED; PG8_LDA(At, 0, 0); PG8_STAGE(PG8_SA(1, 1), a1 + hstep, voffA);
;             PG8_WAIT_V(8); PG8_WAIT_L(0); PG8_BAR; PG8_MMA(0, 0, At, B0); PG8_MMA(0, 1, At, B1); PG8_BAR; PG8_SCHED;
;             PG8_LDA(At, 0, 1); PG8_STAGE(PG8_SB(0, 0), b2, voffB); PG8_STAGE(PG8_SB(0, 1), b2 + hstep, voffB); PG8_STAGE(PG8_SA(0, 0), a2, voffA);
;             PG8_WAIT_V(8); PG8_WAIT_L(0); PG8_BAR; PG8_MMA(1, 0, At, B0); PG8_MMA(1, 1, At, B1); PG8_BAR; PG8_SCHED;
.LBB0_567:
	s_add_u32 s28, s26, 0xfff80080
	s_addc_u32 s29, s27, -1
	s_add_i32 s62, 0, 0x10000
	s_cmp_eq_u32 s66, 28
	s_cselect_b32 s31, s19, s29
	s_cselect_b32 s30, s47, s28
	v_add_u32_e32 v144, s62, v148
	s_cselect_b32 s29, s17, s65
	s_cselect_b32 s28, s52, s64
	s_add_i32 s67, 0, 0x14000
	ds_read_b128 v[140:143], v144
	ds_read_b128 v[152:155], v144 offset:1024
	ds_read_b128 v[156:159], v144 offset:2048
	ds_read_b128 v[160:163], v144 offset:3072
	v_add_u32_e32 v144, s67, v148
	ds_read_b128 v[172:175], v144
	ds_read_b128 v[176:179], v144 offset:1024
	ds_read_b128 v[180:183], v144 offset:2048
	ds_read_b128 v[184:187], v144 offset:3072
	v_lshl_add_u64 v[144:145], s[26:27], 0, v[136:137]
	s_add_i32 m0, s40, 0xc000
	ds_read_b128 v[188:191], v150
	ds_read_b128 v[192:195], v150 offset:1024
	ds_read_b128 v[196:199], v150 offset:2048
	ds_read_b128 v[204:207], v150 offset:3072
	ds_read_b128 v[208:211], v150 offset:4096
	ds_read_b128 v[212:215], v150 offset:5120
	ds_read_b128 v[216:219], v150 offset:6144
	ds_read_b128 v[220:223], v150 offset:7168
	global_load_lds_dwordx4 v[144:145], off
	v_lshl_add_u64 v[144:145], s[26:27], 0, v[138:139]
	s_add_i32 m0, s40, 0xe000
	s_nop 0
	global_load_lds_dwordx4 v[144:145], off
	s_waitcnt vmcnt(8)
	s_waitcnt lgkmcnt(0)
	s_barrier
	s_setprio 1
	s_waitcnt lgkmcnt(0)
	v_mfma_f32_16x16x32_bf16 v[126:129], v[140:143], v[188:191], v[126:129]
	v_mfma_f32_16x16x32_bf16 v[122:125], v[156:159], v[188:191], v[122:125]
	v_mfma_f32_16x16x32_bf16 v[110:113], v[140:143], v[196:199], v[110:113]
	v_mfma_f32_16x16x32_bf16 v[106:109], v[156:159], v[196:199], v[106:109]
	v_mfma_f32_16x16x32_bf16 v[92:95], v[140:143], v[208:211], v[92:95]
	v_mfma_f32_16x16x32_bf16 v[88:91], v[156:159], v[208:211], v[88:91]
	v_mfma_f32_16x16x32_bf16 v[76:79], v[140:143], v[216:219], v[76:79]
	v_mfma_f32_16x16x32_bf16 v[72:75], v[156:159], v[216:219], v[72:75]
	v_mfma_f32_16x16x32_bf16 v[126:129], v[152:155], v[192:195], v[126:129]
	v_mfma_f32_16x16x32_bf16 v[122:125], v[160:163], v[192:195], v[122:125]
	v_mfma_f32_16x16x32_bf16 v[110:113], v[152:155], v[204:207], v[110:113]
	v_mfma_f32_16x16x32_bf16 v[106:109], v[160:163], v[204:207], v[106:109]
	v_mfma_f32_16x16x32_bf16 v[92:95], v[152:155], v[212:215], v[92:95]
	v_mfma_f32_16x16x32_bf16 v[88:91], v[160:163], v[212:215], v[88:91]
	v_mfma_f32_16x16x32_bf16 v[76:79], v[152:155], v[220:223], v[76:79]
	v_mfma_f32_16x16x32_bf16 v[72:75], v[160:163], v[220:223], v[72:75]
	v_mfma_f32_16x16x32_bf16 v[118:121], v[172:175], v[188:191], v[118:121]
	v_mfma_f32_16x16x32_bf16 v[114:117], v[180:183], v[188:191], v[114:117]
	v_mfma_f32_16x16x32_bf16 v[102:105], v[172:175], v[196:199], v[102:105]
	v_mfma_f32_16x16x32_bf16 v[98:101], v[180:183], v[196:199], v[98:101]
	v_mfma_f32_16x16x32_bf16 v[84:87], v[172:175], v[208:211], v[84:87]
	v_mfma_f32_16x16x32_bf16 v[80:83], v[180:183], v[208:211], v[80:83]
	v_mfma_f32_16x16x32_bf16 v[68:71], v[172:175], v[216:219], v[68:71]
	v_mfma_f32_16x16x32_bf16 v[64:67], v[180:183], v[216:219], v[64:67]
	v_mfma_f32_16x16x32_bf16 v[118:121], v[176:179], v[192:195], v[118:121]
	v_mfma_f32_16x16x32_bf16 v[114:117], v[184:187], v[192:195], v[114:117]
	v_mfma_f32_16x16x32_bf16 v[102:105], v[176:179], v[204:207], v[102:105]
	v_mfma_f32_16x16x32_bf16 v[98:101], v[184:187], v[204:207], v[98:101]
	v_mfma_f32_16x16x32_bf16 v[84:87], v[176:179], v[212:215], v[84:87]
	v_mfma_f32_16x16x32_bf16 v[80:83], v[184:187], v[212:215], v[80:83]
	v_mfma_f32_16x16x32_bf16 v[68:71], v[176:179], v[220:223], v[68:71]
	v_mfma_f32_16x16x32_bf16 v[64:67], v[184:187], v[220:223], v[64:67]
	s_setprio 0
	s_barrier
	s_add_i32 s62, s62, s39
	v_lshl_add_u64 v[144:145], s[28:29], 0, v[96:97]
	s_mov_b32 m0, s62
	ds_read_b128 v[188:191], v150 offset:16384
	ds_read_b128 v[192:195], v150 offset:17408
	ds_read_b128 v[196:199], v150 offset:18432
	ds_read_b128 v[204:207], v150 offset:19456
	ds_read_b128 v[208:211], v150 offset:20480
	ds_read_b128 v[212:215], v150 offset:21504
	ds_read_b128 v[216:219], v150 offset:22528
	ds_read_b128 v[220:223], v150 offset:23552
	global_load_lds_dwordx4 v[144:145], off
	s_add_i32 m0, s62, 0x2000
	s_add_u32 s62, s28, 0x80000
	v_lshl_add_u64 v[164:165], s[28:29], 0, v[134:135]
	s_addc_u32 s63, s29, 0
	s_add_i32 s67, s67, s39
	global_load_lds_dwordx4 v[164:165], off
	v_lshl_add_u64 v[200:201], s[62:63], 0, v[96:97]
	s_mov_b32 m0, s67
	v_lshl_add_u64 v[224:225], s[30:31], 0, v[132:133]
	global_load_lds_dwordx4 v[200:201], off
	v_lshl_add_u64 v[200:201], s[62:63], 0, v[134:135]
	s_add_i32 m0, s67, 0x2000
	s_nop 0
	global_load_lds_dwordx4 v[200:201], off
	v_lshl_add_u64 v[200:201], s[30:31], 0, v[130:131]
	s_mov_b32 m0, s40
	s_nop 0
	global_load_lds_dwordx4 v[200:201], off
	s_mov_b32 m0, s41
	s_nop 0
	global_load_lds_dwordx4 v[224:225], off
	s_waitcnt vmcnt(8)
	s_waitcnt lgkmcnt(0)
	s_barrier
; #define PG8_STAGE(bufoff, gbase, voff) do { _Pragma("unroll") for (int _i = 0; _i < 2; ++_i) \
;         __builtin_amdgcn_global_load_lds((const unsigned*)((const char*)(gbase) + (voff)[_i]), (PG8_LAS unsigned*)(lds + (bufoff) + ldsw + _i * 8192), 16, 0, 0); } while (0)
; #define PG8_LDA(dst, b, h) do { _Pragma("unroll") for (int m = 0; m < 4; ++m) _Pragma("unroll") for (int k = 0; k < 2; ++k) dst[m][k] = *(const PG8_LAS bf16x8*)(lds + PG8_SA(b, h) + aoff + m * 2048 + k * 1024); } while (0)
; #define PG8_LDB(dst, b, h) do { _Pragma("unroll") for (int n = 0; n < 2; ++n) _Pragma("unroll") for (int k = 0; k < 2; ++k) dst[n][k] = *(const PG8_LAS bf16x8*)(lds + PG8_SB(b, h) + boff + n * 2048 + k * 1024); } while (0)
; #define PG8_MMA(ai, bj, At, Bt) do { __builtin_amdgcn_s_setprio(1); _Pragma("unroll") for (int m = 0; m < 4; ++m) _Pragma("unroll") for (int n = 0; n < 2; ++n) _Pragma("unroll") for (int k = 0; k < 2; ++k) \
;         acc[ai][bj][m][n] = __builtin_amdgcn_mfma_f32_16x16x32_bf16(Bt[n][k], At[m][k], acc[ai][bj][m][n], 0, 0, 0); __builtin_amdgcn_s_setprio(0); } while (0)
; #define PG8_WAIT_V(n) asm volatile("s_waitcnt vmcnt(" #n ")" ::: "memory")
; #define PG8_WAIT_L(n) asm volatile("s_waitcnt lgkmcnt(" #n ")" ::: "memory")
; #define PG8_BAR __builtin_amdgcn_s_barrier()
; #define PG8_SCHED __builtin_amdgcn_sched_barrier(0)
; template <class Epi, class Sched, bool ALIGN_EPI = false, bool SP2 = false>
; __device__ __forceinline__ void gemm_phase(PG8_LAS unsigned char* lds, const Gemm g, const Sched& S, const Epi& E, int tid_in) {
;     ...
;             PG8_WAIT_V(8); PG8_WAIT_L(0); PG8_BAR; PG8_MMA(1, 0, At, B0); PG8_MMA(1, 1, At, B1); PG8_BAR; PG8_SCHED;
;             PG8_LDB(B0, 1, 0); PG8_LDB(B1, 1, 1); PG8_SCHED; PG8_LDA(At, 1, 0); PG8_STAGE(PG8_SA(0, 1), a2 + hstep, voffA);
;             PG8_WAIT_V(8); PG8_WAIT_L(0); PG8_BAR; PG8_MMA(0, 0, At, B0); PG8_MMA(0, 1, At, B1); PG8_BAR; PG8_SCHED;
	s_setprio 1
	s_waitcnt lgkmcnt(0)
	v_mfma_f32_16x16x32_bf16 v[60:63], v[140:143], v[188:191], v[60:63]
	v_mfma_f32_16x16x32_bf16 v[56:59], v[156:159], v[188:191], v[56:59]
	v_mfma_f32_16x16x32_bf16 v[44:47], v[140:143], v[196:199], v[44:47]
	v_mfma_f32_16x16x32_bf16 v[40:43], v[156:159], v[196:199], v[40:43]
	v_mfma_f32_16x16x32_bf16 v[28:31], v[140:143], v[208:211], v[28:31]
	v_mfma_f32_16x16x32_bf16 v[24:27], v[156:159], v[208:211], v[24:27]
	v_mfma_f32_16x16x32_bf16 v[12:15], v[140:143], v[216:219], v[12:15]
	v_mfma_f32_16x16x32_bf16 v[8:11], v[156:159], v[216:219], v[8:11]
	v_mfma_f32_16x16x32_bf16 v[60:63], v[152:155], v[192:195], v[60:63]
	v_mfma_f32_16x16x32_bf16 v[56:59], v[160:163], v[192:195], v[56:59]
	v_mfma_f32_16x16x32_bf16 v[44:47], v[152:155], v[204:207], v[44:47]
	v_mfma_f32_16x16x32_bf16 v[40:43], v[160:163], v[204:207], v[40:43]
	v_mfma_f32_16x16x32_bf16 v[28:31], v[152:155], v[212:215], v[28:31]
	v_mfma_f32_16x16x32_bf16 v[24:27], v[160:163], v[212:215], v[24:27]
	v_mfma_f32_16x16x32_bf16 v[12:15], v[152:155], v[220:223], v[12:15]
	v_mfma_f32_16x16x32_bf16 v[8:11], v[160:163], v[220:223], v[8:11]
	v_mfma_f32_16x16x32_bf16 v[52:55], v[172:175], v[188:191], v[52:55]
	v_mfma_f32_16x16x32_bf16 v[48:51], v[180:183], v[188:191], v[48:51]
	v_mfma_f32_16x16x32_bf16 v[36:39], v[172:175], v[196:199], v[36:39]
	v_mfma_f32_16x16x32_bf16 v[32:35], v[180:183], v[196:199], v[32:35]
	v_mfma_f32_16x16x32_bf16 v[20:23], v[172:175], v[208:211], v[20:23]
	v_mfma_f32_16x16x32_bf16 v[16:19], v[180:183], v[208:211], v[16:19]
	v_mfma_f32_16x16x32_bf16 v[4:7], v[172:175], v[216:219], v[4:7]
	v_mfma_f32_16x16x32_bf16 v[0:3], v[180:183], v[216:219], v[0:3]
	v_mfma_f32_16x16x32_bf16 v[52:55], v[176:179], v[192:195], v[52:55]
	v_mfma_f32_16x16x32_bf16 v[48:51], v[184:187], v[192:195], v[48:51]
	v_mfma_f32_16x16x32_bf16 v[36:39], v[176:179], v[204:207], v[36:39]
	v_mfma_f32_16x16x32_bf16 v[32:35], v[184:187], v[204:207], v[32:35]
	v_mfma_f32_16x16x32_bf16 v[20:23], v[176:179], v[212:215], v[20:23]
	v_mfma_f32_16x16x32_bf16 v[16:19], v[184:187], v[212:215], v[16:19]
	v_mfma_f32_16x16x32_bf16 v[4:7], v[176:179], v[220:223], v[4:7]
	v_mfma_f32_16x16x32_bf16 v[0:3], v[184:187], v[220:223], v[0:3]
	s_setprio 0
	s_barrier
	s_add_i32 s62, 0, 0x18000
	v_add_u32_e32 v151, s62, v148
	s_add_i32 s63, 0, 0x1c000
	ds_read_b128 v[140:143], v151
	ds_read_b128 v[152:155], v151 offset:1024
	ds_read_b128 v[156:159], v151 offset:2048
	ds_read_b128 v[160:163], v151 offset:3072
	v_add_u32_e32 v151, s63, v148
	ds_read_b128 v[172:175], v151
	ds_read_b128 v[176:179], v151 offset:1024
	ds_read_b128 v[180:183], v151 offset:2048
	ds_read_b128 v[184:187], v151 offset:3072
	s_add_u32 s30, s30, 0x80000
	s_addc_u32 s31, s31, 0
	s_mov_b32 m0, s42
	v_lshl_add_u64 v[226:227], s[30:31], 0, v[130:131]
	ds_read_b128 v[188:191], v150 offset:32768
	ds_read_b128 v[192:195], v150 offset:33792
	ds_read_b128 v[196:199], v150 offset:34816
	ds_read_b128 v[204:207], v150 offset:35840
	ds_read_b128 v[208:211], v150 offset:36864
	ds_read_b128 v[212:215], v150 offset:37888
	ds_read_b128 v[216:219], v150 offset:38912
	ds_read_b128 v[220:223], v150 offset:39936
	global_load_lds_dwordx4 v[226:227], off
	v_lshl_add_u64 v[226:227], s[30:31], 0, v[132:133]
	s_mov_b32 m0, s43
	s_nop 0
	global_load_lds_dwordx4 v[226:227], off
	s_waitcnt vmcnt(8)
	s_waitcnt lgkmcnt(0)
	s_barrier
	s_setprio 1
	s_waitcnt lgkmcnt(0)
	v_mfma_f32_16x16x32_bf16 v[126:129], v[140:143], v[188:191], v[126:129]
	v_mfma_f32_16x16x32_bf16 v[122:125], v[156:159], v[188:191], v[122:125]
	v_mfma_f32_16x16x32_bf16 v[110:113], v[140:143], v[196:199], v[110:113]
	v_mfma_f32_16x16x32_bf16 v[106:109], v[156:159], v[196:199], v[106:109]
	v_mfma_f32_16x16x32_bf16 v[92:95], v[140:143], v[208:211], v[92:95]
	v_mfma_f32_16x16x32_bf16 v[88:91], v[156:159], v[208:211], v[88:91]
	v_mfma_f32_16x16x32_bf16 v[76:79], v[140:143], v[216:219], v[76:79]
	v_mfma_f32_16x16x32_bf16 v[72:75], v[156:159], v[216:219], v[72:75]
	v_mfma_f32_16x16x32_bf16 v[126:129], v[152:155], v[192:195], v[126:129]
	v_mfma_f32_16x16x32_bf16 v[122:125], v[160:163], v[192:195], v[122:125]
	v_mfma_f32_16x16x32_bf16 v[110:113], v[152:155], v[204:207], v[110:113]
	v_mfma_f32_16x16x32_bf16 v[106:109], v[160:163], v[204:207], v[106:109]
	v_mfma_f32_16x16x32_bf16 v[92:95], v[152:155], v[212:215], v[92:95]
	v_mfma_f32_16x16x32_bf16 v[88:91], v[160:163], v[212:215], v[88:91]
	v_mfma_f32_16x16x32_bf16 v[76:79], v[152:155], v[220:223], v[76:79]
	v_mfma_f32_16x16x32_bf16 v[72:75], v[160:163], v[220:223], v[72:75]
	v_mfma_f32_16x16x32_bf16 v[118:121], v[172:175], v[188:191], v[118:121]
	v_mfma_f32_16x16x32_bf16 v[114:117], v[180:183], v[188:191], v[114:117]
	v_mfma_f32_16x16x32_bf16 v[102:105], v[172:175], v[196:199], v[102:105]
	v_mfma_f32_16x16x32_bf16 v[98:101], v[180:183], v[196:199], v[98:101]
	v_mfma_f32_16x16x32_bf16 v[84:87], v[172:175], v[208:211], v[84:87]
	v_mfma_f32_16x16x32_bf16 v[80:83], v[180:183], v[208:211], v[80:83]
	v_mfma_f32_16x16x32_bf16 v[68:71], v[172:175], v[216:219], v[68:71]
	v_mfma_f32_16x16x32_bf16 v[64:67], v[180:183], v[216:219], v[64:67]
	v_mfma_f32_16x16x32_bf16 v[118:121], v[176:179], v[192:195], v[118:121]
	v_mfma_f32_16x16x32_bf16 v[114:117], v[184:187], v[192:195], v[114:117]
	v_mfma_f32_16x16x32_bf16 v[102:105], v[176:179], v[204:207], v[102:105]
	v_mfma_f32_16x16x32_bf16 v[98:101], v[184:187], v[204:207], v[98:101]
	v_mfma_f32_16x16x32_bf16 v[84:87], v[176:179], v[212:215], v[84:87]
	v_mfma_f32_16x16x32_bf16 v[80:83], v[184:187], v[212:215], v[80:83]
	v_mfma_f32_16x16x32_bf16 v[68:71], v[176:179], v[220:223], v[68:71]
	v_mfma_f32_16x16x32_bf16 v[64:67], v[184:187], v[220:223], v[64:67]
	s_setprio 0
	s_barrier
; #define PG8_STAGE(bufoff, gbase, voff) do { _Pragma("unroll") for (int _i = 0; _i < 2; ++_i) \
;         __builtin_amdgcn_global_load_lds((const unsigned*)((const char*)(gbase) + (voff)[_i]), (PG8_LAS unsigned*)(lds + (bufoff) + ldsw + _i * 8192), 16, 0, 0); } while (0)
; #define PG8_LDA(dst, b, h) do { _Pragma("unroll") for (int m = 0; m < 4; ++m) _Pragma("unroll") for (int k = 0; k < 2; ++k) dst[m][k] = *(const PG8_LAS bf16x8*)(lds + PG8_SA(b, h) + aoff + m * 2048 + k * 1024); } while (0)
; #define PG8_MMA(ai, bj, At, Bt) do { __builtin_amdgcn_s_setprio(1); _Pragma("unroll") for (int m = 0; m < 4; ++m) _Pragma("unroll") for (int n = 0; n < 2; ++n) _Pragma("unroll") for (int k = 0; k < 2; ++k) \
;         acc[ai][bj][m][n] = __builtin_amdgcn_mfma_f32_16x16x32_bf16(Bt[n][k], At[m][k], acc[ai][bj][m][n], 0, 0, 0); __builtin_amdgcn_s_setprio(0); } while (0)
; #define PG8_WAIT_V(n) asm volatile("s_waitcnt vmcnt(" #n ")" ::: "memory")
; #define PG8_WAIT_L(n) asm volatile("s_waitcnt lgkmcnt(" #n ")" ::: "memory")
; #define PG8_BAR __builtin_amdgcn_s_barrier()
; #define PG8_SCHED __builtin_amdgcn_sched_barrier(0)
; template <class Epi, class Sched, bool ALIGN_EPI = false, bool SP2 = false>
; __device__ __forceinline__ void gemm_phase(PG8_LAS unsigned char* lds, const Gemm g, const Sched& S, const Epi& E, int tid_in) {
;     ...
;             PG8_LDA(At, 1, 1); PG8_STAGE(PG8_SB(1, 0), b3, voffB); PG8_STAGE(PG8_SB(1, 1), b3 + hstep, voffB); PG8_STAGE(PG8_SA(1, 0), a3, voffA);
;             PG8_WAIT_V(8); PG8_WAIT_L(0); PG8_BAR; PG8_MMA(1, 0, At, B0); PG8_MMA(1, 1, At, B1); PG8_BAR; PG8_SCHED;
;     ...
;         if constexpr (ALIGN_EPI) { if (wr == 0) PG8_BAR; }
	s_add_i32 s30, s62, s39
	v_lshl_add_u64 v[144:145], v[144:145], 0, s[88:89]
	s_mov_b32 m0, s30
	ds_read_b128 v[188:191], v150 offset:49152
	ds_read_b128 v[192:195], v150 offset:50176
	ds_read_b128 v[196:199], v150 offset:51200
	ds_read_b128 v[204:207], v150 offset:52224
	ds_read_b128 v[208:211], v150 offset:53248
	ds_read_b128 v[212:215], v150 offset:54272
	ds_read_b128 v[216:219], v150 offset:55296
	ds_read_b128 v[220:223], v150 offset:56320
	global_load_lds_dwordx4 v[144:145], off
	s_add_i32 m0, s30, 0x2000
	s_add_u32 s28, s28, 0x80080
	v_lshl_add_u64 v[144:145], v[164:165], 0, s[88:89]
	s_addc_u32 s29, s29, 0
	s_add_i32 s30, s63, s39
	global_load_lds_dwordx4 v[144:145], off
	v_lshl_add_u64 v[144:145], s[28:29], 0, v[96:97]
	s_mov_b32 m0, s30
	s_nop 0
	global_load_lds_dwordx4 v[144:145], off
	v_lshl_add_u64 v[144:145], s[28:29], 0, v[134:135]
	s_add_i32 m0, s30, 0x2000
	s_nop 0
	global_load_lds_dwordx4 v[144:145], off
	v_lshl_add_u64 v[144:145], v[200:201], 0, s[88:89]
	s_mov_b32 m0, s44
	s_nop 0
	global_load_lds_dwordx4 v[144:145], off
	v_lshl_add_u64 v[144:145], v[224:225], 0, s[88:89]
	s_mov_b32 m0, s45
	s_nop 0
	global_load_lds_dwordx4 v[144:145], off
	s_waitcnt vmcnt(8)
	s_waitcnt lgkmcnt(0)
	s_barrier
	s_setprio 1
	s_waitcnt lgkmcnt(0)
	v_mfma_f32_16x16x32_bf16 v[60:63], v[140:143], v[188:191], v[60:63]
	v_mfma_f32_16x16x32_bf16 v[56:59], v[156:159], v[188:191], v[56:59]
	v_mfma_f32_16x16x32_bf16 v[44:47], v[140:143], v[196:199], v[44:47]
	v_mfma_f32_16x16x32_bf16 v[40:43], v[156:159], v[196:199], v[40:43]
	v_mfma_f32_16x16x32_bf16 v[28:31], v[140:143], v[208:211], v[28:31]
	v_mfma_f32_16x16x32_bf16 v[24:27], v[156:159], v[208:211], v[24:27]
	v_mfma_f32_16x16x32_bf16 v[12:15], v[140:143], v[216:219], v[12:15]
	v_mfma_f32_16x16x32_bf16 v[8:11], v[156:159], v[216:219], v[8:11]
	v_mfma_f32_16x16x32_bf16 v[60:63], v[152:155], v[192:195], v[60:63]
	v_mfma_f32_16x16x32_bf16 v[56:59], v[160:163], v[192:195], v[56:59]
	v_mfma_f32_16x16x32_bf16 v[44:47], v[152:155], v[204:207], v[44:47]
	v_mfma_f32_16x16x32_bf16 v[40:43], v[160:163], v[204:207], v[40:43]
	v_mfma_f32_16x16x32_bf16 v[28:31], v[152:155], v[212:215], v[28:31]
	v_mfma_f32_16x16x32_bf16 v[24:27], v[160:163], v[212:215], v[24:27]
	v_mfma_f32_16x16x32_bf16 v[12:15], v[152:155], v[220:223], v[12:15]
	v_mfma_f32_16x16x32_bf16 v[8:11], v[160:163], v[220:223], v[8:11]
	v_mfma_f32_16x16x32_bf16 v[52:55], v[172:175], v[188:191], v[52:55]
	v_mfma_f32_16x16x32_bf16 v[48:51], v[180:183], v[188:191], v[48:51]
	v_mfma_f32_16x16x32_bf16 v[36:39], v[172:175], v[196:199], v[36:39]
	v_mfma_f32_16x16x32_bf16 v[32:35], v[180:183], v[196:199], v[32:35]
	v_mfma_f32_16x16x32_bf16 v[20:23], v[172:175], v[208:211], v[20:23]
	v_mfma_f32_16x16x32_bf16 v[16:19], v[180:183], v[208:211], v[16:19]
	v_mfma_f32_16x16x32_bf16 v[4:7], v[172:175], v[216:219], v[4:7]
	v_mfma_f32_16x16x32_bf16 v[0:3], v[180:183], v[216:219], v[0:3]
	v_mfma_f32_16x16x32_bf16 v[52:55], v[176:179], v[192:195], v[52:55]
	v_mfma_f32_16x16x32_bf16 v[48:51], v[184:187], v[192:195], v[48:51]
	v_mfma_f32_16x16x32_bf16 v[36:39], v[176:179], v[204:207], v[36:39]
	v_mfma_f32_16x16x32_bf16 v[32:35], v[184:187], v[204:207], v[32:35]
	v_mfma_f32_16x16x32_bf16 v[20:23], v[176:179], v[212:215], v[20:23]
	v_mfma_f32_16x16x32_bf16 v[16:19], v[184:187], v[212:215], v[16:19]
	v_mfma_f32_16x16x32_bf16 v[4:7], v[176:179], v[220:223], v[4:7]
	v_mfma_f32_16x16x32_bf16 v[0:3], v[184:187], v[220:223], v[0:3]
	s_setprio 0
	s_barrier
	s_add_i32 s66, s66, 2
	s_add_u32 s26, s26, 0x100
	s_addc_u32 s27, s27, 0
	s_add_u32 s64, s64, 0x100
	s_addc_u32 s65, s65, 0
	s_cmp_gt_u32 s66, 29
	s_cbranch_scc0 .LBB0_567
	s_and_b64 vcc, exec, s[14:15]
	s_cbranch_vccz .LBB0_570
	s_barrier

; #define PG8_STAGE(bufoff, gbase, voff) do { _Pragma("unroll") for (int _i = 0; _i < 2; ++_i) \
;         __builtin_amdgcn_global_load_lds((const unsigned*)((const char*)(gbase) + (voff)[_i]), (PG8_LAS unsigned*)(lds + (bufoff) + ldsw + _i * 8192), 16, 0, 0); } while (0)
; #define PG8_LDA(dst, b, h) do { _Pragma("unroll") for (int m = 0; m < 4; ++m) _Pragma("unroll") for (int k = 0; k < 2; ++k) dst[m][k] = *(const PG8_LAS bf16x8*)(lds + PG8_SA(b, h) + aoff + m * 2048 + k * 1024); } while (0)
; #define PG8_LDB(dst, b, h) do { _Pragma("unroll") for (int n = 0; n < 2; ++n) _Pragma("unroll") for (int k = 0; k < 2; ++k) dst[n][k] = *(const PG8_LAS bf16x8*)(lds + PG8_SB(b, h) + boff + n * 2048 + k * 1024); } while (0)
; #define PG8_MMA(ai, bj, At, Bt) do { __builtin_amdgcn_s_setprio(1); _Pragma("unroll") for (int m = 0; m < 4; ++m) _Pragma("unroll") for (int n = 0; n < 2; ++n) _Pragma("unroll") for (int k = 0; k < 2; ++k) \
;         acc[ai][bj][m][n] = __builtin_amdgcn_mfma_f32_16x16x32_bf16(Bt[n][k], At[m][k], acc[ai][bj][m][n], 0, 0, 0); __builtin_amdgcn_s_setprio(0); } while (0)
; #define PG8_WAIT_V(n) asm volatile("s_waitcnt vmcnt(" #n ")" ::: "memory")
; #define PG8_WAIT_L(n) asm volatile("s_waitcnt lgkmcnt(" #n ")" ::: "memory")
; template <class Epi, class Sched, bool ALIGN_EPI = false, bool SP2 = false>
; __device__ __forceinline__ void gemm_phase(PG8_LAS unsigned char* lds, const Gemm g, const Sched& S, const Epi& E, int tid_in) {
;     ...
;             const bool last = (t == nt - 2);
;             const char* a1 = cA + (size_t)(t + 1) * kstep;
;             const char* a2 = last ? nA : cA + (size_t)(t + 2) * kstep; const char* b2 = last ? nB : cB + (size_t)(t + 2) * kstep;
;             const char* a3 = a2 + kstep; const char* b3 = b2 + kstep;
;             if (last && has_next) S.a_ready(nxt);
;             if constexpr (SP2) {
;             PG8_LDB(B0, 0, 0); PG8_LDB(B1, 0, 1); PG8_SCHED; PG8_LDA(At, 0, 0); PG8_STAGE(PG8_SA(1, 1), a1 + hstep, voffA);
;             PG8_WAIT_V(8); PG8_WAIT_L(0); PG8_BAR; PG8_MMA(0, 0, At, B0); PG8_MMA(0, 1, At, B1); PG8_BAR; PG8_SCHED;
;             PG8_LDA(At, 0, 1); PG8_STAGE(PG8_SB(0, 0), b2, voffB); PG8_STAGE(PG8_SB(0, 1), b2 + hstep, voffB); PG8_STAGE(PG8_SA(0, 0), a2, voffA);
;             PG8_WAIT_V(8); PG8_WAIT_L(0); PG8_BAR; PG8_MMA(1, 0, At, B0); PG8_MMA(1, 1, At, B1); PG8_BAR; PG8_SCHED;
.LBB0_632:
	s_add_u32 s30, s28, 0xfff80080
	s_addc_u32 s31, s29, -1
	s_add_i32 s62, 0, 0x10000
	s_cmp_eq_u32 s72, 28
	s_cselect_b32 s35, s21, s31
	s_cselect_b32 s34, s67, s30
	v_add_u32_e32 v148, s62, v133
	s_cselect_b32 s31, s19, s71
	s_cselect_b32 s30, s69, s70
	s_add_i32 s73, 0, 0x14000
	ds_read_b128 v[144:147], v148
	ds_read_b128 v[158:161], v148 offset:1024
	ds_read_b128 v[162:165], v148 offset:2048
	ds_read_b128 v[172:175], v148 offset:3072
	v_add_u32_e32 v148, s73, v133
	ds_read_b128 v[176:179], v148
	ds_read_b128 v[180:183], v148 offset:1024
	ds_read_b128 v[184:187], v148 offset:2048
	ds_read_b128 v[188:191], v148 offset:3072
	v_lshl_add_u64 v[148:149], s[28:29], 0, v[140:141]
	s_add_i32 m0, s45, 0xc000
	ds_read_b128 v[192:195], v156
	ds_read_b128 v[196:199], v156 offset:1024
	ds_read_b128 v[204:207], v156 offset:2048
	ds_read_b128 v[208:211], v156 offset:3072
	ds_read_b128 v[212:215], v156 offset:4096
	ds_read_b128 v[216:219], v156 offset:5120
	ds_read_b128 v[220:223], v156 offset:6144
	ds_read_b128 v[224:227], v156 offset:7168
	global_load_lds_dwordx4 v[148:149], off
	v_lshl_add_u64 v[148:149], s[28:29], 0, v[142:143]
	s_add_i32 m0, s45, 0xe000
	s_nop 0
	global_load_lds_dwordx4 v[148:149], off
	s_waitcnt vmcnt(8)
	s_waitcnt lgkmcnt(0)
	s_barrier
	s_setprio 1
	s_waitcnt lgkmcnt(0)
	v_mfma_f32_16x16x32_bf16 v[126:129], v[144:147], v[192:195], v[126:129]
	v_mfma_f32_16x16x32_bf16 v[122:125], v[162:165], v[192:195], v[122:125]
	v_mfma_f32_16x16x32_bf16 v[110:113], v[144:147], v[204:207], v[110:113]
	v_mfma_f32_16x16x32_bf16 v[106:109], v[162:165], v[204:207], v[106:109]
	v_mfma_f32_16x16x32_bf16 v[92:95], v[144:147], v[212:215], v[92:95]
	v_mfma_f32_16x16x32_bf16 v[88:91], v[162:165], v[212:215], v[88:91]
	v_mfma_f32_16x16x32_bf16 v[76:79], v[144:147], v[220:223], v[76:79]
	v_mfma_f32_16x16x32_bf16 v[72:75], v[162:165], v[220:223], v[72:75]
	v_mfma_f32_16x16x32_bf16 v[126:129], v[158:161], v[196:199], v[126:129]
	v_mfma_f32_16x16x32_bf16 v[122:125], v[172:175], v[196:199], v[122:125]
	v_mfma_f32_16x16x32_bf16 v[110:113], v[158:161], v[208:211], v[110:113]
	v_mfma_f32_16x16x32_bf16 v[106:109], v[172:175], v[208:211], v[106:109]
	v_mfma_f32_16x16x32_bf16 v[92:95], v[158:161], v[216:219], v[92:95]
	v_mfma_f32_16x16x32_bf16 v[88:91], v[172:175], v[216:219], v[88:91]
	v_mfma_f32_16x16x32_bf16 v[76:79], v[158:161], v[224:227], v[76:79]
	v_mfma_f32_16x16x32_bf16 v[72:75], v[172:175], v[224:227], v[72:75]
	v_mfma_f32_16x16x32_bf16 v[118:121], v[176:179], v[192:195], v[118:121]
	v_mfma_f32_16x16x32_bf16 v[114:117], v[184:187], v[192:195], v[114:117]
	v_mfma_f32_16x16x32_bf16 v[102:105], v[176:179], v[204:207], v[102:105]
	v_mfma_f32_16x16x32_bf16 v[98:101], v[184:187], v[204:207], v[98:101]
	v_mfma_f32_16x16x32_bf16 v[84:87], v[176:179], v[212:215], v[84:87]
	v_mfma_f32_16x16x32_bf16 v[80:83], v[184:187], v[212:215], v[80:83]
	v_mfma_f32_16x16x32_bf16 v[68:71], v[176:179], v[220:223], v[68:71]
	v_mfma_f32_16x16x32_bf16 v[64:67], v[184:187], v[220:223], v[64:67]
	v_mfma_f32_16x16x32_bf16 v[118:121], v[180:183], v[196:199], v[118:121]
	v_mfma_f32_16x16x32_bf16 v[114:117], v[188:191], v[196:199], v[114:117]
	v_mfma_f32_16x16x32_bf16 v[102:105], v[180:183], v[208:211], v[102:105]
	v_mfma_f32_16x16x32_bf16 v[98:101], v[188:191], v[208:211], v[98:101]
	v_mfma_f32_16x16x32_bf16 v[84:87], v[180:183], v[216:219], v[84:87]
	v_mfma_f32_16x16x32_bf16 v[80:83], v[188:191], v[216:219], v[80:83]
	v_mfma_f32_16x16x32_bf16 v[68:71], v[180:183], v[224:227], v[68:71]
	v_mfma_f32_16x16x32_bf16 v[64:67], v[188:191], v[224:227], v[64:67]
	s_setprio 0
	s_barrier
	s_add_i32 s62, s62, s44
	v_lshl_add_u64 v[148:149], s[30:31], 0, v[96:97]
	s_mov_b32 m0, s62
	ds_read_b128 v[192:195], v156 offset:16384
	ds_read_b128 v[196:199], v156 offset:17408
	ds_read_b128 v[204:207], v156 offset:18432
	ds_read_b128 v[208:211], v156 offset:19456
	ds_read_b128 v[212:215], v156 offset:20480
	ds_read_b128 v[216:219], v156 offset:21504
	ds_read_b128 v[220:223], v156 offset:22528
	ds_read_b128 v[224:227], v156 offset:23552
	global_load_lds_dwordx4 v[148:149], off
	s_add_i32 m0, s62, 0x2000
	s_add_u32 s62, s30, 0x80000
	v_lshl_add_u64 v[200:201], s[30:31], 0, v[138:139]
	s_addc_u32 s63, s31, 0
	s_add_i32 s73, s73, s44
	global_load_lds_dwordx4 v[200:201], off
	v_lshl_add_u64 v[228:229], s[62:63], 0, v[96:97]
	s_mov_b32 m0, s73
	v_lshl_add_u64 v[230:231], s[34:35], 0, v[136:137]
	global_load_lds_dwordx4 v[228:229], off
	v_lshl_add_u64 v[228:229], s[62:63], 0, v[138:139]
	s_add_i32 m0, s73, 0x2000
	s_nop 0
	global_load_lds_dwordx4 v[228:229], off
	v_lshl_add_u64 v[228:229], s[34:35], 0, v[134:135]
	s_mov_b32 m0, s45
	s_nop 0
	global_load_lds_dwordx4 v[228:229], off
	s_mov_b32 m0, s46
	s_nop 0
	global_load_lds_dwordx4 v[230:231], off
	s_waitcnt vmcnt(8)
	s_waitcnt lgkmcnt(0)
	s_barrier
; #define PG8_STAGE(bufoff, gbase, voff) do { _Pragma("unroll") for (int _i = 0; _i < 2; ++_i) \
;         __builtin_amdgcn_global_load_lds((const unsigned*)((const char*)(gbase) + (voff)[_i]), (PG8_LAS unsigned*)(lds + (bufoff) + ldsw + _i * 8192), 16, 0, 0); } while (0)
; #define PG8_LDA(dst, b, h) do { _Pragma("unroll") for (int m = 0; m < 4; ++m) _Pragma("unroll") for (int k = 0; k < 2; ++k) dst[m][k] = *(const PG8_LAS bf16x8*)(lds + PG8_SA(b, h) + aoff + m * 2048 + k * 1024); } while (0)
; #define PG8_LDB(dst, b, h) do { _Pragma("unroll") for (int n = 0; n < 2; ++n) _Pragma("unroll") for (int k = 0; k < 2; ++k) dst[n][k] = *(const PG8_LAS bf16x8*)(lds + PG8_SB(b, h) + boff + n * 2048 + k * 1024); } while (0)
; #define PG8_MMA(ai, bj, At, Bt) do { __builtin_amdgcn_s_setprio(1); _Pragma("unroll") for (int m = 0; m < 4; ++m) _Pragma("unroll") for (int n = 0; n < 2; ++n) _Pragma("unroll") for (int k = 0; k < 2; ++k) \
;         acc[ai][bj][m][n] = __builtin_amdgcn_mfma_f32_16x16x32_bf16(Bt[n][k], At[m][k], acc[ai][bj][m][n], 0, 0, 0); __builtin_amdgcn_s_setprio(0); } while (0)
; #define PG8_WAIT_V(n) asm volatile("s_waitcnt vmcnt(" #n ")" ::: "memory")
; #define PG8_WAIT_L(n) asm volatile("s_waitcnt lgkmcnt(" #n ")" ::: "memory")
; #define PG8_BAR __builtin_amdgcn_s_barrier()
; #define PG8_SCHED __builtin_amdgcn_sched_barrier(0)
; template <class Epi, class Sched, bool ALIGN_EPI = false, bool SP2 = false>
; __device__ __forceinline__ void gemm_phase(PG8_LAS unsigned char* lds, const Gemm g, const Sched& S, const Epi& E, int tid_in) {
;     ...
;             PG8_WAIT_V(8); PG8_WAIT_L(0); PG8_BAR; PG8_MMA(1, 0, At, B0); PG8_MMA(1, 1, At, B1); PG8_BAR; PG8_SCHED;
;             PG8_LDB(B0, 1, 0); PG8_LDB(B1, 1, 1); PG8_SCHED; PG8_LDA(At, 1, 0); PG8_STAGE(PG8_SA(0, 1), a2 + hstep, voffA);
;             PG8_WAIT_V(8); PG8_WAIT_L(0); PG8_BAR; PG8_MMA(0, 0, At, B0); PG8_MMA(0, 1, At, B1); PG8_BAR; PG8_SCHED;
	s_setprio 1
	s_waitcnt lgkmcnt(0)
	v_mfma_f32_16x16x32_bf16 v[60:63], v[144:147], v[192:195], v[60:63]
	v_mfma_f32_16x16x32_bf16 v[56:59], v[162:165], v[192:195], v[56:59]
	v_mfma_f32_16x16x32_bf16 v[44:47], v[144:147], v[204:207], v[44:47]
	v_mfma_f32_16x16x32_bf16 v[40:43], v[162:165], v[204:207], v[40:43]
	v_mfma_f32_16x16x32_bf16 v[28:31], v[144:147], v[212:215], v[28:31]
	v_mfma_f32_16x16x32_bf16 v[24:27], v[162:165], v[212:215], v[24:27]
	v_mfma_f32_16x16x32_bf16 v[12:15], v[144:147], v[220:223], v[12:15]
	v_mfma_f32_16x16x32_bf16 v[8:11], v[162:165], v[220:223], v[8:11]
	v_mfma_f32_16x16x32_bf16 v[60:63], v[158:161], v[196:199], v[60:63]
	v_mfma_f32_16x16x32_bf16 v[56:59], v[172:175], v[196:199], v[56:59]
	v_mfma_f32_16x16x32_bf16 v[44:47], v[158:161], v[208:211], v[44:47]
	v_mfma_f32_16x16x32_bf16 v[40:43], v[172:175], v[208:211], v[40:43]
	v_mfma_f32_16x16x32_bf16 v[28:31], v[158:161], v[216:219], v[28:31]
	v_mfma_f32_16x16x32_bf16 v[24:27], v[172:175], v[216:219], v[24:27]
	v_mfma_f32_16x16x32_bf16 v[12:15], v[158:161], v[224:227], v[12:15]
	v_mfma_f32_16x16x32_bf16 v[8:11], v[172:175], v[224:227], v[8:11]
	v_mfma_f32_16x16x32_bf16 v[52:55], v[176:179], v[192:195], v[52:55]
	v_mfma_f32_16x16x32_bf16 v[48:51], v[184:187], v[192:195], v[48:51]
	v_mfma_f32_16x16x32_bf16 v[36:39], v[176:179], v[204:207], v[36:39]
	v_mfma_f32_16x16x32_bf16 v[32:35], v[184:187], v[204:207], v[32:35]
	v_mfma_f32_16x16x32_bf16 v[20:23], v[176:179], v[212:215], v[20:23]
	v_mfma_f32_16x16x32_bf16 v[16:19], v[184:187], v[212:215], v[16:19]
	v_mfma_f32_16x16x32_bf16 v[4:7], v[176:179], v[220:223], v[4:7]
	v_mfma_f32_16x16x32_bf16 v[0:3], v[184:187], v[220:223], v[0:3]
	v_mfma_f32_16x16x32_bf16 v[52:55], v[180:183], v[196:199], v[52:55]
	v_mfma_f32_16x16x32_bf16 v[48:51], v[188:191], v[196:199], v[48:51]
	v_mfma_f32_16x16x32_bf16 v[36:39], v[180:183], v[208:211], v[36:39]
	v_mfma_f32_16x16x32_bf16 v[32:35], v[188:191], v[208:211], v[32:35]
	v_mfma_f32_16x16x32_bf16 v[20:23], v[180:183], v[216:219], v[20:23]
	v_mfma_f32_16x16x32_bf16 v[16:19], v[188:191], v[216:219], v[16:19]
	v_mfma_f32_16x16x32_bf16 v[4:7], v[180:183], v[224:227], v[4:7]
	v_mfma_f32_16x16x32_bf16 v[0:3], v[188:191], v[224:227], v[0:3]
	s_setprio 0
	s_barrier
	s_add_i32 s62, 0, 0x18000
	v_add_u32_e32 v157, s62, v133
	s_add_i32 s63, 0, 0x1c000
	ds_read_b128 v[144:147], v157
	ds_read_b128 v[158:161], v157 offset:1024
	ds_read_b128 v[162:165], v157 offset:2048
	ds_read_b128 v[172:175], v157 offset:3072
	v_add_u32_e32 v157, s63, v133
	ds_read_b128 v[176:179], v157
	ds_read_b128 v[180:183], v157 offset:1024
	ds_read_b128 v[184:187], v157 offset:2048
	ds_read_b128 v[188:191], v157 offset:3072
	s_add_u32 s34, s34, 0x80000
	s_addc_u32 s35, s35, 0
	s_mov_b32 m0, s47
	v_lshl_add_u64 v[232:233], s[34:35], 0, v[134:135]
	ds_read_b128 v[192:195], v156 offset:32768
	ds_read_b128 v[196:199], v156 offset:33792
	ds_read_b128 v[204:207], v156 offset:34816
	ds_read_b128 v[208:211], v156 offset:35840
	ds_read_b128 v[212:215], v156 offset:36864
	ds_read_b128 v[216:219], v156 offset:37888
	ds_read_b128 v[220:223], v156 offset:38912
	ds_read_b128 v[224:227], v156 offset:39936
	global_load_lds_dwordx4 v[232:233], off
	v_lshl_add_u64 v[232:233], s[34:35], 0, v[136:137]
	s_mov_b32 m0, s52
	s_nop 0
	global_load_lds_dwordx4 v[232:233], off
	s_waitcnt vmcnt(8)
	s_waitcnt lgkmcnt(0)
	s_barrier
	s_setprio 1
	s_waitcnt lgkmcnt(0)
	v_mfma_f32_16x16x32_bf16 v[126:129], v[144:147], v[192:195], v[126:129]
	v_mfma_f32_16x16x32_bf16 v[122:125], v[162:165], v[192:195], v[122:125]
	v_mfma_f32_16x16x32_bf16 v[110:113], v[144:147], v[204:207], v[110:113]
	v_mfma_f32_16x16x32_bf16 v[106:109], v[162:165], v[204:207], v[106:109]
	v_mfma_f32_16x16x32_bf16 v[92:95], v[144:147], v[212:215], v[92:95]
	v_mfma_f32_16x16x32_bf16 v[88:91], v[162:165], v[212:215], v[88:91]
	v_mfma_f32_16x16x32_bf16 v[76:79], v[144:147], v[220:223], v[76:79]
	v_mfma_f32_16x16x32_bf16 v[72:75], v[162:165], v[220:223], v[72:75]
	v_mfma_f32_16x16x32_bf16 v[126:129], v[158:161], v[196:199], v[126:129]
	v_mfma_f32_16x16x32_bf16 v[122:125], v[172:175], v[196:199], v[122:125]
	v_mfma_f32_16x16x32_bf16 v[110:113], v[158:161], v[208:211], v[110:113]
	v_mfma_f32_16x16x32_bf16 v[106:109], v[172:175], v[208:211], v[106:109]
	v_mfma_f32_16x16x32_bf16 v[92:95], v[158:161], v[216:219], v[92:95]
	v_mfma_f32_16x16x32_bf16 v[88:91], v[172:175], v[216:219], v[88:91]
	v_mfma_f32_16x16x32_bf16 v[76:79], v[158:161], v[224:227], v[76:79]
	v_mfma_f32_16x16x32_bf16 v[72:75], v[172:175], v[224:227], v[72:75]
	v_mfma_f32_16x16x32_bf16 v[118:121], v[176:179], v[192:195], v[118:121]
	v_mfma_f32_16x16x32_bf16 v[114:117], v[184:187], v[192:195], v[114:117]
	v_mfma_f32_16x16x32_bf16 v[102:105], v[176:179], v[204:207], v[102:105]
	v_mfma_f32_16x16x32_bf16 v[98:101], v[184:187], v[204:207], v[98:101]
	v_mfma_f32_16x16x32_bf16 v[84:87], v[176:179], v[212:215], v[84:87]
	v_mfma_f32_16x16x32_bf16 v[80:83], v[184:187], v[212:215], v[80:83]
	v_mfma_f32_16x16x32_bf16 v[68:71], v[176:179], v[220:223], v[68:71]
	v_mfma_f32_16x16x32_bf16 v[64:67], v[184:187], v[220:223], v[64:67]
	v_mfma_f32_16x16x32_bf16 v[118:121], v[180:183], v[196:199], v[118:121]
	v_mfma_f32_16x16x32_bf16 v[114:117], v[188:191], v[196:199], v[114:117]
	v_mfma_f32_16x16x32_bf16 v[102:105], v[180:183], v[208:211], v[102:105]
	v_mfma_f32_16x16x32_bf16 v[98:101], v[188:191], v[208:211], v[98:101]
	v_mfma_f32_16x16x32_bf16 v[84:87], v[180:183], v[216:219], v[84:87]
	v_mfma_f32_16x16x32_bf16 v[80:83], v[188:191], v[216:219], v[80:83]
	v_mfma_f32_16x16x32_bf16 v[68:71], v[180:183], v[224:227], v[68:71]
	v_mfma_f32_16x16x32_bf16 v[64:67], v[188:191], v[224:227], v[64:67]
	s_setprio 0
	s_barrier
; #define PG8_STAGE(bufoff, gbase, voff) do { _Pragma("unroll") for (int _i = 0; _i < 2; ++_i) \
;         __builtin_amdgcn_global_load_lds((const unsigned*)((const char*)(gbase) + (voff)[_i]), (PG8_LAS unsigned*)(lds + (bufoff) + ldsw + _i * 8192), 16, 0, 0); } while (0)
; #define PG8_LDA(dst, b, h) do { _Pragma("unroll") for (int m = 0; m < 4; ++m) _Pragma("unroll") for (int k = 0; k < 2; ++k) dst[m][k] = *(const PG8_LAS bf16x8*)(lds + PG8_SA(b, h) + aoff + m * 2048 + k * 1024); } while (0)
; #define PG8_MMA(ai, bj, At, Bt) do { __builtin_amdgcn_s_setprio(1); _Pragma("unroll") for (int m = 0; m < 4; ++m) _Pragma("unroll") for (int n = 0; n < 2; ++n) _Pragma("unroll") for (int k = 0; k < 2; ++k) \
;         acc[ai][bj][m][n] = __builtin_amdgcn_mfma_f32_16x16x32_bf16(Bt[n][k], At[m][k], acc[ai][bj][m][n], 0, 0, 0); __builtin_amdgcn_s_setprio(0); } while (0)
; #define PG8_WAIT_V(n) asm volatile("s_waitcnt vmcnt(" #n ")" ::: "memory")
; #define PG8_WAIT_L(n) asm volatile("s_waitcnt lgkmcnt(" #n ")" ::: "memory")
; #define PG8_BAR __builtin_amdgcn_s_barrier()
; #define PG8_SCHED __builtin_amdgcn_sched_barrier(0)
; template <class Epi, class Sched, bool ALIGN_EPI = false, bool SP2 = false>
; __device__ __forceinline__ void gemm_phase(PG8_LAS unsigned char* lds, const Gemm g, const Sched& S, const Epi& E, int tid_in) {
;     ...
;             PG8_LDA(At, 1, 1); PG8_STAGE(PG8_SB(1, 0), b3, voffB); PG8_STAGE(PG8_SB(1, 1), b3 + hstep, voffB); PG8_STAGE(PG8_SA(1, 0), a3, voffA);
;             PG8_WAIT_V(8); PG8_WAIT_L(0); PG8_BAR; PG8_MMA(1, 0, At, B0); PG8_MMA(1, 1, At, B1); PG8_BAR; PG8_SCHED;
;     ...
;         if constexpr (ALIGN_EPI) { if (wr == 0) PG8_BAR; }
	s_add_i32 s34, s62, s44
	v_lshl_add_u64 v[148:149], v[148:149], 0, s[88:89]
	s_mov_b32 m0, s34
	ds_read_b128 v[192:195], v156 offset:49152
	ds_read_b128 v[196:199], v156 offset:50176
	ds_read_b128 v[204:207], v156 offset:51200
	ds_read_b128 v[208:211], v156 offset:52224
	ds_read_b128 v[212:215], v156 offset:53248
	ds_read_b128 v[216:219], v156 offset:54272
	ds_read_b128 v[220:223], v156 offset:55296
	ds_read_b128 v[224:227], v156 offset:56320
	global_load_lds_dwordx4 v[148:149], off
	s_add_i32 m0, s34, 0x2000
	s_add_u32 s30, s30, 0x80080
	v_lshl_add_u64 v[148:149], v[200:201], 0, s[88:89]
	s_addc_u32 s31, s31, 0
	s_add_i32 s34, s63, s44
	global_load_lds_dwordx4 v[148:149], off
	v_lshl_add_u64 v[148:149], s[30:31], 0, v[96:97]
	s_mov_b32 m0, s34
	s_nop 0
	global_load_lds_dwordx4 v[148:149], off
	v_lshl_add_u64 v[148:149], s[30:31], 0, v[138:139]
	s_add_i32 m0, s34, 0x2000
	s_nop 0
	global_load_lds_dwordx4 v[148:149], off
	v_lshl_add_u64 v[148:149], v[228:229], 0, s[88:89]
	s_mov_b32 m0, s64
	s_nop 0
	global_load_lds_dwordx4 v[148:149], off
	v_lshl_add_u64 v[148:149], v[230:231], 0, s[88:89]
	s_mov_b32 m0, s65
	s_nop 0
	global_load_lds_dwordx4 v[148:149], off
	s_waitcnt vmcnt(8)
	s_waitcnt lgkmcnt(0)
	s_barrier
	s_setprio 1
	s_waitcnt lgkmcnt(0)
	v_mfma_f32_16x16x32_bf16 v[60:63], v[144:147], v[192:195], v[60:63]
	v_mfma_f32_16x16x32_bf16 v[56:59], v[162:165], v[192:195], v[56:59]
	v_mfma_f32_16x16x32_bf16 v[44:47], v[144:147], v[204:207], v[44:47]
	v_mfma_f32_16x16x32_bf16 v[40:43], v[162:165], v[204:207], v[40:43]
	v_mfma_f32_16x16x32_bf16 v[28:31], v[144:147], v[212:215], v[28:31]
	v_mfma_f32_16x16x32_bf16 v[24:27], v[162:165], v[212:215], v[24:27]
	v_mfma_f32_16x16x32_bf16 v[12:15], v[144:147], v[220:223], v[12:15]
	v_mfma_f32_16x16x32_bf16 v[8:11], v[162:165], v[220:223], v[8:11]
	v_mfma_f32_16x16x32_bf16 v[60:63], v[158:161], v[196:199], v[60:63]
	v_mfma_f32_16x16x32_bf16 v[56:59], v[172:175], v[196:199], v[56:59]
	v_mfma_f32_16x16x32_bf16 v[44:47], v[158:161], v[208:211], v[44:47]
	v_mfma_f32_16x16x32_bf16 v[40:43], v[172:175], v[208:211], v[40:43]
	v_mfma_f32_16x16x32_bf16 v[28:31], v[158:161], v[216:219], v[28:31]
	v_mfma_f32_16x16x32_bf16 v[24:27], v[172:175], v[216:219], v[24:27]
	v_mfma_f32_16x16x32_bf16 v[12:15], v[158:161], v[224:227], v[12:15]
	v_mfma_f32_16x16x32_bf16 v[8:11], v[172:175], v[224:227], v[8:11]
	v_mfma_f32_16x16x32_bf16 v[52:55], v[176:179], v[192:195], v[52:55]
	v_mfma_f32_16x16x32_bf16 v[48:51], v[184:187], v[192:195], v[48:51]
	v_mfma_f32_16x16x32_bf16 v[36:39], v[176:179], v[204:207], v[36:39]
	v_mfma_f32_16x16x32_bf16 v[32:35], v[184:187], v[204:207], v[32:35]
	v_mfma_f32_16x16x32_bf16 v[20:23], v[176:179], v[212:215], v[20:23]
	v_mfma_f32_16x16x32_bf16 v[16:19], v[184:187], v[212:215], v[16:19]
	v_mfma_f32_16x16x32_bf16 v[4:7], v[176:179], v[220:223], v[4:7]
	v_mfma_f32_16x16x32_bf16 v[0:3], v[184:187], v[220:223], v[0:3]
	v_mfma_f32_16x16x32_bf16 v[52:55], v[180:183], v[196:199], v[52:55]
	v_mfma_f32_16x16x32_bf16 v[48:51], v[188:191], v[196:199], v[48:51]
	v_mfma_f32_16x16x32_bf16 v[36:39], v[180:183], v[208:211], v[36:39]
	v_mfma_f32_16x16x32_bf16 v[32:35], v[188:191], v[208:211], v[32:35]
	v_mfma_f32_16x16x32_bf16 v[20:23], v[180:183], v[216:219], v[20:23]
	v_mfma_f32_16x16x32_bf16 v[16:19], v[188:191], v[216:219], v[16:19]
	v_mfma_f32_16x16x32_bf16 v[4:7], v[180:183], v[224:227], v[4:7]
	v_mfma_f32_16x16x32_bf16 v[0:3], v[188:191], v[224:227], v[0:3]
	s_setprio 0
	s_barrier
	s_add_i32 s72, s72, 2
	s_add_u32 s28, s28, 0x100
	s_addc_u32 s29, s29, 0
	s_add_u32 s70, s70, 0x100
	s_addc_u32 s71, s71, 0
	s_cmp_gt_u32 s72, 29
	s_cbranch_scc0 .LBB0_632
	v_readlane_b32 s70, v255, 33
	s_and_b64 vcc, exec, s[16:17]
	v_readlane_b32 s71, v255, 34
	s_cbranch_vccz .LBB0_635
	s_barrier

; #define PG8_STAGE(bufoff, gbase, voff) do { _Pragma("unroll") for (int _i = 0; _i < 2; ++_i) \
;         __builtin_amdgcn_global_load_lds((const unsigned*)((const char*)(gbase) + (voff)[_i]), (PG8_LAS unsigned*)(lds + (bufoff) + ldsw + _i * 8192), 16, 0, 0); } while (0)
; #define PG8_LDA(dst, b, h) do { _Pragma("unroll") for (int m = 0; m < 4; ++m) _Pragma("unroll") for (int k = 0; k < 2; ++k) dst[m][k] = *(const PG8_LAS bf16x8*)(lds + PG8_SA(b, h) + aoff + m * 2048 + k * 1024); } while (0)
; #define PG8_LDB(dst, b, h) do { _Pragma("unroll") for (int n = 0; n < 2; ++n) _Pragma("unroll") for (int k = 0; k < 2; ++k) dst[n][k] = *(const PG8_LAS bf16x8*)(lds + PG8_SB(b, h) + boff + n * 2048 + k * 1024); } while (0)
; #define PG8_MMA(ai, bj, At, Bt) do { __builtin_amdgcn_s_setprio(1); _Pragma("unroll") for (int m = 0; m < 4; ++m) _Pragma("unroll") for (int n = 0; n < 2; ++n) _Pragma("unroll") for (int k = 0; k < 2; ++k) \
;         acc[ai][bj][m][n] = __builtin_amdgcn_mfma_f32_16x16x32_bf16(Bt[n][k], At[m][k], acc[ai][bj][m][n], 0, 0, 0); __builtin_amdgcn_s_setprio(0); } while (0)
; #define PG8_WAIT_V(n) asm volatile("s_waitcnt vmcnt(" #n ")" ::: "memory")
; #define PG8_WAIT_L(n) asm volatile("s_waitcnt lgkmcnt(" #n ")" ::: "memory")
; template <class Epi, class Sched, bool ALIGN_EPI = false, bool SP2 = false>
; __device__ __forceinline__ void gemm_phase(PG8_LAS unsigned char* lds, const Gemm g, const Sched& S, const Epi& E, int tid_in) {
;     ...
;             const bool last = (t == nt - 2);
;             const char* a1 = cA + (size_t)(t + 1) * kstep;
;             const char* a2 = last ? nA : cA + (size_t)(t + 2) * kstep; const char* b2 = last ? nB : cB + (size_t)(t + 2) * kstep;
;             const char* a3 = a2 + kstep; const char* b3 = b2 + kstep;
;             if (last && has_next) S.a_ready(nxt);
;             if constexpr (SP2) {
;             PG8_LDB(B0, 0, 0); PG8_LDB(B1, 0, 1); PG8_SCHED; PG8_LDA(At, 0, 0); PG8_STAGE(PG8_SA(1, 1), a1 + hstep, voffA);
;             PG8_WAIT_V(8); PG8_WAIT_L(0); PG8_BAR; PG8_MMA(0, 0, At, B0); PG8_MMA(0, 1, At, B1); PG8_BAR; PG8_SCHED;
;             PG8_LDA(At, 0, 1); PG8_STAGE(PG8_SB(0, 0), b2, voffB); PG8_STAGE(PG8_SB(0, 1), b2 + hstep, voffB); PG8_STAGE(PG8_SA(0, 0), a2, voffA);
;             PG8_WAIT_V(8); PG8_WAIT_L(0); PG8_BAR; PG8_MMA(1, 0, At, B0); PG8_MMA(1, 1, At, B1); PG8_BAR; PG8_SCHED;
.LBB0_749:
	s_add_u32 s24, s22, 0xfff80080
	s_addc_u32 s25, s23, -1
	s_add_i32 s52, 0, 0x10000
	s_cmp_eq_u32 s47, 28
	s_cselect_b32 s27, s17, s25
	s_cselect_b32 s26, s43, s24
	v_add_u32_e32 v145, s52, v142
	s_cselect_b32 s25, s15, s46
	s_cselect_b32 s24, s44, s45
	s_add_i32 s64, 0, 0x14000
	ds_read_b128 v[146:149], v145
	ds_read_b128 v[150:153], v145 offset:1024
	ds_read_b128 v[154:157], v145 offset:2048
	ds_read_b128 v[158:161], v145 offset:3072
	v_add_u32_e32 v145, s64, v142
	ds_read_b128 v[162:165], v145
	ds_read_b128 v[172:175], v145 offset:1024
	ds_read_b128 v[176:179], v145 offset:2048
	ds_read_b128 v[180:183], v145 offset:3072
	v_lshl_add_u64 v[200:201], s[22:23], 0, v[136:137]
	s_add_i32 m0, s13, 0xc000
	ds_read_b128 v[184:187], v144
	ds_read_b128 v[188:191], v144 offset:1024
	ds_read_b128 v[192:195], v144 offset:2048
	ds_read_b128 v[196:199], v144 offset:3072
	ds_read_b128 v[204:207], v144 offset:4096
	ds_read_b128 v[208:211], v144 offset:5120
	ds_read_b128 v[212:215], v144 offset:6144
	ds_read_b128 v[216:219], v144 offset:7168
	global_load_lds_dwordx4 v[200:201], off
	v_lshl_add_u64 v[200:201], s[22:23], 0, v[138:139]
	s_add_i32 m0, s13, 0xe000
	s_nop 0
	global_load_lds_dwordx4 v[200:201], off
	s_waitcnt vmcnt(8)
	s_waitcnt lgkmcnt(0)
	s_barrier
	s_setprio 1
	s_waitcnt lgkmcnt(0)
	v_mfma_f32_16x16x32_bf16 v[126:129], v[146:149], v[184:187], v[126:129]
	v_mfma_f32_16x16x32_bf16 v[122:125], v[154:157], v[184:187], v[122:125]
	v_mfma_f32_16x16x32_bf16 v[118:121], v[146:149], v[192:195], v[118:121]
	v_mfma_f32_16x16x32_bf16 v[114:117], v[154:157], v[192:195], v[114:117]
	v_mfma_f32_16x16x32_bf16 v[102:105], v[146:149], v[204:207], v[102:105]
	v_mfma_f32_16x16x32_bf16 v[98:101], v[154:157], v[204:207], v[98:101]
	v_mfma_f32_16x16x32_bf16 v[84:87], v[146:149], v[212:215], v[84:87]
	v_mfma_f32_16x16x32_bf16 v[80:83], v[154:157], v[212:215], v[80:83]
	v_mfma_f32_16x16x32_bf16 v[126:129], v[150:153], v[188:191], v[126:129]
	v_mfma_f32_16x16x32_bf16 v[122:125], v[158:161], v[188:191], v[122:125]
	v_mfma_f32_16x16x32_bf16 v[118:121], v[150:153], v[196:199], v[118:121]
	v_mfma_f32_16x16x32_bf16 v[114:117], v[158:161], v[196:199], v[114:117]
	v_mfma_f32_16x16x32_bf16 v[102:105], v[150:153], v[208:211], v[102:105]
	v_mfma_f32_16x16x32_bf16 v[98:101], v[158:161], v[208:211], v[98:101]
	v_mfma_f32_16x16x32_bf16 v[84:87], v[150:153], v[216:219], v[84:87]
	v_mfma_f32_16x16x32_bf16 v[80:83], v[158:161], v[216:219], v[80:83]
	v_mfma_f32_16x16x32_bf16 v[110:113], v[162:165], v[184:187], v[110:113]
	v_mfma_f32_16x16x32_bf16 v[106:109], v[176:179], v[184:187], v[106:109]
	v_mfma_f32_16x16x32_bf16 v[92:95], v[162:165], v[192:195], v[92:95]
	v_mfma_f32_16x16x32_bf16 v[88:91], v[176:179], v[192:195], v[88:91]
	v_mfma_f32_16x16x32_bf16 v[76:79], v[162:165], v[204:207], v[76:79]
	v_mfma_f32_16x16x32_bf16 v[72:75], v[176:179], v[204:207], v[72:75]
	v_mfma_f32_16x16x32_bf16 v[68:71], v[162:165], v[212:215], v[68:71]
	v_mfma_f32_16x16x32_bf16 v[64:67], v[176:179], v[212:215], v[64:67]
	v_mfma_f32_16x16x32_bf16 v[110:113], v[172:175], v[188:191], v[110:113]
	v_mfma_f32_16x16x32_bf16 v[106:109], v[180:183], v[188:191], v[106:109]
	v_mfma_f32_16x16x32_bf16 v[92:95], v[172:175], v[196:199], v[92:95]
	v_mfma_f32_16x16x32_bf16 v[88:91], v[180:183], v[196:199], v[88:91]
	v_mfma_f32_16x16x32_bf16 v[76:79], v[172:175], v[208:211], v[76:79]
	v_mfma_f32_16x16x32_bf16 v[72:75], v[180:183], v[208:211], v[72:75]
	v_mfma_f32_16x16x32_bf16 v[68:71], v[172:175], v[216:219], v[68:71]
	v_mfma_f32_16x16x32_bf16 v[64:67], v[180:183], v[216:219], v[64:67]
	s_setprio 0
	s_barrier
	s_add_i32 s52, s52, s35
	v_lshl_add_u64 v[200:201], s[24:25], 0, v[96:97]
	s_mov_b32 m0, s52
	ds_read_b128 v[184:187], v144 offset:16384
	ds_read_b128 v[188:191], v144 offset:17408
	ds_read_b128 v[192:195], v144 offset:18432
	ds_read_b128 v[196:199], v144 offset:19456
	ds_read_b128 v[204:207], v144 offset:20480
	ds_read_b128 v[208:211], v144 offset:21504
	ds_read_b128 v[212:215], v144 offset:22528
	ds_read_b128 v[216:219], v144 offset:23552
	global_load_lds_dwordx4 v[200:201], off
	s_add_i32 m0, s52, 0x2000
	s_add_u32 s62, s24, 0x80000
	v_lshl_add_u64 v[220:221], s[24:25], 0, v[134:135]
	s_addc_u32 s63, s25, 0
	s_add_i32 s52, s64, s35
	global_load_lds_dwordx4 v[220:221], off
	v_lshl_add_u64 v[222:223], s[62:63], 0, v[96:97]
	s_mov_b32 m0, s52
	v_lshl_add_u64 v[224:225], s[26:27], 0, v[132:133]
	global_load_lds_dwordx4 v[222:223], off
	v_lshl_add_u64 v[222:223], s[62:63], 0, v[134:135]
	s_add_i32 m0, s52, 0x2000
	s_nop 0
	global_load_lds_dwordx4 v[222:223], off
	v_lshl_add_u64 v[222:223], s[26:27], 0, v[130:131]
	s_mov_b32 m0, s13
	s_nop 0
	global_load_lds_dwordx4 v[222:223], off
	s_mov_b32 m0, s36
	s_nop 0
	global_load_lds_dwordx4 v[224:225], off
	s_waitcnt vmcnt(8)
	s_waitcnt lgkmcnt(0)
	s_barrier
; #define PG8_STAGE(bufoff, gbase, voff) do { _Pragma("unroll") for (int _i = 0; _i < 2; ++_i) \
;         __builtin_amdgcn_global_load_lds((const unsigned*)((const char*)(gbase) + (voff)[_i]), (PG8_LAS unsigned*)(lds + (bufoff) + ldsw + _i * 8192), 16, 0, 0); } while (0)
; #define PG8_LDA(dst, b, h) do { _Pragma("unroll") for (int m = 0; m < 4; ++m) _Pragma("unroll") for (int k = 0; k < 2; ++k) dst[m][k] = *(const PG8_LAS bf16x8*)(lds + PG8_SA(b, h) + aoff + m * 2048 + k * 1024); } while (0)
; #define PG8_LDB(dst, b, h) do { _Pragma("unroll") for (int n = 0; n < 2; ++n) _Pragma("unroll") for (int k = 0; k < 2; ++k) dst[n][k] = *(const PG8_LAS bf16x8*)(lds + PG8_SB(b, h) + boff + n * 2048 + k * 1024); } while (0)
; #define PG8_MMA(ai, bj, At, Bt) do { __builtin_amdgcn_s_setprio(1); _Pragma("unroll") for (int m = 0; m < 4; ++m) _Pragma("unroll") for (int n = 0; n < 2; ++n) _Pragma("unroll") for (int k = 0; k < 2; ++k) \
;         acc[ai][bj][m][n] = __builtin_amdgcn_mfma_f32_16x16x32_bf16(Bt[n][k], At[m][k], acc[ai][bj][m][n], 0, 0, 0); __builtin_amdgcn_s_setprio(0); } while (0)
; #define PG8_WAIT_V(n) asm volatile("s_waitcnt vmcnt(" #n ")" ::: "memory")
; #define PG8_WAIT_L(n) asm volatile("s_waitcnt lgkmcnt(" #n ")" ::: "memory")
; #define PG8_BAR __builtin_amdgcn_s_barrier()
; #define PG8_SCHED __builtin_amdgcn_sched_barrier(0)
; template <class Epi, class Sched, bool ALIGN_EPI = false, bool SP2 = false>
; __device__ __forceinline__ void gemm_phase(PG8_LAS unsigned char* lds, const Gemm g, const Sched& S, const Epi& E, int tid_in) {
;     ...
;             PG8_WAIT_V(8); PG8_WAIT_L(0); PG8_BAR; PG8_MMA(1, 0, At, B0); PG8_MMA(1, 1, At, B1); PG8_BAR; PG8_SCHED;
;             PG8_LDB(B0, 1, 0); PG8_LDB(B1, 1, 1); PG8_SCHED; PG8_LDA(At, 1, 0); PG8_STAGE(PG8_SA(0, 1), a2 + hstep, voffA);
;             PG8_WAIT_V(8); PG8_WAIT_L(0); PG8_BAR; PG8_MMA(0, 0, At, B0); PG8_MMA(0, 1, At, B1); PG8_BAR; PG8_SCHED;
	s_setprio 1
	s_waitcnt lgkmcnt(0)
	v_mfma_f32_16x16x32_bf16 v[60:63], v[146:149], v[184:187], v[60:63]
	v_mfma_f32_16x16x32_bf16 v[56:59], v[154:157], v[184:187], v[56:59]
	v_mfma_f32_16x16x32_bf16 v[52:55], v[146:149], v[192:195], v[52:55]
	v_mfma_f32_16x16x32_bf16 v[48:51], v[154:157], v[192:195], v[48:51]
	v_mfma_f32_16x16x32_bf16 v[36:39], v[146:149], v[204:207], v[36:39]
	v_mfma_f32_16x16x32_bf16 v[32:35], v[154:157], v[204:207], v[32:35]
	v_mfma_f32_16x16x32_bf16 v[20:23], v[146:149], v[212:215], v[20:23]
	v_mfma_f32_16x16x32_bf16 v[16:19], v[154:157], v[212:215], v[16:19]
	v_mfma_f32_16x16x32_bf16 v[60:63], v[150:153], v[188:191], v[60:63]
	v_mfma_f32_16x16x32_bf16 v[56:59], v[158:161], v[188:191], v[56:59]
	v_mfma_f32_16x16x32_bf16 v[52:55], v[150:153], v[196:199], v[52:55]
	v_mfma_f32_16x16x32_bf16 v[48:51], v[158:161], v[196:199], v[48:51]
	v_mfma_f32_16x16x32_bf16 v[36:39], v[150:153], v[208:211], v[36:39]
	v_mfma_f32_16x16x32_bf16 v[32:35], v[158:161], v[208:211], v[32:35]
	v_mfma_f32_16x16x32_bf16 v[20:23], v[150:153], v[216:219], v[20:23]
	v_mfma_f32_16x16x32_bf16 v[16:19], v[158:161], v[216:219], v[16:19]
	v_mfma_f32_16x16x32_bf16 v[44:47], v[162:165], v[184:187], v[44:47]
	v_mfma_f32_16x16x32_bf16 v[40:43], v[176:179], v[184:187], v[40:43]
	v_mfma_f32_16x16x32_bf16 v[28:31], v[162:165], v[192:195], v[28:31]
	v_mfma_f32_16x16x32_bf16 v[24:27], v[176:179], v[192:195], v[24:27]
	v_mfma_f32_16x16x32_bf16 v[12:15], v[162:165], v[204:207], v[12:15]
	v_mfma_f32_16x16x32_bf16 v[8:11], v[176:179], v[204:207], v[8:11]
	v_mfma_f32_16x16x32_bf16 v[4:7], v[162:165], v[212:215], v[4:7]
	v_mfma_f32_16x16x32_bf16 v[0:3], v[176:179], v[212:215], v[0:3]
	v_mfma_f32_16x16x32_bf16 v[44:47], v[172:175], v[188:191], v[44:47]
	v_mfma_f32_16x16x32_bf16 v[40:43], v[180:183], v[188:191], v[40:43]
	v_mfma_f32_16x16x32_bf16 v[28:31], v[172:175], v[196:199], v[28:31]
	v_mfma_f32_16x16x32_bf16 v[24:27], v[180:183], v[196:199], v[24:27]
	v_mfma_f32_16x16x32_bf16 v[12:15], v[172:175], v[208:211], v[12:15]
	v_mfma_f32_16x16x32_bf16 v[8:11], v[180:183], v[208:211], v[8:11]
	v_mfma_f32_16x16x32_bf16 v[4:7], v[172:175], v[216:219], v[4:7]
	v_mfma_f32_16x16x32_bf16 v[0:3], v[180:183], v[216:219], v[0:3]
	s_setprio 0
	s_barrier
	s_add_i32 s52, 0, 0x18000
	v_add_u32_e32 v145, s52, v142
	s_add_i32 s62, 0, 0x1c000
	ds_read_b128 v[146:149], v145
	ds_read_b128 v[150:153], v145 offset:1024
	ds_read_b128 v[154:157], v145 offset:2048
	ds_read_b128 v[158:161], v145 offset:3072
	v_add_u32_e32 v145, s62, v142
	ds_read_b128 v[162:165], v145
	ds_read_b128 v[172:175], v145 offset:1024
	ds_read_b128 v[176:179], v145 offset:2048
	ds_read_b128 v[180:183], v145 offset:3072
	s_add_u32 s26, s26, 0x80000
	s_addc_u32 s27, s27, 0
	s_mov_b32 m0, s37
	v_lshl_add_u64 v[226:227], s[26:27], 0, v[130:131]
	ds_read_b128 v[184:187], v144 offset:32768
	ds_read_b128 v[188:191], v144 offset:33792
	ds_read_b128 v[192:195], v144 offset:34816
	ds_read_b128 v[196:199], v144 offset:35840
	ds_read_b128 v[204:207], v144 offset:36864
	ds_read_b128 v[208:211], v144 offset:37888
	ds_read_b128 v[212:215], v144 offset:38912
	ds_read_b128 v[216:219], v144 offset:39936
	global_load_lds_dwordx4 v[226:227], off
	v_lshl_add_u64 v[226:227], s[26:27], 0, v[132:133]
	s_mov_b32 m0, s38
	s_nop 0
	global_load_lds_dwordx4 v[226:227], off
	s_waitcnt vmcnt(8)
	s_waitcnt lgkmcnt(0)
	s_barrier
	s_setprio 1
	s_waitcnt lgkmcnt(0)
	v_mfma_f32_16x16x32_bf16 v[126:129], v[146:149], v[184:187], v[126:129]
	v_mfma_f32_16x16x32_bf16 v[122:125], v[154:157], v[184:187], v[122:125]
	v_mfma_f32_16x16x32_bf16 v[118:121], v[146:149], v[192:195], v[118:121]
	v_mfma_f32_16x16x32_bf16 v[114:117], v[154:157], v[192:195], v[114:117]
	v_mfma_f32_16x16x32_bf16 v[102:105], v[146:149], v[204:207], v[102:105]
	v_mfma_f32_16x16x32_bf16 v[98:101], v[154:157], v[204:207], v[98:101]
	v_mfma_f32_16x16x32_bf16 v[84:87], v[146:149], v[212:215], v[84:87]
	v_mfma_f32_16x16x32_bf16 v[80:83], v[154:157], v[212:215], v[80:83]
	v_mfma_f32_16x16x32_bf16 v[126:129], v[150:153], v[188:191], v[126:129]
	v_mfma_f32_16x16x32_bf16 v[122:125], v[158:161], v[188:191], v[122:125]
	v_mfma_f32_16x16x32_bf16 v[118:121], v[150:153], v[196:199], v[118:121]
	v_mfma_f32_16x16x32_bf16 v[114:117], v[158:161], v[196:199], v[114:117]
	v_mfma_f32_16x16x32_bf16 v[102:105], v[150:153], v[208:211], v[102:105]
	v_mfma_f32_16x16x32_bf16 v[98:101], v[158:161], v[208:211], v[98:101]
	v_mfma_f32_16x16x32_bf16 v[84:87], v[150:153], v[216:219], v[84:87]
	v_mfma_f32_16x16x32_bf16 v[80:83], v[158:161], v[216:219], v[80:83]
	v_mfma_f32_16x16x32_bf16 v[110:113], v[162:165], v[184:187], v[110:113]
	v_mfma_f32_16x16x32_bf16 v[106:109], v[176:179], v[184:187], v[106:109]
	v_mfma_f32_16x16x32_bf16 v[92:95], v[162:165], v[192:195], v[92:95]
	v_mfma_f32_16x16x32_bf16 v[88:91], v[176:179], v[192:195], v[88:91]
	v_mfma_f32_16x16x32_bf16 v[76:79], v[162:165], v[204:207], v[76:79]
	v_mfma_f32_16x16x32_bf16 v[72:75], v[176:179], v[204:207], v[72:75]
	v_mfma_f32_16x16x32_bf16 v[68:71], v[162:165], v[212:215], v[68:71]
	v_mfma_f32_16x16x32_bf16 v[64:67], v[176:179], v[212:215], v[64:67]
	v_mfma_f32_16x16x32_bf16 v[110:113], v[172:175], v[188:191], v[110:113]
	v_mfma_f32_16x16x32_bf16 v[106:109], v[180:183], v[188:191], v[106:109]
	v_mfma_f32_16x16x32_bf16 v[92:95], v[172:175], v[196:199], v[92:95]
	v_mfma_f32_16x16x32_bf16 v[88:91], v[180:183], v[196:199], v[88:91]
	v_mfma_f32_16x16x32_bf16 v[76:79], v[172:175], v[208:211], v[76:79]
	v_mfma_f32_16x16x32_bf16 v[72:75], v[180:183], v[208:211], v[72:75]
	v_mfma_f32_16x16x32_bf16 v[68:71], v[172:175], v[216:219], v[68:71]
	v_mfma_f32_16x16x32_bf16 v[64:67], v[180:183], v[216:219], v[64:67]
	s_setprio 0
	s_barrier
; #define PG8_STAGE(bufoff, gbase, voff) do { _Pragma("unroll") for (int _i = 0; _i < 2; ++_i) \
;         __builtin_amdgcn_global_load_lds((const unsigned*)((const char*)(gbase) + (voff)[_i]), (PG8_LAS unsigned*)(lds + (bufoff) + ldsw + _i * 8192), 16, 0, 0); } while (0)
; #define PG8_LDA(dst, b, h) do { _Pragma("unroll") for (int m = 0; m < 4; ++m) _Pragma("unroll") for (int k = 0; k < 2; ++k) dst[m][k] = *(const PG8_LAS bf16x8*)(lds + PG8_SA(b, h) + aoff + m * 2048 + k * 1024); } while (0)
; #define PG8_MMA(ai, bj, At, Bt) do { __builtin_amdgcn_s_setprio(1); _Pragma("unroll") for (int m = 0; m < 4; ++m) _Pragma("unroll") for (int n = 0; n < 2; ++n) _Pragma("unroll") for (int k = 0; k < 2; ++k) \
;         acc[ai][bj][m][n] = __builtin_amdgcn_mfma_f32_16x16x32_bf16(Bt[n][k], At[m][k], acc[ai][bj][m][n], 0, 0, 0); __builtin_amdgcn_s_setprio(0); } while (0)
; #define PG8_WAIT_V(n) asm volatile("s_waitcnt vmcnt(" #n ")" ::: "memory")
; #define PG8_WAIT_L(n) asm volatile("s_waitcnt lgkmcnt(" #n ")" ::: "memory")
; #define PG8_BAR __builtin_amdgcn_s_barrier()
; #define PG8_SCHED __builtin_amdgcn_sched_barrier(0)
; template <class Epi, class Sched, bool ALIGN_EPI = false, bool SP2 = false>
; __device__ __forceinline__ void gemm_phase(PG8_LAS unsigned char* lds, const Gemm g, const Sched& S, const Epi& E, int tid_in) {
;     ...
;             PG8_LDA(At, 1, 1); PG8_STAGE(PG8_SB(1, 0), b3, voffB); PG8_STAGE(PG8_SB(1, 1), b3 + hstep, voffB); PG8_STAGE(PG8_SA(1, 0), a3, voffA);
;             PG8_WAIT_V(8); PG8_WAIT_L(0); PG8_BAR; PG8_MMA(1, 0, At, B0); PG8_MMA(1, 1, At, B1); PG8_BAR; PG8_SCHED;
;     ...
;         if constexpr (ALIGN_EPI) { if (wr == 0) PG8_BAR; }
	s_add_i32 s26, s52, s35
	v_lshl_add_u64 v[200:201], v[200:201], 0, s[88:89]
	s_mov_b32 m0, s26
	ds_read_b128 v[184:187], v144 offset:49152
	ds_read_b128 v[188:191], v144 offset:50176
	ds_read_b128 v[192:195], v144 offset:51200
	ds_read_b128 v[196:199], v144 offset:52224
	ds_read_b128 v[204:207], v144 offset:53248
	ds_read_b128 v[208:211], v144 offset:54272
	ds_read_b128 v[212:215], v144 offset:55296
	ds_read_b128 v[216:219], v144 offset:56320
	global_load_lds_dwordx4 v[200:201], off
	s_add_i32 m0, s26, 0x2000
	s_add_u32 s24, s24, 0x80080
	v_lshl_add_u64 v[200:201], v[220:221], 0, s[88:89]
	s_addc_u32 s25, s25, 0
	s_add_i32 s26, s62, s35
	global_load_lds_dwordx4 v[200:201], off
	v_lshl_add_u64 v[200:201], s[24:25], 0, v[96:97]
	s_mov_b32 m0, s26
	s_nop 0
	global_load_lds_dwordx4 v[200:201], off
	v_lshl_add_u64 v[200:201], s[24:25], 0, v[134:135]
	s_add_i32 m0, s26, 0x2000
	s_nop 0
	global_load_lds_dwordx4 v[200:201], off
	v_lshl_add_u64 v[200:201], v[222:223], 0, s[88:89]
	s_mov_b32 m0, s39
	s_nop 0
	global_load_lds_dwordx4 v[200:201], off
	v_lshl_add_u64 v[200:201], v[224:225], 0, s[88:89]
	s_mov_b32 m0, s40
	s_nop 0
	global_load_lds_dwordx4 v[200:201], off
	s_waitcnt vmcnt(8)
	s_waitcnt lgkmcnt(0)
	s_barrier
	s_setprio 1
	s_waitcnt lgkmcnt(0)
	v_mfma_f32_16x16x32_bf16 v[60:63], v[146:149], v[184:187], v[60:63]
	v_mfma_f32_16x16x32_bf16 v[56:59], v[154:157], v[184:187], v[56:59]
	v_mfma_f32_16x16x32_bf16 v[52:55], v[146:149], v[192:195], v[52:55]
	v_mfma_f32_16x16x32_bf16 v[48:51], v[154:157], v[192:195], v[48:51]
	v_mfma_f32_16x16x32_bf16 v[36:39], v[146:149], v[204:207], v[36:39]
	v_mfma_f32_16x16x32_bf16 v[32:35], v[154:157], v[204:207], v[32:35]
	v_mfma_f32_16x16x32_bf16 v[20:23], v[146:149], v[212:215], v[20:23]
	v_mfma_f32_16x16x32_bf16 v[16:19], v[154:157], v[212:215], v[16:19]
	v_mfma_f32_16x16x32_bf16 v[60:63], v[150:153], v[188:191], v[60:63]
	v_mfma_f32_16x16x32_bf16 v[56:59], v[158:161], v[188:191], v[56:59]
	v_mfma_f32_16x16x32_bf16 v[52:55], v[150:153], v[196:199], v[52:55]
	v_mfma_f32_16x16x32_bf16 v[48:51], v[158:161], v[196:199], v[48:51]
	v_mfma_f32_16x16x32_bf16 v[36:39], v[150:153], v[208:211], v[36:39]
	v_mfma_f32_16x16x32_bf16 v[32:35], v[158:161], v[208:211], v[32:35]
	v_mfma_f32_16x16x32_bf16 v[20:23], v[150:153], v[216:219], v[20:23]
	v_mfma_f32_16x16x32_bf16 v[16:19], v[158:161], v[216:219], v[16:19]
	v_mfma_f32_16x16x32_bf16 v[44:47], v[162:165], v[184:187], v[44:47]
	v_mfma_f32_16x16x32_bf16 v[40:43], v[176:179], v[184:187], v[40:43]
	v_mfma_f32_16x16x32_bf16 v[28:31], v[162:165], v[192:195], v[28:31]
	v_mfma_f32_16x16x32_bf16 v[24:27], v[176:179], v[192:195], v[24:27]
	v_mfma_f32_16x16x32_bf16 v[12:15], v[162:165], v[204:207], v[12:15]
	v_mfma_f32_16x16x32_bf16 v[8:11], v[176:179], v[204:207], v[8:11]
	v_mfma_f32_16x16x32_bf16 v[4:7], v[162:165], v[212:215], v[4:7]
	v_mfma_f32_16x16x32_bf16 v[0:3], v[176:179], v[212:215], v[0:3]
	v_mfma_f32_16x16x32_bf16 v[44:47], v[172:175], v[188:191], v[44:47]
	v_mfma_f32_16x16x32_bf16 v[40:43], v[180:183], v[188:191], v[40:43]
	v_mfma_f32_16x16x32_bf16 v[28:31], v[172:175], v[196:199], v[28:31]
	v_mfma_f32_16x16x32_bf16 v[24:27], v[180:183], v[196:199], v[24:27]
	v_mfma_f32_16x16x32_bf16 v[12:15], v[172:175], v[208:211], v[12:15]
	v_mfma_f32_16x16x32_bf16 v[8:11], v[180:183], v[208:211], v[8:11]
	v_mfma_f32_16x16x32_bf16 v[4:7], v[172:175], v[216:219], v[4:7]
	v_mfma_f32_16x16x32_bf16 v[0:3], v[180:183], v[216:219], v[0:3]
	s_setprio 0
	s_barrier
	s_add_i32 s47, s47, 2
	s_add_u32 s22, s22, 0x100
	s_addc_u32 s23, s23, 0
	s_add_u32 s45, s45, 0x100
	s_addc_u32 s46, s46, 0
	s_cmp_gt_u32 s47, 29
	s_cbranch_scc0 .LBB0_749
	s_and_b64 vcc, exec, s[10:11]
	s_cbranch_vccz .LBB0_752
	s_barrier

; #define PG8_STAGE(bufoff, gbase, voff) do { _Pragma("unroll") for (int _i = 0; _i < 2; ++_i) \
;         __builtin_amdgcn_global_load_lds((const unsigned*)((const char*)(gbase) + (voff)[_i]), (PG8_LAS unsigned*)(lds + (bufoff) + ldsw + _i * 8192), 16, 0, 0); } while (0)
; #define PG8_LDA(dst, b, h) do { _Pragma("unroll") for (int m = 0; m < 4; ++m) _Pragma("unroll") for (int k = 0; k < 2; ++k) dst[m][k] = *(const PG8_LAS bf16x8*)(lds + PG8_SA(b, h) + aoff + m * 2048 + k * 1024); } while (0)
; #define PG8_LDB(dst, b, h) do { _Pragma("unroll") for (int n = 0; n < 2; ++n) _Pragma("unroll") for (int k = 0; k < 2; ++k) dst[n][k] = *(const PG8_LAS bf16x8*)(lds + PG8_SB(b, h) + boff + n * 2048 + k * 1024); } while (0)
; #define PG8_MMA(ai, bj, At, Bt) do { __builtin_amdgcn_s_setprio(1); _Pragma("unroll") for (int m = 0; m < 4; ++m) _Pragma("unroll") for (int n = 0; n < 2; ++n) _Pragma("unroll") for (int k = 0; k < 2; ++k) \
;         acc[ai][bj][m][n] = __builtin_amdgcn_mfma_f32_16x16x32_bf16(Bt[n][k], At[m][k], acc[ai][bj][m][n], 0, 0, 0); __builtin_amdgcn_s_setprio(0); } while (0)
; #define PG8_WAIT_V(n) asm volatile("s_waitcnt vmcnt(" #n ")" ::: "memory")
; #define PG8_WAIT_L(n) asm volatile("s_waitcnt lgkmcnt(" #n ")" ::: "memory")
; template <class Epi, class Sched, bool ALIGN_EPI = false, bool SP2 = false>
; __device__ __forceinline__ void gemm_phase(PG8_LAS unsigned char* lds, const Gemm g, const Sched& S, const Epi& E, int tid_in) {
;     ...
;             const bool last = (t == nt - 2);
;             const char* a1 = cA + (size_t)(t + 1) * kstep;
;             const char* a2 = last ? nA : cA + (size_t)(t + 2) * kstep; const char* b2 = last ? nB : cB + (size_t)(t + 2) * kstep;
;             const char* a3 = a2 + kstep; const char* b3 = b2 + kstep;
;             if (last && has_next) S.a_ready(nxt);
;             if constexpr (SP2) {
;             PG8_LDB(B0, 0, 0); PG8_LDB(B1, 0, 1); PG8_SCHED; PG8_LDA(At, 0, 0); PG8_STAGE(PG8_SA(1, 1), a1 + hstep, voffA);
;             PG8_WAIT_V(8); PG8_WAIT_L(0); PG8_BAR; PG8_MMA(0, 0, At, B0); PG8_MMA(0, 1, At, B1); PG8_BAR; PG8_SCHED;
;             PG8_LDA(At, 0, 1); PG8_STAGE(PG8_SB(0, 0), b2, voffB); PG8_STAGE(PG8_SB(0, 1), b2 + hstep, voffB); PG8_STAGE(PG8_SA(0, 0), a2, voffA);
;             PG8_WAIT_V(8); PG8_WAIT_L(0); PG8_BAR; PG8_MMA(1, 0, At, B0); PG8_MMA(1, 1, At, B1); PG8_BAR; PG8_SCHED;
.LBB0_979:
	s_add_u32 s26, s24, 0xfff80080
	s_addc_u32 s27, s25, -1
	s_add_i32 s62, 0, 0x10000
	s_cmp_eq_u32 s64, 28
	s_cselect_b32 s29, s17, s27
	s_cselect_b32 s28, s45, s26
	v_add_u32_e32 v140, s62, v144
	s_cselect_b32 s27, s15, s52
	s_cselect_b32 s26, s46, s47
	s_add_i32 s65, 0, 0x14000
	ds_read_b128 v[148:151], v140
	ds_read_b128 v[152:155], v140 offset:1024
	ds_read_b128 v[156:159], v140 offset:2048
	ds_read_b128 v[160:163], v140 offset:3072
	v_add_u32_e32 v140, s65, v144
	ds_read_b128 v[172:175], v140
	ds_read_b128 v[176:179], v140 offset:1024
	ds_read_b128 v[180:183], v140 offset:2048
	ds_read_b128 v[184:187], v140 offset:3072
	v_lshl_add_u64 v[140:141], s[24:25], 0, v[136:137]
	s_add_i32 m0, s38, 0xc000
	ds_read_b128 v[188:191], v146
	ds_read_b128 v[192:195], v146 offset:1024
	ds_read_b128 v[196:199], v146 offset:2048
	ds_read_b128 v[204:207], v146 offset:3072
	ds_read_b128 v[208:211], v146 offset:4096
	ds_read_b128 v[212:215], v146 offset:5120
	ds_read_b128 v[216:219], v146 offset:6144
	ds_read_b128 v[220:223], v146 offset:7168
	global_load_lds_dwordx4 v[140:141], off
	v_lshl_add_u64 v[140:141], s[24:25], 0, v[138:139]
	s_add_i32 m0, s38, 0xe000
	s_nop 0
	global_load_lds_dwordx4 v[140:141], off
	s_waitcnt vmcnt(8)
	s_waitcnt lgkmcnt(0)
	s_barrier
	s_setprio 1
	s_waitcnt lgkmcnt(0)
	v_mfma_f32_16x16x32_bf16 v[126:129], v[148:151], v[188:191], v[126:129]
	v_mfma_f32_16x16x32_bf16 v[118:121], v[156:159], v[188:191], v[118:121]
	v_mfma_f32_16x16x32_bf16 v[110:113], v[148:151], v[196:199], v[110:113]
	v_mfma_f32_16x16x32_bf16 v[102:105], v[156:159], v[196:199], v[102:105]
	v_mfma_f32_16x16x32_bf16 v[92:95], v[148:151], v[208:211], v[92:95]
	v_mfma_f32_16x16x32_bf16 v[84:87], v[156:159], v[208:211], v[84:87]
	v_mfma_f32_16x16x32_bf16 v[76:79], v[148:151], v[216:219], v[76:79]
	v_mfma_f32_16x16x32_bf16 v[68:71], v[156:159], v[216:219], v[68:71]
	v_mfma_f32_16x16x32_bf16 v[126:129], v[152:155], v[192:195], v[126:129]
	v_mfma_f32_16x16x32_bf16 v[118:121], v[160:163], v[192:195], v[118:121]
	v_mfma_f32_16x16x32_bf16 v[110:113], v[152:155], v[204:207], v[110:113]
	v_mfma_f32_16x16x32_bf16 v[102:105], v[160:163], v[204:207], v[102:105]
	v_mfma_f32_16x16x32_bf16 v[92:95], v[152:155], v[212:215], v[92:95]
	v_mfma_f32_16x16x32_bf16 v[84:87], v[160:163], v[212:215], v[84:87]
	v_mfma_f32_16x16x32_bf16 v[76:79], v[152:155], v[220:223], v[76:79]
	v_mfma_f32_16x16x32_bf16 v[68:71], v[160:163], v[220:223], v[68:71]
	v_mfma_f32_16x16x32_bf16 v[122:125], v[172:175], v[188:191], v[122:125]
	v_mfma_f32_16x16x32_bf16 v[114:117], v[180:183], v[188:191], v[114:117]
	v_mfma_f32_16x16x32_bf16 v[106:109], v[172:175], v[196:199], v[106:109]
	v_mfma_f32_16x16x32_bf16 v[98:101], v[180:183], v[196:199], v[98:101]
	v_mfma_f32_16x16x32_bf16 v[88:91], v[172:175], v[208:211], v[88:91]
	v_mfma_f32_16x16x32_bf16 v[80:83], v[180:183], v[208:211], v[80:83]
	v_mfma_f32_16x16x32_bf16 v[72:75], v[172:175], v[216:219], v[72:75]
	v_mfma_f32_16x16x32_bf16 v[64:67], v[180:183], v[216:219], v[64:67]
	v_mfma_f32_16x16x32_bf16 v[122:125], v[176:179], v[192:195], v[122:125]
	v_mfma_f32_16x16x32_bf16 v[114:117], v[184:187], v[192:195], v[114:117]
	v_mfma_f32_16x16x32_bf16 v[106:109], v[176:179], v[204:207], v[106:109]
	v_mfma_f32_16x16x32_bf16 v[98:101], v[184:187], v[204:207], v[98:101]
	v_mfma_f32_16x16x32_bf16 v[88:91], v[176:179], v[212:215], v[88:91]
	v_mfma_f32_16x16x32_bf16 v[80:83], v[184:187], v[212:215], v[80:83]
	v_mfma_f32_16x16x32_bf16 v[72:75], v[176:179], v[220:223], v[72:75]
	v_mfma_f32_16x16x32_bf16 v[64:67], v[184:187], v[220:223], v[64:67]
	s_setprio 0
	s_barrier
	s_add_i32 s62, s62, s36
	v_lshl_add_u64 v[140:141], s[26:27], 0, v[96:97]
	s_mov_b32 m0, s62
	ds_read_b128 v[188:191], v146 offset:16384
	ds_read_b128 v[192:195], v146 offset:17408
	ds_read_b128 v[196:199], v146 offset:18432
	ds_read_b128 v[204:207], v146 offset:19456
	ds_read_b128 v[208:211], v146 offset:20480
	ds_read_b128 v[212:215], v146 offset:21504
	ds_read_b128 v[216:219], v146 offset:22528
	ds_read_b128 v[220:223], v146 offset:23552
	global_load_lds_dwordx4 v[140:141], off
	s_add_i32 m0, s62, 0x2000
	s_add_u32 s62, s26, 0x80000
	v_lshl_add_u64 v[164:165], s[26:27], 0, v[130:131]
	s_addc_u32 s63, s27, 0
	s_add_i32 s65, s65, s36
	global_load_lds_dwordx4 v[164:165], off
	v_lshl_add_u64 v[200:201], s[62:63], 0, v[96:97]
	s_mov_b32 m0, s65
	v_lshl_add_u64 v[224:225], s[28:29], 0, v[132:133]
	global_load_lds_dwordx4 v[200:201], off
	v_lshl_add_u64 v[200:201], s[62:63], 0, v[130:131]
	s_add_i32 m0, s65, 0x2000
	s_nop 0
	global_load_lds_dwordx4 v[200:201], off
	v_lshl_add_u64 v[200:201], s[28:29], 0, v[134:135]
	s_mov_b32 m0, s38
	s_nop 0
	global_load_lds_dwordx4 v[200:201], off
	s_mov_b32 m0, s39
	s_nop 0
	global_load_lds_dwordx4 v[224:225], off
	s_waitcnt vmcnt(8)
	s_waitcnt lgkmcnt(0)
	s_barrier
; #define PG8_STAGE(bufoff, gbase, voff) do { _Pragma("unroll") for (int _i = 0; _i < 2; ++_i) \
;         __builtin_amdgcn_global_load_lds((const unsigned*)((const char*)(gbase) + (voff)[_i]), (PG8_LAS unsigned*)(lds + (bufoff) + ldsw + _i * 8192), 16, 0, 0); } while (0)
; #define PG8_LDA(dst, b, h) do { _Pragma("unroll") for (int m = 0; m < 4; ++m) _Pragma("unroll") for (int k = 0; k < 2; ++k) dst[m][k] = *(const PG8_LAS bf16x8*)(lds + PG8_SA(b, h) + aoff + m * 2048 + k * 1024); } while (0)
; #define PG8_LDB(dst, b, h) do { _Pragma("unroll") for (int n = 0; n < 2; ++n) _Pragma("unroll") for (int k = 0; k < 2; ++k) dst[n][k] = *(const PG8_LAS bf16x8*)(lds + PG8_SB(b, h) + boff + n * 2048 + k * 1024); } while (0)
; #define PG8_MMA(ai, bj, At, Bt) do { __builtin_amdgcn_s_setprio(1); _Pragma("unroll") for (int m = 0; m < 4; ++m) _Pragma("unroll") for (int n = 0; n < 2; ++n) _Pragma("unroll") for (int k = 0; k < 2; ++k) \
;         acc[ai][bj][m][n] = __builtin_amdgcn_mfma_f32_16x16x32_bf16(Bt[n][k], At[m][k], acc[ai][bj][m][n], 0, 0, 0); __builtin_amdgcn_s_setprio(0); } while (0)
; #define PG8_WAIT_V(n) asm volatile("s_waitcnt vmcnt(" #n ")" ::: "memory")
; #define PG8_WAIT_L(n) asm volatile("s_waitcnt lgkmcnt(" #n ")" ::: "memory")
; #define PG8_BAR __builtin_amdgcn_s_barrier()
; #define PG8_SCHED __builtin_amdgcn_sched_barrier(0)
; template <class Epi, class Sched, bool ALIGN_EPI = false, bool SP2 = false>
; __device__ __forceinline__ void gemm_phase(PG8_LAS unsigned char* lds, const Gemm g, const Sched& S, const Epi& E, int tid_in) {
;     ...
;             PG8_WAIT_V(8); PG8_WAIT_L(0); PG8_BAR; PG8_MMA(1, 0, At, B0); PG8_MMA(1, 1, At, B1); PG8_BAR; PG8_SCHED;
;             PG8_LDB(B0, 1, 0); PG8_LDB(B1, 1, 1); PG8_SCHED; PG8_LDA(At, 1, 0); PG8_STAGE(PG8_SA(0, 1), a2 + hstep, voffA);
;             PG8_WAIT_V(8); PG8_WAIT_L(0); PG8_BAR; PG8_MMA(0, 0, At, B0); PG8_MMA(0, 1, At, B1); PG8_BAR; PG8_SCHED;
	s_setprio 1
	s_waitcnt lgkmcnt(0)
	v_mfma_f32_16x16x32_bf16 v[60:63], v[148:151], v[188:191], v[60:63]
	v_mfma_f32_16x16x32_bf16 v[52:55], v[156:159], v[188:191], v[52:55]
	v_mfma_f32_16x16x32_bf16 v[44:47], v[148:151], v[196:199], v[44:47]
	v_mfma_f32_16x16x32_bf16 v[36:39], v[156:159], v[196:199], v[36:39]
	v_mfma_f32_16x16x32_bf16 v[28:31], v[148:151], v[208:211], v[28:31]
	v_mfma_f32_16x16x32_bf16 v[20:23], v[156:159], v[208:211], v[20:23]
	v_mfma_f32_16x16x32_bf16 v[12:15], v[148:151], v[216:219], v[12:15]
	v_mfma_f32_16x16x32_bf16 v[4:7], v[156:159], v[216:219], v[4:7]
	v_mfma_f32_16x16x32_bf16 v[60:63], v[152:155], v[192:195], v[60:63]
	v_mfma_f32_16x16x32_bf16 v[52:55], v[160:163], v[192:195], v[52:55]
	v_mfma_f32_16x16x32_bf16 v[44:47], v[152:155], v[204:207], v[44:47]
	v_mfma_f32_16x16x32_bf16 v[36:39], v[160:163], v[204:207], v[36:39]
	v_mfma_f32_16x16x32_bf16 v[28:31], v[152:155], v[212:215], v[28:31]
	v_mfma_f32_16x16x32_bf16 v[20:23], v[160:163], v[212:215], v[20:23]
	v_mfma_f32_16x16x32_bf16 v[12:15], v[152:155], v[220:223], v[12:15]
	v_mfma_f32_16x16x32_bf16 v[4:7], v[160:163], v[220:223], v[4:7]
	v_mfma_f32_16x16x32_bf16 v[56:59], v[172:175], v[188:191], v[56:59]
	v_mfma_f32_16x16x32_bf16 v[48:51], v[180:183], v[188:191], v[48:51]
	v_mfma_f32_16x16x32_bf16 v[40:43], v[172:175], v[196:199], v[40:43]
	v_mfma_f32_16x16x32_bf16 v[32:35], v[180:183], v[196:199], v[32:35]
	v_mfma_f32_16x16x32_bf16 v[24:27], v[172:175], v[208:211], v[24:27]
	v_mfma_f32_16x16x32_bf16 v[16:19], v[180:183], v[208:211], v[16:19]
	v_mfma_f32_16x16x32_bf16 v[8:11], v[172:175], v[216:219], v[8:11]
	v_mfma_f32_16x16x32_bf16 v[0:3], v[180:183], v[216:219], v[0:3]
	v_mfma_f32_16x16x32_bf16 v[56:59], v[176:179], v[192:195], v[56:59]
	v_mfma_f32_16x16x32_bf16 v[48:51], v[184:187], v[192:195], v[48:51]
	v_mfma_f32_16x16x32_bf16 v[40:43], v[176:179], v[204:207], v[40:43]
	v_mfma_f32_16x16x32_bf16 v[32:35], v[184:187], v[204:207], v[32:35]
	v_mfma_f32_16x16x32_bf16 v[24:27], v[176:179], v[212:215], v[24:27]
	v_mfma_f32_16x16x32_bf16 v[16:19], v[184:187], v[212:215], v[16:19]
	v_mfma_f32_16x16x32_bf16 v[8:11], v[176:179], v[220:223], v[8:11]
	v_mfma_f32_16x16x32_bf16 v[0:3], v[184:187], v[220:223], v[0:3]
	s_setprio 0
	s_barrier
	s_add_i32 s62, 0, 0x18000
	v_add_u32_e32 v147, s62, v144
	s_add_i32 s63, 0, 0x1c000
	ds_read_b128 v[148:151], v147
	ds_read_b128 v[152:155], v147 offset:1024
	ds_read_b128 v[156:159], v147 offset:2048
	ds_read_b128 v[160:163], v147 offset:3072
	v_add_u32_e32 v147, s63, v144
	ds_read_b128 v[172:175], v147
	ds_read_b128 v[176:179], v147 offset:1024
	ds_read_b128 v[180:183], v147 offset:2048
	ds_read_b128 v[184:187], v147 offset:3072
	s_add_u32 s28, s28, 0x80000
	s_addc_u32 s29, s29, 0
	s_mov_b32 m0, s40
	v_lshl_add_u64 v[226:227], s[28:29], 0, v[134:135]
	ds_read_b128 v[188:191], v146 offset:32768
	ds_read_b128 v[192:195], v146 offset:33792
	ds_read_b128 v[196:199], v146 offset:34816
	ds_read_b128 v[204:207], v146 offset:35840
	ds_read_b128 v[208:211], v146 offset:36864
	ds_read_b128 v[212:215], v146 offset:37888
	ds_read_b128 v[216:219], v146 offset:38912
	ds_read_b128 v[220:223], v146 offset:39936
	global_load_lds_dwordx4 v[226:227], off
	v_lshl_add_u64 v[226:227], s[28:29], 0, v[132:133]
	s_mov_b32 m0, s41
	s_nop 0
	global_load_lds_dwordx4 v[226:227], off
	s_waitcnt vmcnt(8)
	s_waitcnt lgkmcnt(0)
	s_barrier
	s_setprio 1
	s_waitcnt lgkmcnt(0)
	v_mfma_f32_16x16x32_bf16 v[126:129], v[148:151], v[188:191], v[126:129]
	v_mfma_f32_16x16x32_bf16 v[118:121], v[156:159], v[188:191], v[118:121]
	v_mfma_f32_16x16x32_bf16 v[110:113], v[148:151], v[196:199], v[110:113]
	v_mfma_f32_16x16x32_bf16 v[102:105], v[156:159], v[196:199], v[102:105]
	v_mfma_f32_16x16x32_bf16 v[92:95], v[148:151], v[208:211], v[92:95]
	v_mfma_f32_16x16x32_bf16 v[84:87], v[156:159], v[208:211], v[84:87]
	v_mfma_f32_16x16x32_bf16 v[76:79], v[148:151], v[216:219], v[76:79]
	v_mfma_f32_16x16x32_bf16 v[68:71], v[156:159], v[216:219], v[68:71]
	v_mfma_f32_16x16x32_bf16 v[126:129], v[152:155], v[192:195], v[126:129]
	v_mfma_f32_16x16x32_bf16 v[118:121], v[160:163], v[192:195], v[118:121]
	v_mfma_f32_16x16x32_bf16 v[110:113], v[152:155], v[204:207], v[110:113]
	v_mfma_f32_16x16x32_bf16 v[102:105], v[160:163], v[204:207], v[102:105]
	v_mfma_f32_16x16x32_bf16 v[92:95], v[152:155], v[212:215], v[92:95]
	v_mfma_f32_16x16x32_bf16 v[84:87], v[160:163], v[212:215], v[84:87]
	v_mfma_f32_16x16x32_bf16 v[76:79], v[152:155], v[220:223], v[76:79]
	v_mfma_f32_16x16x32_bf16 v[68:71], v[160:163], v[220:223], v[68:71]
	v_mfma_f32_16x16x32_bf16 v[122:125], v[172:175], v[188:191], v[122:125]
	v_mfma_f32_16x16x32_bf16 v[114:117], v[180:183], v[188:191], v[114:117]
	v_mfma_f32_16x16x32_bf16 v[106:109], v[172:175], v[196:199], v[106:109]
	v_mfma_f32_16x16x32_bf16 v[98:101], v[180:183], v[196:199], v[98:101]
	v_mfma_f32_16x16x32_bf16 v[88:91], v[172:175], v[208:211], v[88:91]
	v_mfma_f32_16x16x32_bf16 v[80:83], v[180:183], v[208:211], v[80:83]
	v_mfma_f32_16x16x32_bf16 v[72:75], v[172:175], v[216:219], v[72:75]
	v_mfma_f32_16x16x32_bf16 v[64:67], v[180:183], v[216:219], v[64:67]
	v_mfma_f32_16x16x32_bf16 v[122:125], v[176:179], v[192:195], v[122:125]
	v_mfma_f32_16x16x32_bf16 v[114:117], v[184:187], v[192:195], v[114:117]
	v_mfma_f32_16x16x32_bf16 v[106:109], v[176:179], v[204:207], v[106:109]
	v_mfma_f32_16x16x32_bf16 v[98:101], v[184:187], v[204:207], v[98:101]
	v_mfma_f32_16x16x32_bf16 v[88:91], v[176:179], v[212:215], v[88:91]
	v_mfma_f32_16x16x32_bf16 v[80:83], v[184:187], v[212:215], v[80:83]
	v_mfma_f32_16x16x32_bf16 v[72:75], v[176:179], v[220:223], v[72:75]
	v_mfma_f32_16x16x32_bf16 v[64:67], v[184:187], v[220:223], v[64:67]
	s_setprio 0
	s_barrier
; #define PG8_STAGE(bufoff, gbase, voff) do { _Pragma("unroll") for (int _i = 0; _i < 2; ++_i) \
;         __builtin_amdgcn_global_load_lds((const unsigned*)((const char*)(gbase) + (voff)[_i]), (PG8_LAS unsigned*)(lds + (bufoff) + ldsw + _i * 8192), 16, 0, 0); } while (0)
; #define PG8_LDA(dst, b, h) do { _Pragma("unroll") for (int m = 0; m < 4; ++m) _Pragma("unroll") for (int k = 0; k < 2; ++k) dst[m][k] = *(const PG8_LAS bf16x8*)(lds + PG8_SA(b, h) + aoff + m * 2048 + k * 1024); } while (0)
; #define PG8_MMA(ai, bj, At, Bt) do { __builtin_amdgcn_s_setprio(1); _Pragma("unroll") for (int m = 0; m < 4; ++m) _Pragma("unroll") for (int n = 0; n < 2; ++n) _Pragma("unroll") for (int k = 0; k < 2; ++k) \
;         acc[ai][bj][m][n] = __builtin_amdgcn_mfma_f32_16x16x32_bf16(Bt[n][k], At[m][k], acc[ai][bj][m][n], 0, 0, 0); __builtin_amdgcn_s_setprio(0); } while (0)
; #define PG8_WAIT_V(n) asm volatile("s_waitcnt vmcnt(" #n ")" ::: "memory")
; #define PG8_WAIT_L(n) asm volatile("s_waitcnt lgkmcnt(" #n ")" ::: "memory")
; #define PG8_BAR __builtin_amdgcn_s_barrier()
; #define PG8_SCHED __builtin_amdgcn_sched_barrier(0)
; template <class Epi, class Sched, bool ALIGN_EPI = false, bool SP2 = false>
; __device__ __forceinline__ void gemm_phase(PG8_LAS unsigned char* lds, const Gemm g, const Sched& S, const Epi& E, int tid_in) {
;     ...
;             PG8_LDA(At, 1, 1); PG8_STAGE(PG8_SB(1, 0), b3, voffB); PG8_STAGE(PG8_SB(1, 1), b3 + hstep, voffB); PG8_STAGE(PG8_SA(1, 0), a3, voffA);
;             PG8_WAIT_V(8); PG8_WAIT_L(0); PG8_BAR; PG8_MMA(1, 0, At, B0); PG8_MMA(1, 1, At, B1); PG8_BAR; PG8_SCHED;
;     ...
;         if constexpr (ALIGN_EPI) { if (wr == 0) PG8_BAR; }
	s_add_i32 s28, s62, s36
	v_lshl_add_u64 v[140:141], v[140:141], 0, s[88:89]
	s_mov_b32 m0, s28
	ds_read_b128 v[188:191], v146 offset:49152
	ds_read_b128 v[192:195], v146 offset:50176
	ds_read_b128 v[196:199], v146 offset:51200
	ds_read_b128 v[204:207], v146 offset:52224
	ds_read_b128 v[208:211], v146 offset:53248
	ds_read_b128 v[212:215], v146 offset:54272
	ds_read_b128 v[216:219], v146 offset:55296
	ds_read_b128 v[220:223], v146 offset:56320
	global_load_lds_dwordx4 v[140:141], off
	s_add_i32 m0, s28, 0x2000
	s_add_u32 s26, s26, 0x80080
	v_lshl_add_u64 v[140:141], v[164:165], 0, s[88:89]
	s_addc_u32 s27, s27, 0
	s_add_i32 s28, s63, s36
	global_load_lds_dwordx4 v[140:141], off
	v_lshl_add_u64 v[140:141], s[26:27], 0, v[96:97]
	s_mov_b32 m0, s28
	s_nop 0
	global_load_lds_dwordx4 v[140:141], off
	v_lshl_add_u64 v[140:141], s[26:27], 0, v[130:131]
	s_add_i32 m0, s28, 0x2000
	s_nop 0
	global_load_lds_dwordx4 v[140:141], off
	v_lshl_add_u64 v[140:141], v[200:201], 0, s[88:89]
	s_mov_b32 m0, s42
	s_nop 0
	global_load_lds_dwordx4 v[140:141], off
	v_lshl_add_u64 v[140:141], v[224:225], 0, s[88:89]
	s_mov_b32 m0, s43
	s_nop 0
	global_load_lds_dwordx4 v[140:141], off
	s_waitcnt vmcnt(8)
	s_waitcnt lgkmcnt(0)
	s_barrier
	s_setprio 1
	s_waitcnt lgkmcnt(0)
	v_mfma_f32_16x16x32_bf16 v[60:63], v[148:151], v[188:191], v[60:63]
	v_mfma_f32_16x16x32_bf16 v[52:55], v[156:159], v[188:191], v[52:55]
	v_mfma_f32_16x16x32_bf16 v[44:47], v[148:151], v[196:199], v[44:47]
	v_mfma_f32_16x16x32_bf16 v[36:39], v[156:159], v[196:199], v[36:39]
	v_mfma_f32_16x16x32_bf16 v[28:31], v[148:151], v[208:211], v[28:31]
	v_mfma_f32_16x16x32_bf16 v[20:23], v[156:159], v[208:211], v[20:23]
	v_mfma_f32_16x16x32_bf16 v[12:15], v[148:151], v[216:219], v[12:15]
	v_mfma_f32_16x16x32_bf16 v[4:7], v[156:159], v[216:219], v[4:7]
	v_mfma_f32_16x16x32_bf16 v[60:63], v[152:155], v[192:195], v[60:63]
	v_mfma_f32_16x16x32_bf16 v[52:55], v[160:163], v[192:195], v[52:55]
	v_mfma_f32_16x16x32_bf16 v[44:47], v[152:155], v[204:207], v[44:47]
	v_mfma_f32_16x16x32_bf16 v[36:39], v[160:163], v[204:207], v[36:39]
	v_mfma_f32_16x16x32_bf16 v[28:31], v[152:155], v[212:215], v[28:31]
	v_mfma_f32_16x16x32_bf16 v[20:23], v[160:163], v[212:215], v[20:23]
	v_mfma_f32_16x16x32_bf16 v[12:15], v[152:155], v[220:223], v[12:15]
	v_mfma_f32_16x16x32_bf16 v[4:7], v[160:163], v[220:223], v[4:7]
	v_mfma_f32_16x16x32_bf16 v[56:59], v[172:175], v[188:191], v[56:59]
	v_mfma_f32_16x16x32_bf16 v[48:51], v[180:183], v[188:191], v[48:51]
	v_mfma_f32_16x16x32_bf16 v[40:43], v[172:175], v[196:199], v[40:43]
	v_mfma_f32_16x16x32_bf16 v[32:35], v[180:183], v[196:199], v[32:35]
	v_mfma_f32_16x16x32_bf16 v[24:27], v[172:175], v[208:211], v[24:27]
	v_mfma_f32_16x16x32_bf16 v[16:19], v[180:183], v[208:211], v[16:19]
	v_mfma_f32_16x16x32_bf16 v[8:11], v[172:175], v[216:219], v[8:11]
	v_mfma_f32_16x16x32_bf16 v[0:3], v[180:183], v[216:219], v[0:3]
	v_mfma_f32_16x16x32_bf16 v[56:59], v[176:179], v[192:195], v[56:59]
	v_mfma_f32_16x16x32_bf16 v[48:51], v[184:187], v[192:195], v[48:51]
	v_mfma_f32_16x16x32_bf16 v[40:43], v[176:179], v[204:207], v[40:43]
	v_mfma_f32_16x16x32_bf16 v[32:35], v[184:187], v[204:207], v[32:35]
	v_mfma_f32_16x16x32_bf16 v[24:27], v[176:179], v[212:215], v[24:27]
	v_mfma_f32_16x16x32_bf16 v[16:19], v[184:187], v[212:215], v[16:19]
	v_mfma_f32_16x16x32_bf16 v[8:11], v[176:179], v[220:223], v[8:11]
	v_mfma_f32_16x16x32_bf16 v[0:3], v[184:187], v[220:223], v[0:3]
	s_setprio 0
	s_barrier
	s_add_i32 s64, s64, 2
	s_add_u32 s24, s24, 0x100
	s_addc_u32 s25, s25, 0
	s_add_u32 s47, s47, 0x100
	s_addc_u32 s52, s52, 0
	s_cmp_gt_u32 s64, 29
	s_cbranch_scc0 .LBB0_979
	s_and_b64 vcc, exec, s[12:13]
	s_cbranch_vccz .LBB0_982
	s_barrier

; #define PG8_STAGE(bufoff, gbase, voff) do { _Pragma("unroll") for (int _i = 0; _i < 2; ++_i) \
;         __builtin_amdgcn_global_load_lds((const unsigned*)((const char*)(gbase) + (voff)[_i]), (PG8_LAS unsigned*)(lds + (bufoff) + ldsw + _i * 8192), 16, 0, 0); } while (0)
; #define PG8_LDA(dst, b, h) do { _Pragma("unroll") for (int m = 0; m < 4; ++m) _Pragma("unroll") for (int k = 0; k < 2; ++k) dst[m][k] = *(const PG8_LAS bf16x8*)(lds + PG8_SA(b, h) + aoff + m * 2048 + k * 1024); } while (0)
; #define PG8_LDB(dst, b, h) do { _Pragma("unroll") for (int n = 0; n < 2; ++n) _Pragma("unroll") for (int k = 0; k < 2; ++k) dst[n][k] = *(const PG8_LAS bf16x8*)(lds + PG8_SB(b, h) + boff + n * 2048 + k * 1024); } while (0)
; #define PG8_MMA(ai, bj, At, Bt) do { __builtin_amdgcn_s_setprio(1); _Pragma("unroll") for (int m = 0; m < 4; ++m) _Pragma("unroll") for (int n = 0; n < 2; ++n) _Pragma("unroll") for (int k = 0; k < 2; ++k) \
;         acc[ai][bj][m][n] = __builtin_amdgcn_mfma_f32_16x16x32_bf16(Bt[n][k], At[m][k], acc[ai][bj][m][n], 0, 0, 0); __builtin_amdgcn_s_setprio(0); } while (0)
; #define PG8_WAIT_V(n) asm volatile("s_waitcnt vmcnt(" #n ")" ::: "memory")
; #define PG8_WAIT_L(n) asm volatile("s_waitcnt lgkmcnt(" #n ")" ::: "memory")
; template <class Epi, class Sched, bool ALIGN_EPI = false, bool SP2 = false>
; __device__ __forceinline__ void gemm_phase(PG8_LAS unsigned char* lds, const Gemm g, const Sched& S, const Epi& E, int tid_in) {
;     ...
;             const bool last = (t == nt - 2);
;             const char* a1 = cA + (size_t)(t + 1) * kstep;
;             const char* a2 = last ? nA : cA + (size_t)(t + 2) * kstep; const char* b2 = last ? nB : cB + (size_t)(t + 2) * kstep;
;             const char* a3 = a2 + kstep; const char* b3 = b2 + kstep;
;             if (last && has_next) S.a_ready(nxt);
;             if constexpr (SP2) {
;             PG8_LDB(B0, 0, 0); PG8_LDB(B1, 0, 1); PG8_SCHED; PG8_LDA(At, 0, 0); PG8_STAGE(PG8_SA(1, 1), a1 + hstep, voffA);
;             PG8_WAIT_V(8); PG8_WAIT_L(0); PG8_BAR; PG8_MMA(0, 0, At, B0); PG8_MMA(0, 1, At, B1); PG8_BAR; PG8_SCHED;
;             PG8_LDA(At, 0, 1); PG8_STAGE(PG8_SB(0, 0), b2, voffB); PG8_STAGE(PG8_SB(0, 1), b2 + hstep, voffB); PG8_STAGE(PG8_SA(0, 0), a2, voffA);
;             PG8_WAIT_V(8); PG8_WAIT_L(0); PG8_BAR; PG8_MMA(1, 0, At, B0); PG8_MMA(1, 1, At, B1); PG8_BAR; PG8_SCHED;
.LBB0_1100:
	s_add_u32 s20, s18, 0x100
	s_addc_u32 s21, s19, 0
	s_add_i32 s52, 0, 0x10000
	s_cmpk_eq_i32 s47, 0x54
	s_cselect_b32 s25, s3, s21
	s_cselect_b32 s24, s2, s20
	v_add_u32_e32 v145, s52, v142
	s_cselect_b32 s23, s17, s46
	s_cselect_b32 s22, s16, s45
	s_add_i32 s62, 0, 0x14000
	ds_read_b128 v[146:149], v145
	ds_read_b128 v[150:153], v145 offset:1024
	ds_read_b128 v[154:157], v145 offset:2048
	ds_read_b128 v[158:161], v145 offset:3072
	v_add_u32_e32 v145, s62, v142
	ds_read_b128 v[162:165], v145
	ds_read_b128 v[172:175], v145 offset:1024
	ds_read_b128 v[176:179], v145 offset:2048
	ds_read_b128 v[180:183], v145 offset:3072
	v_lshl_add_u64 v[200:201], s[18:19], 0, v[136:137]
	s_add_i32 m0, s34, 0xc000
	ds_read_b128 v[184:187], v144
	ds_read_b128 v[188:191], v144 offset:1024
	ds_read_b128 v[192:195], v144 offset:2048
	ds_read_b128 v[196:199], v144 offset:3072
	ds_read_b128 v[204:207], v144 offset:4096
	ds_read_b128 v[208:211], v144 offset:5120
	ds_read_b128 v[212:215], v144 offset:6144
	ds_read_b128 v[216:219], v144 offset:7168
	global_load_lds_dwordx4 v[200:201], off
	v_lshl_add_u64 v[200:201], s[18:19], 0, v[138:139]
	s_add_i32 m0, s34, 0xe000
	s_nop 0
	global_load_lds_dwordx4 v[200:201], off
	s_waitcnt vmcnt(8)
	s_waitcnt lgkmcnt(0)
	s_barrier
	s_setprio 1
	s_waitcnt lgkmcnt(0)
	v_mfma_f32_16x16x32_bf16 v[126:129], v[146:149], v[184:187], v[126:129]
	v_mfma_f32_16x16x32_bf16 v[122:125], v[154:157], v[184:187], v[122:125]
	v_mfma_f32_16x16x32_bf16 v[118:121], v[146:149], v[192:195], v[118:121]
	v_mfma_f32_16x16x32_bf16 v[114:117], v[154:157], v[192:195], v[114:117]
	v_mfma_f32_16x16x32_bf16 v[102:105], v[146:149], v[204:207], v[102:105]
	v_mfma_f32_16x16x32_bf16 v[98:101], v[154:157], v[204:207], v[98:101]
	v_mfma_f32_16x16x32_bf16 v[84:87], v[146:149], v[212:215], v[84:87]
	v_mfma_f32_16x16x32_bf16 v[80:83], v[154:157], v[212:215], v[80:83]
	v_mfma_f32_16x16x32_bf16 v[126:129], v[150:153], v[188:191], v[126:129]
	v_mfma_f32_16x16x32_bf16 v[122:125], v[158:161], v[188:191], v[122:125]
	v_mfma_f32_16x16x32_bf16 v[118:121], v[150:153], v[196:199], v[118:121]
	v_mfma_f32_16x16x32_bf16 v[114:117], v[158:161], v[196:199], v[114:117]
	v_mfma_f32_16x16x32_bf16 v[102:105], v[150:153], v[208:211], v[102:105]
	v_mfma_f32_16x16x32_bf16 v[98:101], v[158:161], v[208:211], v[98:101]
	v_mfma_f32_16x16x32_bf16 v[84:87], v[150:153], v[216:219], v[84:87]
	v_mfma_f32_16x16x32_bf16 v[80:83], v[158:161], v[216:219], v[80:83]
	v_mfma_f32_16x16x32_bf16 v[110:113], v[162:165], v[184:187], v[110:113]
	v_mfma_f32_16x16x32_bf16 v[106:109], v[176:179], v[184:187], v[106:109]
	v_mfma_f32_16x16x32_bf16 v[92:95], v[162:165], v[192:195], v[92:95]
	v_mfma_f32_16x16x32_bf16 v[88:91], v[176:179], v[192:195], v[88:91]
	v_mfma_f32_16x16x32_bf16 v[76:79], v[162:165], v[204:207], v[76:79]
	v_mfma_f32_16x16x32_bf16 v[72:75], v[176:179], v[204:207], v[72:75]
	v_mfma_f32_16x16x32_bf16 v[68:71], v[162:165], v[212:215], v[68:71]
	v_mfma_f32_16x16x32_bf16 v[64:67], v[176:179], v[212:215], v[64:67]
	v_mfma_f32_16x16x32_bf16 v[110:113], v[172:175], v[188:191], v[110:113]
	v_mfma_f32_16x16x32_bf16 v[106:109], v[180:183], v[188:191], v[106:109]
	v_mfma_f32_16x16x32_bf16 v[92:95], v[172:175], v[196:199], v[92:95]
	v_mfma_f32_16x16x32_bf16 v[88:91], v[180:183], v[196:199], v[88:91]
	v_mfma_f32_16x16x32_bf16 v[76:79], v[172:175], v[208:211], v[76:79]
	v_mfma_f32_16x16x32_bf16 v[72:75], v[180:183], v[208:211], v[72:75]
	v_mfma_f32_16x16x32_bf16 v[68:71], v[172:175], v[216:219], v[68:71]
	v_mfma_f32_16x16x32_bf16 v[64:67], v[180:183], v[216:219], v[64:67]
	s_setprio 0
	s_barrier
	s_add_i32 s18, s52, s31
	v_lshl_add_u64 v[200:201], s[22:23], 0, v[96:97]
	s_mov_b32 m0, s18
	ds_read_b128 v[184:187], v144 offset:16384
	ds_read_b128 v[188:191], v144 offset:17408
	ds_read_b128 v[192:195], v144 offset:18432
	ds_read_b128 v[196:199], v144 offset:19456
	ds_read_b128 v[204:207], v144 offset:20480
	ds_read_b128 v[208:211], v144 offset:21504
	ds_read_b128 v[212:215], v144 offset:22528
	ds_read_b128 v[216:219], v144 offset:23552
	global_load_lds_dwordx4 v[200:201], off
	s_add_i32 m0, s18, 0x2000
	s_add_u32 s18, s22, 0x160000
	v_lshl_add_u64 v[220:221], s[22:23], 0, v[134:135]
	s_addc_u32 s19, s23, 0
	s_add_i32 s52, s62, s31
	global_load_lds_dwordx4 v[220:221], off
	v_lshl_add_u64 v[222:223], s[18:19], 0, v[96:97]
	s_mov_b32 m0, s52
	v_lshl_add_u64 v[224:225], s[24:25], 0, v[132:133]
	global_load_lds_dwordx4 v[222:223], off
	v_lshl_add_u64 v[222:223], s[18:19], 0, v[134:135]
	s_add_i32 m0, s52, 0x2000
	s_nop 0
	global_load_lds_dwordx4 v[222:223], off
	v_lshl_add_u64 v[222:223], s[24:25], 0, v[130:131]
	s_mov_b32 m0, s34
	s_nop 0
	global_load_lds_dwordx4 v[222:223], off
	s_mov_b32 m0, s35
	s_nop 0
	global_load_lds_dwordx4 v[224:225], off
	s_waitcnt vmcnt(8)
	s_waitcnt lgkmcnt(0)
	s_barrier
; #define PG8_STAGE(bufoff, gbase, voff) do { _Pragma("unroll") for (int _i = 0; _i < 2; ++_i) \
;         __builtin_amdgcn_global_load_lds((const unsigned*)((const char*)(gbase) + (voff)[_i]), (PG8_LAS unsigned*)(lds + (bufoff) + ldsw + _i * 8192), 16, 0, 0); } while (0)
; #define PG8_LDA(dst, b, h) do { _Pragma("unroll") for (int m = 0; m < 4; ++m) _Pragma("unroll") for (int k = 0; k < 2; ++k) dst[m][k] = *(const PG8_LAS bf16x8*)(lds + PG8_SA(b, h) + aoff + m * 2048 + k * 1024); } while (0)
; #define PG8_LDB(dst, b, h) do { _Pragma("unroll") for (int n = 0; n < 2; ++n) _Pragma("unroll") for (int k = 0; k < 2; ++k) dst[n][k] = *(const PG8_LAS bf16x8*)(lds + PG8_SB(b, h) + boff + n * 2048 + k * 1024); } while (0)
; #define PG8_MMA(ai, bj, At, Bt) do { __builtin_amdgcn_s_setprio(1); _Pragma("unroll") for (int m = 0; m < 4; ++m) _Pragma("unroll") for (int n = 0; n < 2; ++n) _Pragma("unroll") for (int k = 0; k < 2; ++k) \
;         acc[ai][bj][m][n] = __builtin_amdgcn_mfma_f32_16x16x32_bf16(Bt[n][k], At[m][k], acc[ai][bj][m][n], 0, 0, 0); __builtin_amdgcn_s_setprio(0); } while (0)
; #define PG8_WAIT_V(n) asm volatile("s_waitcnt vmcnt(" #n ")" ::: "memory")
; #define PG8_WAIT_L(n) asm volatile("s_waitcnt lgkmcnt(" #n ")" ::: "memory")
; #define PG8_BAR __builtin_amdgcn_s_barrier()
; #define PG8_SCHED __builtin_amdgcn_sched_barrier(0)
; template <class Epi, class Sched, bool ALIGN_EPI = false, bool SP2 = false>
; __device__ __forceinline__ void gemm_phase(PG8_LAS unsigned char* lds, const Gemm g, const Sched& S, const Epi& E, int tid_in) {
;     ...
;             PG8_WAIT_V(8); PG8_WAIT_L(0); PG8_BAR; PG8_MMA(1, 0, At, B0); PG8_MMA(1, 1, At, B1); PG8_BAR; PG8_SCHED;
;             PG8_LDB(B0, 1, 0); PG8_LDB(B1, 1, 1); PG8_SCHED; PG8_LDA(At, 1, 0); PG8_STAGE(PG8_SA(0, 1), a2 + hstep, voffA);
;             PG8_WAIT_V(8); PG8_WAIT_L(0); PG8_BAR; PG8_MMA(0, 0, At, B0); PG8_MMA(0, 1, At, B1); PG8_BAR; PG8_SCHED;
	s_setprio 1
	s_waitcnt lgkmcnt(0)
	v_mfma_f32_16x16x32_bf16 v[60:63], v[146:149], v[184:187], v[60:63]
	v_mfma_f32_16x16x32_bf16 v[56:59], v[154:157], v[184:187], v[56:59]
	v_mfma_f32_16x16x32_bf16 v[52:55], v[146:149], v[192:195], v[52:55]
	v_mfma_f32_16x16x32_bf16 v[48:51], v[154:157], v[192:195], v[48:51]
	v_mfma_f32_16x16x32_bf16 v[36:39], v[146:149], v[204:207], v[36:39]
	v_mfma_f32_16x16x32_bf16 v[32:35], v[154:157], v[204:207], v[32:35]
	v_mfma_f32_16x16x32_bf16 v[20:23], v[146:149], v[212:215], v[20:23]
	v_mfma_f32_16x16x32_bf16 v[16:19], v[154:157], v[212:215], v[16:19]
	v_mfma_f32_16x16x32_bf16 v[60:63], v[150:153], v[188:191], v[60:63]
	v_mfma_f32_16x16x32_bf16 v[56:59], v[158:161], v[188:191], v[56:59]
	v_mfma_f32_16x16x32_bf16 v[52:55], v[150:153], v[196:199], v[52:55]
	v_mfma_f32_16x16x32_bf16 v[48:51], v[158:161], v[196:199], v[48:51]
	v_mfma_f32_16x16x32_bf16 v[36:39], v[150:153], v[208:211], v[36:39]
	v_mfma_f32_16x16x32_bf16 v[32:35], v[158:161], v[208:211], v[32:35]
	v_mfma_f32_16x16x32_bf16 v[20:23], v[150:153], v[216:219], v[20:23]
	v_mfma_f32_16x16x32_bf16 v[16:19], v[158:161], v[216:219], v[16:19]
	v_mfma_f32_16x16x32_bf16 v[44:47], v[162:165], v[184:187], v[44:47]
	v_mfma_f32_16x16x32_bf16 v[40:43], v[176:179], v[184:187], v[40:43]
	v_mfma_f32_16x16x32_bf16 v[28:31], v[162:165], v[192:195], v[28:31]
	v_mfma_f32_16x16x32_bf16 v[24:27], v[176:179], v[192:195], v[24:27]
	v_mfma_f32_16x16x32_bf16 v[12:15], v[162:165], v[204:207], v[12:15]
	v_mfma_f32_16x16x32_bf16 v[8:11], v[176:179], v[204:207], v[8:11]
	v_mfma_f32_16x16x32_bf16 v[4:7], v[162:165], v[212:215], v[4:7]
	v_mfma_f32_16x16x32_bf16 v[0:3], v[176:179], v[212:215], v[0:3]
	v_mfma_f32_16x16x32_bf16 v[44:47], v[172:175], v[188:191], v[44:47]
	v_mfma_f32_16x16x32_bf16 v[40:43], v[180:183], v[188:191], v[40:43]
	v_mfma_f32_16x16x32_bf16 v[28:31], v[172:175], v[196:199], v[28:31]
	v_mfma_f32_16x16x32_bf16 v[24:27], v[180:183], v[196:199], v[24:27]
	v_mfma_f32_16x16x32_bf16 v[12:15], v[172:175], v[208:211], v[12:15]
	v_mfma_f32_16x16x32_bf16 v[8:11], v[180:183], v[208:211], v[8:11]
	v_mfma_f32_16x16x32_bf16 v[4:7], v[172:175], v[216:219], v[4:7]
	v_mfma_f32_16x16x32_bf16 v[0:3], v[180:183], v[216:219], v[0:3]
	s_setprio 0
	s_barrier
	s_add_i32 s52, 0, 0x18000
	v_add_u32_e32 v145, s52, v142
	s_add_i32 s62, 0, 0x1c000
	ds_read_b128 v[146:149], v145
	ds_read_b128 v[150:153], v145 offset:1024
	ds_read_b128 v[154:157], v145 offset:2048
	ds_read_b128 v[158:161], v145 offset:3072
	v_add_u32_e32 v145, s62, v142
	ds_read_b128 v[162:165], v145
	ds_read_b128 v[172:175], v145 offset:1024
	ds_read_b128 v[176:179], v145 offset:2048
	ds_read_b128 v[180:183], v145 offset:3072
	s_add_u32 s18, s24, 0x160000
	s_addc_u32 s19, s25, 0
	s_mov_b32 m0, s36
	v_lshl_add_u64 v[226:227], s[18:19], 0, v[130:131]
	ds_read_b128 v[184:187], v144 offset:32768
	ds_read_b128 v[188:191], v144 offset:33792
	ds_read_b128 v[192:195], v144 offset:34816
	ds_read_b128 v[196:199], v144 offset:35840
	ds_read_b128 v[204:207], v144 offset:36864
	ds_read_b128 v[208:211], v144 offset:37888
	ds_read_b128 v[212:215], v144 offset:38912
	ds_read_b128 v[216:219], v144 offset:39936
	global_load_lds_dwordx4 v[226:227], off
	v_lshl_add_u64 v[226:227], s[18:19], 0, v[132:133]
	s_mov_b32 m0, s37
	s_nop 0
	global_load_lds_dwordx4 v[226:227], off
	s_waitcnt vmcnt(8)
	s_waitcnt lgkmcnt(0)
	s_barrier
	s_setprio 1
	s_waitcnt lgkmcnt(0)
	v_mfma_f32_16x16x32_bf16 v[126:129], v[146:149], v[184:187], v[126:129]
	v_mfma_f32_16x16x32_bf16 v[122:125], v[154:157], v[184:187], v[122:125]
	v_mfma_f32_16x16x32_bf16 v[118:121], v[146:149], v[192:195], v[118:121]
	v_mfma_f32_16x16x32_bf16 v[114:117], v[154:157], v[192:195], v[114:117]
	v_mfma_f32_16x16x32_bf16 v[102:105], v[146:149], v[204:207], v[102:105]
	v_mfma_f32_16x16x32_bf16 v[98:101], v[154:157], v[204:207], v[98:101]
	v_mfma_f32_16x16x32_bf16 v[84:87], v[146:149], v[212:215], v[84:87]
	v_mfma_f32_16x16x32_bf16 v[80:83], v[154:157], v[212:215], v[80:83]
	v_mfma_f32_16x16x32_bf16 v[126:129], v[150:153], v[188:191], v[126:129]
	v_mfma_f32_16x16x32_bf16 v[122:125], v[158:161], v[188:191], v[122:125]
	v_mfma_f32_16x16x32_bf16 v[118:121], v[150:153], v[196:199], v[118:121]
	v_mfma_f32_16x16x32_bf16 v[114:117], v[158:161], v[196:199], v[114:117]
	v_mfma_f32_16x16x32_bf16 v[102:105], v[150:153], v[208:211], v[102:105]
	v_mfma_f32_16x16x32_bf16 v[98:101], v[158:161], v[208:211], v[98:101]
	v_mfma_f32_16x16x32_bf16 v[84:87], v[150:153], v[216:219], v[84:87]
	v_mfma_f32_16x16x32_bf16 v[80:83], v[158:161], v[216:219], v[80:83]
	v_mfma_f32_16x16x32_bf16 v[110:113], v[162:165], v[184:187], v[110:113]
	v_mfma_f32_16x16x32_bf16 v[106:109], v[176:179], v[184:187], v[106:109]
	v_mfma_f32_16x16x32_bf16 v[92:95], v[162:165], v[192:195], v[92:95]
	v_mfma_f32_16x16x32_bf16 v[88:91], v[176:179], v[192:195], v[88:91]
	v_mfma_f32_16x16x32_bf16 v[76:79], v[162:165], v[204:207], v[76:79]
	v_mfma_f32_16x16x32_bf16 v[72:75], v[176:179], v[204:207], v[72:75]
	v_mfma_f32_16x16x32_bf16 v[68:71], v[162:165], v[212:215], v[68:71]
	v_mfma_f32_16x16x32_bf16 v[64:67], v[176:179], v[212:215], v[64:67]
	v_mfma_f32_16x16x32_bf16 v[110:113], v[172:175], v[188:191], v[110:113]
	v_mfma_f32_16x16x32_bf16 v[106:109], v[180:183], v[188:191], v[106:109]
	v_mfma_f32_16x16x32_bf16 v[92:95], v[172:175], v[196:199], v[92:95]
	v_mfma_f32_16x16x32_bf16 v[88:91], v[180:183], v[196:199], v[88:91]
	v_mfma_f32_16x16x32_bf16 v[76:79], v[172:175], v[208:211], v[76:79]
	v_mfma_f32_16x16x32_bf16 v[72:75], v[180:183], v[208:211], v[72:75]
	v_mfma_f32_16x16x32_bf16 v[68:71], v[172:175], v[216:219], v[68:71]
	v_mfma_f32_16x16x32_bf16 v[64:67], v[180:183], v[216:219], v[64:67]
	s_setprio 0
	s_barrier
; #define PG8_STAGE(bufoff, gbase, voff) do { _Pragma("unroll") for (int _i = 0; _i < 2; ++_i) \
;         __builtin_amdgcn_global_load_lds((const unsigned*)((const char*)(gbase) + (voff)[_i]), (PG8_LAS unsigned*)(lds + (bufoff) + ldsw + _i * 8192), 16, 0, 0); } while (0)
; #define PG8_LDA(dst, b, h) do { _Pragma("unroll") for (int m = 0; m < 4; ++m) _Pragma("unroll") for (int k = 0; k < 2; ++k) dst[m][k] = *(const PG8_LAS bf16x8*)(lds + PG8_SA(b, h) + aoff + m * 2048 + k * 1024); } while (0)
; #define PG8_MMA(ai, bj, At, Bt) do { __builtin_amdgcn_s_setprio(1); _Pragma("unroll") for (int m = 0; m < 4; ++m) _Pragma("unroll") for (int n = 0; n < 2; ++n) _Pragma("unroll") for (int k = 0; k < 2; ++k) \
;         acc[ai][bj][m][n] = __builtin_amdgcn_mfma_f32_16x16x32_bf16(Bt[n][k], At[m][k], acc[ai][bj][m][n], 0, 0, 0); __builtin_amdgcn_s_setprio(0); } while (0)
; #define PG8_WAIT_V(n) asm volatile("s_waitcnt vmcnt(" #n ")" ::: "memory")
; #define PG8_WAIT_L(n) asm volatile("s_waitcnt lgkmcnt(" #n ")" ::: "memory")
; #define PG8_BAR __builtin_amdgcn_s_barrier()
; #define PG8_SCHED __builtin_amdgcn_sched_barrier(0)
; template <class Epi, class Sched, bool ALIGN_EPI = false, bool SP2 = false>
; __device__ __forceinline__ void gemm_phase(PG8_LAS unsigned char* lds, const Gemm g, const Sched& S, const Epi& E, int tid_in) {
;     ...
;             PG8_LDA(At, 1, 1); PG8_STAGE(PG8_SB(1, 0), b3, voffB); PG8_STAGE(PG8_SB(1, 1), b3 + hstep, voffB); PG8_STAGE(PG8_SA(1, 0), a3, voffA);
;             PG8_WAIT_V(8); PG8_WAIT_L(0); PG8_BAR; PG8_MMA(1, 0, At, B0); PG8_MMA(1, 1, At, B1); PG8_BAR; PG8_SCHED;
;     ...
;         if constexpr (ALIGN_EPI) { if (wr == 0) PG8_BAR; }
	s_add_i32 s18, s52, s31
	v_lshl_add_u64 v[200:201], v[200:201], 0, s[88:89]
	s_mov_b32 m0, s18
	ds_read_b128 v[184:187], v144 offset:49152
	ds_read_b128 v[188:191], v144 offset:50176
	ds_read_b128 v[192:195], v144 offset:51200
	ds_read_b128 v[196:199], v144 offset:52224
	ds_read_b128 v[204:207], v144 offset:53248
	ds_read_b128 v[208:211], v144 offset:54272
	ds_read_b128 v[212:215], v144 offset:55296
	ds_read_b128 v[216:219], v144 offset:56320
	global_load_lds_dwordx4 v[200:201], off
	s_add_i32 m0, s18, 0x2000
	s_add_u32 s18, s22, 0x160080
	v_lshl_add_u64 v[200:201], v[220:221], 0, s[88:89]
	s_addc_u32 s19, s23, 0
	s_add_i32 s22, s62, s31
	global_load_lds_dwordx4 v[200:201], off
	v_lshl_add_u64 v[200:201], s[18:19], 0, v[96:97]
	s_mov_b32 m0, s22
	s_nop 0
	global_load_lds_dwordx4 v[200:201], off
	v_lshl_add_u64 v[200:201], s[18:19], 0, v[134:135]
	s_add_i32 m0, s22, 0x2000
	s_nop 0
	global_load_lds_dwordx4 v[200:201], off
	v_lshl_add_u64 v[200:201], v[222:223], 0, s[88:89]
	s_mov_b32 m0, s38
	s_nop 0
	global_load_lds_dwordx4 v[200:201], off
	v_lshl_add_u64 v[200:201], v[224:225], 0, s[88:89]
	s_mov_b32 m0, s39
	s_nop 0
	global_load_lds_dwordx4 v[200:201], off
	s_waitcnt vmcnt(8)
	s_waitcnt lgkmcnt(0)
	s_barrier
	s_setprio 1
	s_waitcnt lgkmcnt(0)
	v_mfma_f32_16x16x32_bf16 v[60:63], v[146:149], v[184:187], v[60:63]
	v_mfma_f32_16x16x32_bf16 v[56:59], v[154:157], v[184:187], v[56:59]
	v_mfma_f32_16x16x32_bf16 v[52:55], v[146:149], v[192:195], v[52:55]
	v_mfma_f32_16x16x32_bf16 v[48:51], v[154:157], v[192:195], v[48:51]
	v_mfma_f32_16x16x32_bf16 v[36:39], v[146:149], v[204:207], v[36:39]
	v_mfma_f32_16x16x32_bf16 v[32:35], v[154:157], v[204:207], v[32:35]
	v_mfma_f32_16x16x32_bf16 v[20:23], v[146:149], v[212:215], v[20:23]
	v_mfma_f32_16x16x32_bf16 v[16:19], v[154:157], v[212:215], v[16:19]
	v_mfma_f32_16x16x32_bf16 v[60:63], v[150:153], v[188:191], v[60:63]
	v_mfma_f32_16x16x32_bf16 v[56:59], v[158:161], v[188:191], v[56:59]
	v_mfma_f32_16x16x32_bf16 v[52:55], v[150:153], v[196:199], v[52:55]
	v_mfma_f32_16x16x32_bf16 v[48:51], v[158:161], v[196:199], v[48:51]
	v_mfma_f32_16x16x32_bf16 v[36:39], v[150:153], v[208:211], v[36:39]
	v_mfma_f32_16x16x32_bf16 v[32:35], v[158:161], v[208:211], v[32:35]
	v_mfma_f32_16x16x32_bf16 v[20:23], v[150:153], v[216:219], v[20:23]
	v_mfma_f32_16x16x32_bf16 v[16:19], v[158:161], v[216:219], v[16:19]
	v_mfma_f32_16x16x32_bf16 v[44:47], v[162:165], v[184:187], v[44:47]
	v_mfma_f32_16x16x32_bf16 v[40:43], v[176:179], v[184:187], v[40:43]
	v_mfma_f32_16x16x32_bf16 v[28:31], v[162:165], v[192:195], v[28:31]
	v_mfma_f32_16x16x32_bf16 v[24:27], v[176:179], v[192:195], v[24:27]
	v_mfma_f32_16x16x32_bf16 v[12:15], v[162:165], v[204:207], v[12:15]
	v_mfma_f32_16x16x32_bf16 v[8:11], v[176:179], v[204:207], v[8:11]
	v_mfma_f32_16x16x32_bf16 v[4:7], v[162:165], v[212:215], v[4:7]
	v_mfma_f32_16x16x32_bf16 v[0:3], v[176:179], v[212:215], v[0:3]
	v_mfma_f32_16x16x32_bf16 v[44:47], v[172:175], v[188:191], v[44:47]
	v_mfma_f32_16x16x32_bf16 v[40:43], v[180:183], v[188:191], v[40:43]
	v_mfma_f32_16x16x32_bf16 v[28:31], v[172:175], v[196:199], v[28:31]
	v_mfma_f32_16x16x32_bf16 v[24:27], v[180:183], v[196:199], v[24:27]
	v_mfma_f32_16x16x32_bf16 v[12:15], v[172:175], v[208:211], v[12:15]
	v_mfma_f32_16x16x32_bf16 v[8:11], v[180:183], v[208:211], v[8:11]
	v_mfma_f32_16x16x32_bf16 v[4:7], v[172:175], v[216:219], v[4:7]
	v_mfma_f32_16x16x32_bf16 v[0:3], v[180:183], v[216:219], v[0:3]
	s_setprio 0
	s_barrier
	s_add_i32 s47, s47, 2
	s_add_u32 s45, s45, 0x100
	s_addc_u32 s46, s46, 0
	s_cmpk_gt_u32 s47, 0x55
	s_mov_b64 s[18:19], s[20:21]
	s_cbranch_scc0 .LBB0_1100
	s_and_b64 vcc, exec, s[14:15]
	s_cbranch_vccz .LBB0_1103
	s_barrier
